# v054 + K-loops: s_setprio 1 moved ahead of the load-segment barrier, redundant lgkmcnt(0) before the first MFMA dropped, s_setprio 0 moved behind the MFMA-segment barrier
# speedup vs baseline: 1.0101x; 1.0025x over previous
; #define PG8_STAGE(bufoff, gbase, voff) do { _Pragma("unroll") for (int _i = 0; _i < 2; ++_i) \
;         __builtin_amdgcn_global_load_lds((const unsigned*)((const char*)(gbase) + (voff)[_i]), (PG8_LAS unsigned*)(lds + (bufoff) + ldsw + _i * 8192), 16, 0, 0); } while (0)
; #define PG8_WAIT_V(n) asm volatile("s_waitcnt vmcnt(" #n ")" ::: "memory")
; #define PG8_WAIT_L(n) asm volatile("s_waitcnt lgkmcnt(" #n ")" ::: "memory")
; template <class Epi, class Sched, bool ALIGN_EPI = false, bool SP2 = false, bool PAIR_ACC = false>
; __device__ __forceinline__ void gemm_phase(PG8_LAS unsigned char* lds, const Gemm g, const Sched& S, const Epi& E) {
;     ...
;         const bool has_next = S.next(ui + 1, nxt);
;         const char* nA = has_next ? (const char*)g.A + (size_t)nxt.pm * tstep + (size_t)(nxt.pn / g.a_div) * g.a_sel : cA; const char* nB = has_next ? (const char*)g.Bt + (size_t)nxt.pn * tstep : cB;
;         for (int t = 0; t < nt; t += 2) {
;             const bool last = (t == nt - 2);
;             const char* a1 = cA + (size_t)(t + 1) * kstep;
;             const char* a2 = last ? nA : cA + (size_t)(t + 2) * kstep; const char* b2 = last ? nB : cB + (size_t)(t + 2) * kstep;
;             const char* a3 = a2 + kstep; const char* b3 = b2 + kstep;
;             if (last && has_next) S.a_ready(nxt);
;             if constexpr (SP2) {
;             PG8_LDB(B0, 0, 0); PG8_LDB(B1, 0, 1); PG8_SCHED; PG8_LDA(At, 0, 0); PG8_STAGE(PG8_SA(1, 1), a1 + hstep, voffA);
;             PG8_WAIT_V(8); PG8_WAIT_L(0); PG8_BAR; PG8_MMA(0, 0, At, B0); PG8_MMA(0, 1, At, B1); PG8_BAR; PG8_SCHED;
;             PG8_LDA(At, 0, 1); PG8_STAGE(PG8_SB(0, 0), b2, voffB); PG8_STAGE(PG8_SB(0, 1), b2 + hstep, voffB); PG8_STAGE(PG8_SA(0, 0), a2, voffA);
;             PG8_WAIT_V(8); PG8_WAIT_L(0); PG8_BAR; PG8_MMA(1, 0, At, B0); PG8_MMA(1, 1, At, B1); PG8_BAR; PG8_SCHED;
;             PG8_LDB(B0, 1, 0); PG8_LDB(B1, 1, 1); PG8_SCHED; PG8_LDA(At, 1, 0); PG8_STAGE(PG8_SA(0, 1), a2 + hstep, voffA);
;             PG8_WAIT_V(8); PG8_WAIT_L(0); PG8_BAR; PG8_MMA(0, 0, At, B0); PG8_MMA(0, 1, At, B1); PG8_BAR; PG8_SCHED;
;             PG8_LDA(At, 1, 1); PG8_STAGE(PG8_SB(1, 0), b3, voffB); PG8_STAGE(PG8_SB(1, 1), b3 + hstep, voffB); PG8_STAGE(PG8_SA(1, 0), a3, voffA);
;             PG8_WAIT_V(8); PG8_WAIT_L(0); PG8_BAR; PG8_MMA(1, 0, At, B0); PG8_MMA(1, 1, At, B1); PG8_BAR; PG8_SCHED;
.LBB0_189:
	s_mov_b32 s80, s21
	s_ashr_i32 s81, s21, 31
	s_lshl_b64 s[18:19], s[80:81], 19
	s_add_u32 s84, s23, s18
	s_addc_u32 s85, s61, s19
	s_mov_b32 s78, s17
	s_and_b64 s[18:19], s[82:83], exec
	s_cselect_b32 s13, s85, s11
	s_cselect_b32 s17, s84, s10
	s_ashr_i32 s79, s78, 31
	s_lshl_b64 s[18:19], s[78:79], 19
	s_add_u32 s86, s63, s18
	s_addc_u32 s87, s65, s19
	s_and_b64 s[18:19], s[82:83], exec
	s_cselect_b32 s20, s87, s15
	s_cselect_b32 s21, s86, s14
	s_add_u32 s10, s10, 0x40080
	s_addc_u32 s11, s11, 0
	s_add_u32 s30, s14, 0x100
	s_addc_u32 s38, s15, 0
	s_mov_b32 s39, -2
	s_waitcnt lgkmcnt(0)
	ds_read_b128 v[130:133], v196
	ds_read_b128 v[134:137], v196 offset:1024
	ds_read_b128 v[138:141], v196 offset:2048
	ds_read_b128 v[142:145], v196 offset:3072
	ds_read_b128 v[178:181], v197
	ds_read_b128 v[182:185], v197 offset:1024
	ds_read_b128 v[186:189], v197 offset:2048
	ds_read_b128 v[190:193], v197 offset:3072
	s_add_u32 s14, s10, 0xfffc0080
	s_addc_u32 s15, s11, -1
	s_cmp_eq_u32 s39, 12
	s_cselect_b32 s19, s13, s15
	s_cselect_b32 s18, s17, s14
	s_cselect_b32 s15, s20, s38
	s_cselect_b32 s14, s21, s30
	v_lshl_add_u64 v[194:195], s[10:11], 0, v[170:171]
	s_add_i32 m0, s69, 0xc000
	ds_read_b128 v[206:209], v198
	ds_read_b128 v[210:213], v198 offset:1024
	ds_read_b128 v[214:217], v198 offset:2048
	ds_read_b128 v[218:221], v198 offset:3072
	ds_read_b128 v[222:225], v198 offset:4096
	ds_read_b128 v[226:229], v198 offset:5120
	ds_read_b128 v[230:233], v198 offset:6144
	ds_read_b128 v[234:237], v198 offset:7168
	global_load_lds_dwordx4 v[194:195], off
	v_lshl_add_u64 v[194:195], s[10:11], 0, v[174:175]
	s_add_i32 m0, s69, 0xe000
	s_nop 0
	global_load_lds_dwordx4 v[194:195], off
	s_waitcnt vmcnt(8)
	s_waitcnt lgkmcnt(0)
	s_setprio 1
	s_barrier
	v_mfma_f32_16x16x32_bf16 v[126:129], v[130:133], v[206:209], 0
	v_mfma_f32_16x16x32_bf16 v[122:125], v[138:141], v[206:209], 0
	v_mfma_f32_16x16x32_bf16 v[110:113], v[130:133], v[214:217], 0
	v_mfma_f32_16x16x32_bf16 v[106:109], v[138:141], v[214:217], 0
	v_mfma_f32_16x16x32_bf16 v[94:97], v[130:133], v[222:225], 0
	v_mfma_f32_16x16x32_bf16 v[90:93], v[138:141], v[222:225], 0
	v_mfma_f32_16x16x32_bf16 v[78:81], v[130:133], v[230:233], 0
	v_mfma_f32_16x16x32_bf16 v[74:77], v[138:141], v[230:233], 0
	v_mfma_f32_16x16x32_bf16 v[126:129], v[134:137], v[210:213], v[126:129]
	v_mfma_f32_16x16x32_bf16 v[122:125], v[142:145], v[210:213], v[122:125]
	v_mfma_f32_16x16x32_bf16 v[110:113], v[134:137], v[218:221], v[110:113]
	v_mfma_f32_16x16x32_bf16 v[106:109], v[142:145], v[218:221], v[106:109]
	v_mfma_f32_16x16x32_bf16 v[94:97], v[134:137], v[226:229], v[94:97]
	v_mfma_f32_16x16x32_bf16 v[90:93], v[142:145], v[226:229], v[90:93]
	v_mfma_f32_16x16x32_bf16 v[78:81], v[134:137], v[234:237], v[78:81]
	v_mfma_f32_16x16x32_bf16 v[74:77], v[142:145], v[234:237], v[74:77]
	s_setprio 0
	s_setprio 1
	v_mfma_f32_16x16x32_bf16 v[118:121], v[178:181], v[206:209], 0
	v_mfma_f32_16x16x32_bf16 v[114:117], v[186:189], v[206:209], 0
	v_mfma_f32_16x16x32_bf16 v[102:105], v[178:181], v[214:217], 0
	v_mfma_f32_16x16x32_bf16 v[98:101], v[186:189], v[214:217], 0
	v_mfma_f32_16x16x32_bf16 v[86:89], v[178:181], v[222:225], 0
	v_mfma_f32_16x16x32_bf16 v[82:85], v[186:189], v[222:225], 0
	v_mfma_f32_16x16x32_bf16 v[70:73], v[178:181], v[230:233], 0
	v_mfma_f32_16x16x32_bf16 v[66:69], v[186:189], v[230:233], 0
	v_mfma_f32_16x16x32_bf16 v[118:121], v[182:185], v[210:213], v[118:121]
	v_mfma_f32_16x16x32_bf16 v[114:117], v[190:193], v[210:213], v[114:117]
	v_mfma_f32_16x16x32_bf16 v[102:105], v[182:185], v[218:221], v[102:105]
	v_mfma_f32_16x16x32_bf16 v[98:101], v[190:193], v[218:221], v[98:101]
	v_mfma_f32_16x16x32_bf16 v[86:89], v[182:185], v[226:229], v[86:89]
	v_mfma_f32_16x16x32_bf16 v[82:85], v[190:193], v[226:229], v[82:85]
	v_mfma_f32_16x16x32_bf16 v[70:73], v[182:185], v[234:237], v[70:73]
	v_mfma_f32_16x16x32_bf16 v[66:69], v[190:193], v[234:237], v[66:69]
	s_barrier
	s_setprio 0
	s_add_i32 s40, s25, s67
	v_lshl_add_u64 v[194:195], s[14:15], 0, v[148:149]
	s_mov_b32 m0, s40
	ds_read_b128 v[206:209], v198 offset:16384
	ds_read_b128 v[210:213], v198 offset:17408
	ds_read_b128 v[214:217], v198 offset:18432
	ds_read_b128 v[218:221], v198 offset:19456
	ds_read_b128 v[222:225], v198 offset:20480
	ds_read_b128 v[226:229], v198 offset:21504
	ds_read_b128 v[230:233], v198 offset:22528
	ds_read_b128 v[234:237], v198 offset:23552
	global_load_lds_dwordx4 v[194:195], off
	s_add_i32 m0, s40, 0x2000
	s_add_u32 s40, s14, 0x40000
	v_lshl_add_u64 v[238:239], s[14:15], 0, v[152:153]
	s_addc_u32 s41, s15, 0
	s_add_i32 s79, s35, s67
	global_load_lds_dwordx4 v[238:239], off
	v_lshl_add_u64 v[240:241], s[40:41], 0, v[148:149]
	s_mov_b32 m0, s79
	v_lshl_add_u64 v[242:243], s[18:19], 0, v[150:151]
	global_load_lds_dwordx4 v[240:241], off
	v_lshl_add_u64 v[240:241], s[40:41], 0, v[152:153]
	s_add_i32 m0, s79, 0x2000
	s_nop 0
	global_load_lds_dwordx4 v[240:241], off
	v_lshl_add_u64 v[240:241], s[18:19], 0, v[146:147]
	s_mov_b32 m0, s69
	s_nop 0
	global_load_lds_dwordx4 v[240:241], off
	s_mov_b32 m0, s71
	s_nop 0
	global_load_lds_dwordx4 v[242:243], off
	s_waitcnt vmcnt(8)
	s_waitcnt lgkmcnt(0)
	s_setprio 1
	s_barrier
; #define PG8_STAGE(bufoff, gbase, voff) do { _Pragma("unroll") for (int _i = 0; _i < 2; ++_i) \
;         __builtin_amdgcn_global_load_lds((const unsigned*)((const char*)(gbase) + (voff)[_i]), (PG8_LAS unsigned*)(lds + (bufoff) + ldsw + _i * 8192), 16, 0, 0); } while (0)
; #define PG8_LDA(dst, b, h) do { _Pragma("unroll") for (int m = 0; m < 4; ++m) _Pragma("unroll") for (int k = 0; k < 2; ++k) dst[m][k] = *(const PG8_LAS bf16x8*)(lds + PG8_SA(b, h) + aoff + m * 2048 + k * 1024); } while (0)
; #define PG8_LDB(dst, b, h) do { _Pragma("unroll") for (int n = 0; n < 2; ++n) _Pragma("unroll") for (int k = 0; k < 2; ++k) dst[n][k] = *(const PG8_LAS bf16x8*)(lds + PG8_SB(b, h) + boff + n * 2048 + k * 1024); } while (0)
; #define PG8_MMA(ai, bj, At, Bt) do { __builtin_amdgcn_s_setprio(1); _Pragma("unroll") for (int m = 0; m < 4; ++m) _Pragma("unroll") for (int n = 0; n < 2; ++n) _Pragma("unroll") for (int k = 0; k < 2; ++k) \
;         acc[ai][bj][m][n] = __builtin_amdgcn_mfma_f32_16x16x32_bf16(Bt[n][k], At[m][k], acc[ai][bj][m][n], 0, 0, 0); __builtin_amdgcn_s_setprio(0); } while (0)
; #define PG8_BAR __builtin_amdgcn_s_barrier()
; template <class Epi, class Sched, bool ALIGN_EPI = false, bool SP2 = false, bool PAIR_ACC = false>
; __device__ __forceinline__ void gemm_phase(PG8_LAS unsigned char* lds, const Gemm g, const Sched& S, const Epi& E) {
;     ...
;             PG8_LDB(B0, 0, 0); PG8_LDB(B1, 0, 1); PG8_SCHED; PG8_LDA(At, 0, 0); PG8_STAGE(PG8_SA(1, 1), a1 + hstep, voffA);
;             PG8_WAIT_V(8); PG8_WAIT_L(0); PG8_BAR; PG8_MMA(0, 0, At, B0); PG8_MMA(0, 1, At, B1); PG8_BAR; PG8_SCHED;
;             PG8_LDA(At, 0, 1); PG8_STAGE(PG8_SB(0, 0), b2, voffB); PG8_STAGE(PG8_SB(0, 1), b2 + hstep, voffB); PG8_STAGE(PG8_SA(0, 0), a2, voffA);
;             PG8_WAIT_V(8); PG8_WAIT_L(0); PG8_BAR; PG8_MMA(1, 0, At, B0); PG8_MMA(1, 1, At, B1); PG8_BAR; PG8_SCHED;
;             PG8_LDB(B0, 1, 0); PG8_LDB(B1, 1, 1); PG8_SCHED; PG8_LDA(At, 1, 0); PG8_STAGE(PG8_SA(0, 1), a2 + hstep, voffA);
;             PG8_WAIT_V(8); PG8_WAIT_L(0); PG8_BAR; PG8_MMA(0, 0, At, B0); PG8_MMA(0, 1, At, B1); PG8_BAR; PG8_SCHED;
;             PG8_LDA(At, 1, 1); PG8_STAGE(PG8_SB(1, 0), b3, voffB); PG8_STAGE(PG8_SB(1, 1), b3 + hstep, voffB); PG8_STAGE(PG8_SA(1, 0), a3, voffA);
;             PG8_WAIT_V(8); PG8_WAIT_L(0); PG8_BAR; PG8_MMA(1, 0, At, B0); PG8_MMA(1, 1, At, B1); PG8_BAR; PG8_SCHED;
	v_mfma_f32_16x16x32_bf16 v[62:65], v[130:133], v[206:209], 0
	v_mfma_f32_16x16x32_bf16 v[58:61], v[138:141], v[206:209], 0
	v_mfma_f32_16x16x32_bf16 v[46:49], v[130:133], v[214:217], 0
	v_mfma_f32_16x16x32_bf16 v[42:45], v[138:141], v[214:217], 0
	v_mfma_f32_16x16x32_bf16 v[30:33], v[130:133], v[222:225], 0
	v_mfma_f32_16x16x32_bf16 v[26:29], v[138:141], v[222:225], 0
	v_mfma_f32_16x16x32_bf16 v[14:17], v[130:133], v[230:233], 0
	v_mfma_f32_16x16x32_bf16 v[10:13], v[138:141], v[230:233], 0
	v_mfma_f32_16x16x32_bf16 v[62:65], v[134:137], v[210:213], v[62:65]
	v_mfma_f32_16x16x32_bf16 v[58:61], v[142:145], v[210:213], v[58:61]
	v_mfma_f32_16x16x32_bf16 v[46:49], v[134:137], v[218:221], v[46:49]
	v_mfma_f32_16x16x32_bf16 v[42:45], v[142:145], v[218:221], v[42:45]
	v_mfma_f32_16x16x32_bf16 v[30:33], v[134:137], v[226:229], v[30:33]
	v_mfma_f32_16x16x32_bf16 v[26:29], v[142:145], v[226:229], v[26:29]
	v_mfma_f32_16x16x32_bf16 v[14:17], v[134:137], v[234:237], v[14:17]
	v_mfma_f32_16x16x32_bf16 v[10:13], v[142:145], v[234:237], v[10:13]
	s_setprio 0
	s_setprio 1
	v_mfma_f32_16x16x32_bf16 v[54:57], v[178:181], v[206:209], 0
	v_mfma_f32_16x16x32_bf16 v[50:53], v[186:189], v[206:209], 0
	v_mfma_f32_16x16x32_bf16 v[38:41], v[178:181], v[214:217], 0
	v_mfma_f32_16x16x32_bf16 v[34:37], v[186:189], v[214:217], 0
	v_mfma_f32_16x16x32_bf16 v[22:25], v[178:181], v[222:225], 0
	v_mfma_f32_16x16x32_bf16 v[18:21], v[186:189], v[222:225], 0
	v_mfma_f32_16x16x32_bf16 v[6:9], v[178:181], v[230:233], 0
	v_mfma_f32_16x16x32_bf16 v[2:5], v[186:189], v[230:233], 0
	v_mfma_f32_16x16x32_bf16 v[54:57], v[182:185], v[210:213], v[54:57]
	v_mfma_f32_16x16x32_bf16 v[50:53], v[190:193], v[210:213], v[50:53]
	v_mfma_f32_16x16x32_bf16 v[38:41], v[182:185], v[218:221], v[38:41]
	v_mfma_f32_16x16x32_bf16 v[34:37], v[190:193], v[218:221], v[34:37]
	v_mfma_f32_16x16x32_bf16 v[22:25], v[182:185], v[226:229], v[22:25]
	v_mfma_f32_16x16x32_bf16 v[18:21], v[190:193], v[226:229], v[18:21]
	v_mfma_f32_16x16x32_bf16 v[6:9], v[182:185], v[234:237], v[6:9]
	v_mfma_f32_16x16x32_bf16 v[2:5], v[190:193], v[234:237], v[2:5]
	s_barrier
	s_setprio 0
	s_branch .Lpeel_mid_190
.LBB0_190:
	ds_read_b128 v[130:133], v196
	ds_read_b128 v[134:137], v196 offset:1024
	ds_read_b128 v[138:141], v196 offset:2048
	ds_read_b128 v[142:145], v196 offset:3072
	ds_read_b128 v[178:181], v197
	ds_read_b128 v[182:185], v197 offset:1024
	ds_read_b128 v[186:189], v197 offset:2048
	ds_read_b128 v[190:193], v197 offset:3072
	s_add_u32 s14, s10, 0xfffc0080
	s_addc_u32 s15, s11, -1
	s_cmp_eq_u32 s39, 12
	s_cselect_b32 s19, s13, s15
	s_cselect_b32 s18, s17, s14
	s_cselect_b32 s15, s20, s38
	s_cselect_b32 s14, s21, s30
	v_lshl_add_u64 v[194:195], s[10:11], 0, v[170:171]
	s_add_i32 m0, s69, 0xc000
	ds_read_b128 v[206:209], v198
	ds_read_b128 v[210:213], v198 offset:1024
	ds_read_b128 v[214:217], v198 offset:2048
	ds_read_b128 v[218:221], v198 offset:3072
	ds_read_b128 v[222:225], v198 offset:4096
	ds_read_b128 v[226:229], v198 offset:5120
	ds_read_b128 v[230:233], v198 offset:6144
	ds_read_b128 v[234:237], v198 offset:7168
	global_load_lds_dwordx4 v[194:195], off
	v_lshl_add_u64 v[194:195], s[10:11], 0, v[174:175]
	s_add_i32 m0, s69, 0xe000
	s_nop 0
	global_load_lds_dwordx4 v[194:195], off
	s_waitcnt vmcnt(8)
	s_waitcnt lgkmcnt(0)
	s_setprio 1
	s_barrier
	v_mfma_f32_16x16x32_bf16 v[126:129], v[130:133], v[206:209], v[126:129]
	v_mfma_f32_16x16x32_bf16 v[122:125], v[138:141], v[206:209], v[122:125]
	v_mfma_f32_16x16x32_bf16 v[110:113], v[130:133], v[214:217], v[110:113]
	v_mfma_f32_16x16x32_bf16 v[106:109], v[138:141], v[214:217], v[106:109]
	v_mfma_f32_16x16x32_bf16 v[94:97], v[130:133], v[222:225], v[94:97]
	v_mfma_f32_16x16x32_bf16 v[90:93], v[138:141], v[222:225], v[90:93]
	v_mfma_f32_16x16x32_bf16 v[78:81], v[130:133], v[230:233], v[78:81]
	v_mfma_f32_16x16x32_bf16 v[74:77], v[138:141], v[230:233], v[74:77]
	v_mfma_f32_16x16x32_bf16 v[126:129], v[134:137], v[210:213], v[126:129]
	v_mfma_f32_16x16x32_bf16 v[122:125], v[142:145], v[210:213], v[122:125]
	v_mfma_f32_16x16x32_bf16 v[110:113], v[134:137], v[218:221], v[110:113]
	v_mfma_f32_16x16x32_bf16 v[106:109], v[142:145], v[218:221], v[106:109]
	v_mfma_f32_16x16x32_bf16 v[94:97], v[134:137], v[226:229], v[94:97]
	v_mfma_f32_16x16x32_bf16 v[90:93], v[142:145], v[226:229], v[90:93]
	v_mfma_f32_16x16x32_bf16 v[78:81], v[134:137], v[234:237], v[78:81]
	v_mfma_f32_16x16x32_bf16 v[74:77], v[142:145], v[234:237], v[74:77]
	s_setprio 0
	s_setprio 1
	v_mfma_f32_16x16x32_bf16 v[118:121], v[178:181], v[206:209], v[118:121]
	v_mfma_f32_16x16x32_bf16 v[114:117], v[186:189], v[206:209], v[114:117]
	v_mfma_f32_16x16x32_bf16 v[102:105], v[178:181], v[214:217], v[102:105]
	v_mfma_f32_16x16x32_bf16 v[98:101], v[186:189], v[214:217], v[98:101]
	v_mfma_f32_16x16x32_bf16 v[86:89], v[178:181], v[222:225], v[86:89]
	v_mfma_f32_16x16x32_bf16 v[82:85], v[186:189], v[222:225], v[82:85]
	v_mfma_f32_16x16x32_bf16 v[70:73], v[178:181], v[230:233], v[70:73]
	v_mfma_f32_16x16x32_bf16 v[66:69], v[186:189], v[230:233], v[66:69]
	v_mfma_f32_16x16x32_bf16 v[118:121], v[182:185], v[210:213], v[118:121]
	v_mfma_f32_16x16x32_bf16 v[114:117], v[190:193], v[210:213], v[114:117]
	v_mfma_f32_16x16x32_bf16 v[102:105], v[182:185], v[218:221], v[102:105]
	v_mfma_f32_16x16x32_bf16 v[98:101], v[190:193], v[218:221], v[98:101]
	v_mfma_f32_16x16x32_bf16 v[86:89], v[182:185], v[226:229], v[86:89]
	v_mfma_f32_16x16x32_bf16 v[82:85], v[190:193], v[226:229], v[82:85]
	v_mfma_f32_16x16x32_bf16 v[70:73], v[182:185], v[234:237], v[70:73]
	v_mfma_f32_16x16x32_bf16 v[66:69], v[190:193], v[234:237], v[66:69]
	s_barrier
; #define PG8_STAGE(bufoff, gbase, voff) do { _Pragma("unroll") for (int _i = 0; _i < 2; ++_i) \
;         __builtin_amdgcn_global_load_lds((const unsigned*)((const char*)(gbase) + (voff)[_i]), (PG8_LAS unsigned*)(lds + (bufoff) + ldsw + _i * 8192), 16, 0, 0); } while (0)
; #define PG8_LDA(dst, b, h) do { _Pragma("unroll") for (int m = 0; m < 4; ++m) _Pragma("unroll") for (int k = 0; k < 2; ++k) dst[m][k] = *(const PG8_LAS bf16x8*)(lds + PG8_SA(b, h) + aoff + m * 2048 + k * 1024); } while (0)
; #define PG8_LDB(dst, b, h) do { _Pragma("unroll") for (int n = 0; n < 2; ++n) _Pragma("unroll") for (int k = 0; k < 2; ++k) dst[n][k] = *(const PG8_LAS bf16x8*)(lds + PG8_SB(b, h) + boff + n * 2048 + k * 1024); } while (0)
; #define PG8_MMA(ai, bj, At, Bt) do { __builtin_amdgcn_s_setprio(1); _Pragma("unroll") for (int m = 0; m < 4; ++m) _Pragma("unroll") for (int n = 0; n < 2; ++n) _Pragma("unroll") for (int k = 0; k < 2; ++k) \
;         acc[ai][bj][m][n] = __builtin_amdgcn_mfma_f32_16x16x32_bf16(Bt[n][k], At[m][k], acc[ai][bj][m][n], 0, 0, 0); __builtin_amdgcn_s_setprio(0); } while (0)
; #define PG8_BAR __builtin_amdgcn_s_barrier()
; template <class Epi, class Sched, bool ALIGN_EPI = false, bool SP2 = false, bool PAIR_ACC = false>
; __device__ __forceinline__ void gemm_phase(PG8_LAS unsigned char* lds, const Gemm g, const Sched& S, const Epi& E) {
;     ...
;             PG8_LDB(B0, 0, 0); PG8_LDB(B1, 0, 1); PG8_SCHED; PG8_LDA(At, 0, 0); PG8_STAGE(PG8_SA(1, 1), a1 + hstep, voffA);
;             PG8_WAIT_V(8); PG8_WAIT_L(0); PG8_BAR; PG8_MMA(0, 0, At, B0); PG8_MMA(0, 1, At, B1); PG8_BAR; PG8_SCHED;
;             PG8_LDA(At, 0, 1); PG8_STAGE(PG8_SB(0, 0), b2, voffB); PG8_STAGE(PG8_SB(0, 1), b2 + hstep, voffB); PG8_STAGE(PG8_SA(0, 0), a2, voffA);
;             PG8_WAIT_V(8); PG8_WAIT_L(0); PG8_BAR; PG8_MMA(1, 0, At, B0); PG8_MMA(1, 1, At, B1); PG8_BAR; PG8_SCHED;
;             PG8_LDB(B0, 1, 0); PG8_LDB(B1, 1, 1); PG8_SCHED; PG8_LDA(At, 1, 0); PG8_STAGE(PG8_SA(0, 1), a2 + hstep, voffA);
;             PG8_WAIT_V(8); PG8_WAIT_L(0); PG8_BAR; PG8_MMA(0, 0, At, B0); PG8_MMA(0, 1, At, B1); PG8_BAR; PG8_SCHED;
;             PG8_LDA(At, 1, 1); PG8_STAGE(PG8_SB(1, 0), b3, voffB); PG8_STAGE(PG8_SB(1, 1), b3 + hstep, voffB); PG8_STAGE(PG8_SA(1, 0), a3, voffA);
;             PG8_WAIT_V(8); PG8_WAIT_L(0); PG8_BAR; PG8_MMA(1, 0, At, B0); PG8_MMA(1, 1, At, B1); PG8_BAR; PG8_SCHED;
	s_setprio 0
	s_add_i32 s40, s25, s67
	v_lshl_add_u64 v[194:195], s[14:15], 0, v[148:149]
	s_mov_b32 m0, s40
	ds_read_b128 v[206:209], v198 offset:16384
	ds_read_b128 v[210:213], v198 offset:17408
	ds_read_b128 v[214:217], v198 offset:18432
	ds_read_b128 v[218:221], v198 offset:19456
	ds_read_b128 v[222:225], v198 offset:20480
	ds_read_b128 v[226:229], v198 offset:21504
	ds_read_b128 v[230:233], v198 offset:22528
	ds_read_b128 v[234:237], v198 offset:23552
	global_load_lds_dwordx4 v[194:195], off
	s_add_i32 m0, s40, 0x2000
	s_add_u32 s40, s14, 0x40000
	v_lshl_add_u64 v[238:239], s[14:15], 0, v[152:153]
	s_addc_u32 s41, s15, 0
	s_add_i32 s79, s35, s67
	global_load_lds_dwordx4 v[238:239], off
	v_lshl_add_u64 v[240:241], s[40:41], 0, v[148:149]
	s_mov_b32 m0, s79
	v_lshl_add_u64 v[242:243], s[18:19], 0, v[150:151]
	global_load_lds_dwordx4 v[240:241], off
	v_lshl_add_u64 v[240:241], s[40:41], 0, v[152:153]
	s_add_i32 m0, s79, 0x2000
	s_nop 0
	global_load_lds_dwordx4 v[240:241], off
	v_lshl_add_u64 v[240:241], s[18:19], 0, v[146:147]
	s_mov_b32 m0, s69
	s_nop 0
	global_load_lds_dwordx4 v[240:241], off
	s_mov_b32 m0, s71
	s_nop 0
	global_load_lds_dwordx4 v[242:243], off
	s_waitcnt vmcnt(8)
	s_waitcnt lgkmcnt(0)
	s_setprio 1
	s_barrier
	v_mfma_f32_16x16x32_bf16 v[62:65], v[130:133], v[206:209], v[62:65]
	v_mfma_f32_16x16x32_bf16 v[58:61], v[138:141], v[206:209], v[58:61]
	v_mfma_f32_16x16x32_bf16 v[46:49], v[130:133], v[214:217], v[46:49]
	v_mfma_f32_16x16x32_bf16 v[42:45], v[138:141], v[214:217], v[42:45]
	v_mfma_f32_16x16x32_bf16 v[30:33], v[130:133], v[222:225], v[30:33]
	v_mfma_f32_16x16x32_bf16 v[26:29], v[138:141], v[222:225], v[26:29]
	v_mfma_f32_16x16x32_bf16 v[14:17], v[130:133], v[230:233], v[14:17]
	v_mfma_f32_16x16x32_bf16 v[10:13], v[138:141], v[230:233], v[10:13]
	v_mfma_f32_16x16x32_bf16 v[62:65], v[134:137], v[210:213], v[62:65]
	v_mfma_f32_16x16x32_bf16 v[58:61], v[142:145], v[210:213], v[58:61]
	v_mfma_f32_16x16x32_bf16 v[46:49], v[134:137], v[218:221], v[46:49]
	v_mfma_f32_16x16x32_bf16 v[42:45], v[142:145], v[218:221], v[42:45]
	v_mfma_f32_16x16x32_bf16 v[30:33], v[134:137], v[226:229], v[30:33]
	v_mfma_f32_16x16x32_bf16 v[26:29], v[142:145], v[226:229], v[26:29]
	v_mfma_f32_16x16x32_bf16 v[14:17], v[134:137], v[234:237], v[14:17]
	v_mfma_f32_16x16x32_bf16 v[10:13], v[142:145], v[234:237], v[10:13]
	s_setprio 0
	s_setprio 1
	v_mfma_f32_16x16x32_bf16 v[54:57], v[178:181], v[206:209], v[54:57]
	v_mfma_f32_16x16x32_bf16 v[50:53], v[186:189], v[206:209], v[50:53]
	v_mfma_f32_16x16x32_bf16 v[38:41], v[178:181], v[214:217], v[38:41]
	v_mfma_f32_16x16x32_bf16 v[34:37], v[186:189], v[214:217], v[34:37]
	v_mfma_f32_16x16x32_bf16 v[22:25], v[178:181], v[222:225], v[22:25]
	v_mfma_f32_16x16x32_bf16 v[18:21], v[186:189], v[222:225], v[18:21]
	v_mfma_f32_16x16x32_bf16 v[6:9], v[178:181], v[230:233], v[6:9]
	v_mfma_f32_16x16x32_bf16 v[2:5], v[186:189], v[230:233], v[2:5]
	v_mfma_f32_16x16x32_bf16 v[54:57], v[182:185], v[210:213], v[54:57]
	v_mfma_f32_16x16x32_bf16 v[50:53], v[190:193], v[210:213], v[50:53]
	v_mfma_f32_16x16x32_bf16 v[38:41], v[182:185], v[218:221], v[38:41]
	v_mfma_f32_16x16x32_bf16 v[34:37], v[190:193], v[218:221], v[34:37]
	v_mfma_f32_16x16x32_bf16 v[22:25], v[182:185], v[226:229], v[22:25]
	v_mfma_f32_16x16x32_bf16 v[18:21], v[190:193], v[226:229], v[18:21]
	v_mfma_f32_16x16x32_bf16 v[6:9], v[182:185], v[234:237], v[6:9]
	v_mfma_f32_16x16x32_bf16 v[2:5], v[190:193], v[234:237], v[2:5]
	s_barrier
	s_setprio 0
.Lpeel_mid_190:
	s_add_i32 s40, 0, 0x18000
	s_add_i32 s41, 0, 0x1c000
	v_add_u32_e32 v142, s40, v173
	v_add_u32_e32 v154, s41, v173
	ds_read_b128 v[130:133], v142
	ds_read_b128 v[134:137], v142 offset:1024
	ds_read_b128 v[138:141], v142 offset:2048
	ds_read_b128 v[142:145], v142 offset:3072
	ds_read_b128 v[178:181], v154
	ds_read_b128 v[182:185], v154 offset:1024
	ds_read_b128 v[186:189], v154 offset:2048
	ds_read_b128 v[190:193], v154 offset:3072
	s_add_u32 s18, s18, 0x40000
	s_addc_u32 s19, s19, 0
	s_mov_b32 m0, s73
	v_lshl_add_u64 v[244:245], s[18:19], 0, v[146:147]
	ds_read_b128 v[206:209], v198 offset:32768
	ds_read_b128 v[210:213], v198 offset:33792
	ds_read_b128 v[214:217], v198 offset:34816
	ds_read_b128 v[218:221], v198 offset:35840
	ds_read_b128 v[222:225], v198 offset:36864
	ds_read_b128 v[226:229], v198 offset:37888
	ds_read_b128 v[230:233], v198 offset:38912
	ds_read_b128 v[234:237], v198 offset:39936
	global_load_lds_dwordx4 v[244:245], off
	v_lshl_add_u64 v[244:245], s[18:19], 0, v[150:151]
	s_mov_b32 m0, s36
	s_nop 0
	global_load_lds_dwordx4 v[244:245], off
	s_waitcnt vmcnt(8)
	s_waitcnt lgkmcnt(0)
	s_setprio 1
	s_barrier
; #define PG8_STAGE(bufoff, gbase, voff) do { _Pragma("unroll") for (int _i = 0; _i < 2; ++_i) \
;         __builtin_amdgcn_global_load_lds((const unsigned*)((const char*)(gbase) + (voff)[_i]), (PG8_LAS unsigned*)(lds + (bufoff) + ldsw + _i * 8192), 16, 0, 0); } while (0)
; #define PG8_LDA(dst, b, h) do { _Pragma("unroll") for (int m = 0; m < 4; ++m) _Pragma("unroll") for (int k = 0; k < 2; ++k) dst[m][k] = *(const PG8_LAS bf16x8*)(lds + PG8_SA(b, h) + aoff + m * 2048 + k * 1024); } while (0)
; #define PG8_LDB(dst, b, h) do { _Pragma("unroll") for (int n = 0; n < 2; ++n) _Pragma("unroll") for (int k = 0; k < 2; ++k) dst[n][k] = *(const PG8_LAS bf16x8*)(lds + PG8_SB(b, h) + boff + n * 2048 + k * 1024); } while (0)
; #define PG8_WAIT_V(n) asm volatile("s_waitcnt vmcnt(" #n ")" ::: "memory")
; #define PG8_WAIT_L(n) asm volatile("s_waitcnt lgkmcnt(" #n ")" ::: "memory")
; #define PG8_BAR __builtin_amdgcn_s_barrier()
; #define PG8_SCHED __builtin_amdgcn_sched_barrier(0)
; template <class Epi, class Sched, bool ALIGN_EPI = false, bool SP2 = false, bool PAIR_ACC = false>
; __device__ __forceinline__ void gemm_phase(PG8_LAS unsigned char* lds, const Gemm g, const Sched& S, const Epi& E) {
;     ...
;             PG8_LDB(B0, 0, 0); PG8_LDB(B1, 0, 1); PG8_SCHED; PG8_LDA(At, 0, 0); PG8_STAGE(PG8_SA(1, 1), a1 + hstep, voffA);
;             PG8_WAIT_V(8); PG8_WAIT_L(0); PG8_BAR; PG8_MMA(0, 0, At, B0); PG8_MMA(0, 1, At, B1); PG8_BAR; PG8_SCHED;
;             PG8_LDA(At, 0, 1); PG8_STAGE(PG8_SB(0, 0), b2, voffB); PG8_STAGE(PG8_SB(0, 1), b2 + hstep, voffB); PG8_STAGE(PG8_SA(0, 0), a2, voffA);
;             PG8_WAIT_V(8); PG8_WAIT_L(0); PG8_BAR; PG8_MMA(1, 0, At, B0); PG8_MMA(1, 1, At, B1); PG8_BAR; PG8_SCHED;
;             PG8_LDB(B0, 1, 0); PG8_LDB(B1, 1, 1); PG8_SCHED; PG8_LDA(At, 1, 0); PG8_STAGE(PG8_SA(0, 1), a2 + hstep, voffA);
;             PG8_WAIT_V(8); PG8_WAIT_L(0); PG8_BAR; PG8_MMA(0, 0, At, B0); PG8_MMA(0, 1, At, B1); PG8_BAR; PG8_SCHED;
;             PG8_LDA(At, 1, 1); PG8_STAGE(PG8_SB(1, 0), b3, voffB); PG8_STAGE(PG8_SB(1, 1), b3 + hstep, voffB); PG8_STAGE(PG8_SA(1, 0), a3, voffA);
;             PG8_WAIT_V(8); PG8_WAIT_L(0); PG8_BAR; PG8_MMA(1, 0, At, B0); PG8_MMA(1, 1, At, B1); PG8_BAR; PG8_SCHED;
;     ...
;         if constexpr (ALIGN_EPI) { if (wr == 0) PG8_BAR; }
	v_mfma_f32_16x16x32_bf16 v[126:129], v[130:133], v[206:209], v[126:129]
	v_mfma_f32_16x16x32_bf16 v[122:125], v[138:141], v[206:209], v[122:125]
	v_mfma_f32_16x16x32_bf16 v[110:113], v[130:133], v[214:217], v[110:113]
	v_mfma_f32_16x16x32_bf16 v[106:109], v[138:141], v[214:217], v[106:109]
	v_mfma_f32_16x16x32_bf16 v[94:97], v[130:133], v[222:225], v[94:97]
	v_mfma_f32_16x16x32_bf16 v[90:93], v[138:141], v[222:225], v[90:93]
	v_mfma_f32_16x16x32_bf16 v[78:81], v[130:133], v[230:233], v[78:81]
	v_mfma_f32_16x16x32_bf16 v[74:77], v[138:141], v[230:233], v[74:77]
	v_mfma_f32_16x16x32_bf16 v[126:129], v[134:137], v[210:213], v[126:129]
	v_mfma_f32_16x16x32_bf16 v[122:125], v[142:145], v[210:213], v[122:125]
	v_mfma_f32_16x16x32_bf16 v[110:113], v[134:137], v[218:221], v[110:113]
	v_mfma_f32_16x16x32_bf16 v[106:109], v[142:145], v[218:221], v[106:109]
	v_mfma_f32_16x16x32_bf16 v[94:97], v[134:137], v[226:229], v[94:97]
	v_mfma_f32_16x16x32_bf16 v[90:93], v[142:145], v[226:229], v[90:93]
	v_mfma_f32_16x16x32_bf16 v[78:81], v[134:137], v[234:237], v[78:81]
	v_mfma_f32_16x16x32_bf16 v[74:77], v[142:145], v[234:237], v[74:77]
	s_setprio 0
	s_setprio 1
	v_mfma_f32_16x16x32_bf16 v[118:121], v[178:181], v[206:209], v[118:121]
	v_mfma_f32_16x16x32_bf16 v[114:117], v[186:189], v[206:209], v[114:117]
	v_mfma_f32_16x16x32_bf16 v[102:105], v[178:181], v[214:217], v[102:105]
	v_mfma_f32_16x16x32_bf16 v[98:101], v[186:189], v[214:217], v[98:101]
	v_mfma_f32_16x16x32_bf16 v[86:89], v[178:181], v[222:225], v[86:89]
	v_mfma_f32_16x16x32_bf16 v[82:85], v[186:189], v[222:225], v[82:85]
	v_mfma_f32_16x16x32_bf16 v[70:73], v[178:181], v[230:233], v[70:73]
	v_mfma_f32_16x16x32_bf16 v[66:69], v[186:189], v[230:233], v[66:69]
	v_mfma_f32_16x16x32_bf16 v[118:121], v[182:185], v[210:213], v[118:121]
	v_mfma_f32_16x16x32_bf16 v[114:117], v[190:193], v[210:213], v[114:117]
	v_mfma_f32_16x16x32_bf16 v[102:105], v[182:185], v[218:221], v[102:105]
	v_mfma_f32_16x16x32_bf16 v[98:101], v[190:193], v[218:221], v[98:101]
	v_mfma_f32_16x16x32_bf16 v[86:89], v[182:185], v[226:229], v[86:89]
	v_mfma_f32_16x16x32_bf16 v[82:85], v[190:193], v[226:229], v[82:85]
	v_mfma_f32_16x16x32_bf16 v[70:73], v[182:185], v[234:237], v[70:73]
	v_mfma_f32_16x16x32_bf16 v[66:69], v[190:193], v[234:237], v[66:69]
	s_barrier
	s_setprio 0
	s_add_i32 s18, s40, s67
	v_lshl_add_u64 v[194:195], v[194:195], 0, s[50:51]
	s_mov_b32 m0, s18
	ds_read_b128 v[206:209], v198 offset:49152
	ds_read_b128 v[210:213], v198 offset:50176
	ds_read_b128 v[214:217], v198 offset:51200
	ds_read_b128 v[218:221], v198 offset:52224
	ds_read_b128 v[222:225], v198 offset:53248
	ds_read_b128 v[226:229], v198 offset:54272
	ds_read_b128 v[230:233], v198 offset:55296
	ds_read_b128 v[234:237], v198 offset:56320
	global_load_lds_dwordx4 v[194:195], off
	s_add_i32 m0, s18, 0x2000
	s_add_u32 s14, s14, 0x40080
	v_lshl_add_u64 v[194:195], v[238:239], 0, s[50:51]
	s_addc_u32 s15, s15, 0
	s_add_i32 s18, s41, s67
	global_load_lds_dwordx4 v[194:195], off
	v_lshl_add_u64 v[194:195], s[14:15], 0, v[148:149]
	s_mov_b32 m0, s18
	s_nop 0
	global_load_lds_dwordx4 v[194:195], off
	v_lshl_add_u64 v[194:195], s[14:15], 0, v[152:153]
	s_add_i32 m0, s18, 0x2000
	s_nop 0
	global_load_lds_dwordx4 v[194:195], off
	v_lshl_add_u64 v[194:195], v[240:241], 0, s[50:51]
	s_mov_b32 m0, s37
	s_nop 0
	global_load_lds_dwordx4 v[194:195], off
	v_lshl_add_u64 v[194:195], v[242:243], 0, s[50:51]
	s_mov_b32 m0, s75
	s_nop 0
	global_load_lds_dwordx4 v[194:195], off
	s_waitcnt vmcnt(8)
	s_waitcnt lgkmcnt(0)
	s_setprio 1
	s_barrier
	v_mfma_f32_16x16x32_bf16 v[62:65], v[130:133], v[206:209], v[62:65]
	v_mfma_f32_16x16x32_bf16 v[58:61], v[138:141], v[206:209], v[58:61]
	v_mfma_f32_16x16x32_bf16 v[46:49], v[130:133], v[214:217], v[46:49]
	v_mfma_f32_16x16x32_bf16 v[42:45], v[138:141], v[214:217], v[42:45]
	v_mfma_f32_16x16x32_bf16 v[30:33], v[130:133], v[222:225], v[30:33]
	v_mfma_f32_16x16x32_bf16 v[26:29], v[138:141], v[222:225], v[26:29]
	v_mfma_f32_16x16x32_bf16 v[14:17], v[130:133], v[230:233], v[14:17]
	v_mfma_f32_16x16x32_bf16 v[10:13], v[138:141], v[230:233], v[10:13]
	v_mfma_f32_16x16x32_bf16 v[62:65], v[134:137], v[210:213], v[62:65]
	v_mfma_f32_16x16x32_bf16 v[58:61], v[142:145], v[210:213], v[58:61]
	v_mfma_f32_16x16x32_bf16 v[46:49], v[134:137], v[218:221], v[46:49]
	v_mfma_f32_16x16x32_bf16 v[42:45], v[142:145], v[218:221], v[42:45]
	v_mfma_f32_16x16x32_bf16 v[30:33], v[134:137], v[226:229], v[30:33]
	v_mfma_f32_16x16x32_bf16 v[26:29], v[142:145], v[226:229], v[26:29]
	v_mfma_f32_16x16x32_bf16 v[14:17], v[134:137], v[234:237], v[14:17]
	v_mfma_f32_16x16x32_bf16 v[10:13], v[142:145], v[234:237], v[10:13]
	s_setprio 0
	s_setprio 1
	v_mfma_f32_16x16x32_bf16 v[54:57], v[178:181], v[206:209], v[54:57]
	v_mfma_f32_16x16x32_bf16 v[50:53], v[186:189], v[206:209], v[50:53]
	v_mfma_f32_16x16x32_bf16 v[38:41], v[178:181], v[214:217], v[38:41]
	v_mfma_f32_16x16x32_bf16 v[34:37], v[186:189], v[214:217], v[34:37]
	v_mfma_f32_16x16x32_bf16 v[22:25], v[178:181], v[222:225], v[22:25]
	v_mfma_f32_16x16x32_bf16 v[18:21], v[186:189], v[222:225], v[18:21]
	v_mfma_f32_16x16x32_bf16 v[6:9], v[178:181], v[230:233], v[6:9]
	v_mfma_f32_16x16x32_bf16 v[2:5], v[186:189], v[230:233], v[2:5]
	v_mfma_f32_16x16x32_bf16 v[54:57], v[182:185], v[210:213], v[54:57]
	v_mfma_f32_16x16x32_bf16 v[50:53], v[190:193], v[210:213], v[50:53]
	v_mfma_f32_16x16x32_bf16 v[38:41], v[182:185], v[218:221], v[38:41]
	v_mfma_f32_16x16x32_bf16 v[34:37], v[190:193], v[218:221], v[34:37]
	v_mfma_f32_16x16x32_bf16 v[22:25], v[182:185], v[226:229], v[22:25]
	v_mfma_f32_16x16x32_bf16 v[18:21], v[190:193], v[226:229], v[18:21]
	v_mfma_f32_16x16x32_bf16 v[6:9], v[182:185], v[234:237], v[6:9]
	v_mfma_f32_16x16x32_bf16 v[2:5], v[190:193], v[234:237], v[2:5]
	s_barrier
	s_setprio 0
	s_add_i32 s39, s39, 2
	s_add_u32 s10, s10, 0x100
	s_addc_u32 s11, s11, 0
	s_add_u32 s30, s30, 0x100
	s_addc_u32 s38, s38, 0
	s_cmp_gt_u32 s39, 13
	s_cbranch_scc0 .LBB0_190
	s_and_b64 vcc, exec, s[52:53]
	s_cbranch_vccz .LBB0_193
	s_barrier

; #define PG8_STAGE(bufoff, gbase, voff) do { _Pragma("unroll") for (int _i = 0; _i < 2; ++_i) \
;         __builtin_amdgcn_global_load_lds((const unsigned*)((const char*)(gbase) + (voff)[_i]), (PG8_LAS unsigned*)(lds + (bufoff) + ldsw + _i * 8192), 16, 0, 0); } while (0)
; #define PG8_LDA(dst, b, h) do { _Pragma("unroll") for (int m = 0; m < 4; ++m) _Pragma("unroll") for (int k = 0; k < 2; ++k) dst[m][k] = *(const PG8_LAS bf16x8*)(lds + PG8_SA(b, h) + aoff + m * 2048 + k * 1024); } while (0)
; #define PG8_LDB(dst, b, h) do { _Pragma("unroll") for (int n = 0; n < 2; ++n) _Pragma("unroll") for (int k = 0; k < 2; ++k) dst[n][k] = *(const PG8_LAS bf16x8*)(lds + PG8_SB(b, h) + boff + n * 2048 + k * 1024); } while (0)
; #define PG8_MMA(ai, bj, At, Bt) do { __builtin_amdgcn_s_setprio(1); _Pragma("unroll") for (int m = 0; m < 4; ++m) _Pragma("unroll") for (int n = 0; n < 2; ++n) _Pragma("unroll") for (int k = 0; k < 2; ++k) \
;         acc[ai][bj][m][n] = __builtin_amdgcn_mfma_f32_16x16x32_bf16(Bt[n][k], At[m][k], acc[ai][bj][m][n], 0, 0, 0); __builtin_amdgcn_s_setprio(0); } while (0)
; #define PG8_BAR __builtin_amdgcn_s_barrier()
; template <class Epi, class Sched, bool ALIGN_EPI = false, bool SP2 = false, bool PAIR_ACC = false>
; __device__ __forceinline__ void gemm_phase(PG8_LAS unsigned char* lds, const Gemm g, const Sched& S, const Epi& E) {
;     ...
;             PG8_LDB(B0, 0, 0); PG8_LDB(B1, 0, 1); PG8_SCHED; PG8_LDA(At, 0, 0); PG8_STAGE(PG8_SA(1, 1), a1 + hstep, voffA);
;             PG8_WAIT_V(8); PG8_WAIT_L(0); PG8_BAR; PG8_MMA(0, 0, At, B0); PG8_MMA(0, 1, At, B1); PG8_BAR; PG8_SCHED;
;             PG8_LDA(At, 0, 1); PG8_STAGE(PG8_SB(0, 0), b2, voffB); PG8_STAGE(PG8_SB(0, 1), b2 + hstep, voffB); PG8_STAGE(PG8_SA(0, 0), a2, voffA);
;             PG8_WAIT_V(8); PG8_WAIT_L(0); PG8_BAR; PG8_MMA(1, 0, At, B0); PG8_MMA(1, 1, At, B1); PG8_BAR; PG8_SCHED;
;             PG8_LDB(B0, 1, 0); PG8_LDB(B1, 1, 1); PG8_SCHED; PG8_LDA(At, 1, 0); PG8_STAGE(PG8_SA(0, 1), a2 + hstep, voffA);
;             PG8_WAIT_V(8); PG8_WAIT_L(0); PG8_BAR; PG8_MMA(0, 0, At, B0); PG8_MMA(0, 1, At, B1); PG8_BAR; PG8_SCHED;
;             PG8_LDA(At, 1, 1); PG8_STAGE(PG8_SB(1, 0), b3, voffB); PG8_STAGE(PG8_SB(1, 1), b3 + hstep, voffB); PG8_STAGE(PG8_SA(1, 0), a3, voffA);
;             PG8_WAIT_V(8); PG8_WAIT_L(0); PG8_BAR; PG8_MMA(1, 0, At, B0); PG8_MMA(1, 1, At, B1); PG8_BAR; PG8_SCHED;
.LBB0_585:
	v_add_u32_e32 v142, s46, v206
	v_add_u32_e32 v166, s47, v206
	ds_read_b128 v[130:133], v142
	ds_read_b128 v[134:137], v142 offset:1024
	ds_read_b128 v[138:141], v142 offset:2048
	ds_read_b128 v[142:145], v142 offset:3072
	ds_read_b128 v[146:149], v166
	ds_read_b128 v[150:153], v166 offset:1024
	ds_read_b128 v[154:157], v166 offset:2048
	ds_read_b128 v[178:181], v166 offset:3072
	s_add_u32 s38, s8, 0xfffc0080
	s_addc_u32 s39, s9, -1
	s_cmp_eq_u32 s56, 12
	s_cselect_b32 s55, s43, s39
	s_cselect_b32 s54, s42, s38
	s_cselect_b32 s39, s29, s53
	s_cselect_b32 s38, s31, s51
	v_lshl_add_u64 v[198:199], s[8:9], 0, v[168:169]
	s_add_i32 m0, s34, 0xc000
	ds_read_b128 v[182:185], v208
	ds_read_b128 v[186:189], v208 offset:1024
	ds_read_b128 v[190:193], v208 offset:2048
	ds_read_b128 v[194:197], v208 offset:3072
	ds_read_b128 v[210:213], v208 offset:4096
	ds_read_b128 v[214:217], v208 offset:5120
	ds_read_b128 v[218:221], v208 offset:6144
	ds_read_b128 v[222:225], v208 offset:7168
	global_load_lds_dwordx4 v[198:199], off
	v_lshl_add_u64 v[198:199], s[8:9], 0, v[170:171]
	s_add_i32 m0, s34, 0xe000
	s_nop 0
	global_load_lds_dwordx4 v[198:199], off
	s_waitcnt vmcnt(8)
	s_waitcnt lgkmcnt(0)
	s_setprio 1
	s_barrier
	v_mfma_f32_16x16x32_bf16 v[126:129], v[130:133], v[182:185], v[126:129]
	v_mfma_f32_16x16x32_bf16 v[122:125], v[138:141], v[182:185], v[122:125]
	v_mfma_f32_16x16x32_bf16 v[118:121], v[130:133], v[190:193], v[118:121]
	v_mfma_f32_16x16x32_bf16 v[114:117], v[138:141], v[190:193], v[114:117]
	v_mfma_f32_16x16x32_bf16 v[110:113], v[130:133], v[210:213], v[110:113]
	v_mfma_f32_16x16x32_bf16 v[106:109], v[138:141], v[210:213], v[106:109]
	v_mfma_f32_16x16x32_bf16 v[102:105], v[130:133], v[218:221], v[102:105]
	v_mfma_f32_16x16x32_bf16 v[98:101], v[138:141], v[218:221], v[98:101]
	v_mfma_f32_16x16x32_bf16 v[126:129], v[134:137], v[186:189], v[126:129]
	v_mfma_f32_16x16x32_bf16 v[122:125], v[142:145], v[186:189], v[122:125]
	v_mfma_f32_16x16x32_bf16 v[118:121], v[134:137], v[194:197], v[118:121]
	v_mfma_f32_16x16x32_bf16 v[114:117], v[142:145], v[194:197], v[114:117]
	v_mfma_f32_16x16x32_bf16 v[110:113], v[134:137], v[214:217], v[110:113]
	v_mfma_f32_16x16x32_bf16 v[106:109], v[142:145], v[214:217], v[106:109]
	v_mfma_f32_16x16x32_bf16 v[102:105], v[134:137], v[222:225], v[102:105]
	v_mfma_f32_16x16x32_bf16 v[98:101], v[142:145], v[222:225], v[98:101]
	s_setprio 0
	s_setprio 1
	v_mfma_f32_16x16x32_bf16 v[94:97], v[146:149], v[182:185], v[94:97]
	v_mfma_f32_16x16x32_bf16 v[90:93], v[154:157], v[182:185], v[90:93]
	v_mfma_f32_16x16x32_bf16 v[86:89], v[146:149], v[190:193], v[86:89]
	v_mfma_f32_16x16x32_bf16 v[82:85], v[154:157], v[190:193], v[82:85]
	v_mfma_f32_16x16x32_bf16 v[78:81], v[146:149], v[210:213], v[78:81]
	v_mfma_f32_16x16x32_bf16 v[74:77], v[154:157], v[210:213], v[74:77]
	v_mfma_f32_16x16x32_bf16 v[70:73], v[146:149], v[218:221], v[70:73]
	v_mfma_f32_16x16x32_bf16 v[66:69], v[154:157], v[218:221], v[66:69]
	v_mfma_f32_16x16x32_bf16 v[94:97], v[150:153], v[186:189], v[94:97]
	v_mfma_f32_16x16x32_bf16 v[90:93], v[178:181], v[186:189], v[90:93]
	v_mfma_f32_16x16x32_bf16 v[86:89], v[150:153], v[194:197], v[86:89]
	v_mfma_f32_16x16x32_bf16 v[82:85], v[178:181], v[194:197], v[82:85]
	v_mfma_f32_16x16x32_bf16 v[78:81], v[150:153], v[214:217], v[78:81]
	v_mfma_f32_16x16x32_bf16 v[74:77], v[178:181], v[214:217], v[74:77]
	v_mfma_f32_16x16x32_bf16 v[70:73], v[150:153], v[222:225], v[70:73]
	v_mfma_f32_16x16x32_bf16 v[66:69], v[178:181], v[222:225], v[66:69]
	s_barrier
	s_setprio 0
	s_add_i32 s57, s46, s25
	v_lshl_add_u64 v[198:199], s[38:39], 0, v[160:161]
	s_mov_b32 m0, s57
	ds_read_b128 v[182:185], v208 offset:16384
	ds_read_b128 v[186:189], v208 offset:17408
	ds_read_b128 v[190:193], v208 offset:18432
	ds_read_b128 v[194:197], v208 offset:19456
	ds_read_b128 v[210:213], v208 offset:20480
	ds_read_b128 v[214:217], v208 offset:21504
	ds_read_b128 v[218:221], v208 offset:22528
	ds_read_b128 v[222:225], v208 offset:23552
	global_load_lds_dwordx4 v[198:199], off
	s_add_i32 m0, s57, 0x2000
	s_add_u32 s58, s38, 0x40000
	v_lshl_add_u64 v[226:227], s[38:39], 0, v[164:165]
	s_addc_u32 s59, s39, 0
	s_add_i32 s57, s47, s25
	global_load_lds_dwordx4 v[226:227], off
	v_lshl_add_u64 v[228:229], s[58:59], 0, v[160:161]
	s_mov_b32 m0, s57
	v_lshl_add_u64 v[230:231], s[54:55], 0, v[162:163]
	global_load_lds_dwordx4 v[228:229], off
	v_lshl_add_u64 v[228:229], s[58:59], 0, v[164:165]
	s_add_i32 m0, s57, 0x2000
	s_nop 0
	global_load_lds_dwordx4 v[228:229], off
	v_lshl_add_u64 v[228:229], s[54:55], 0, v[158:159]
	s_mov_b32 m0, s34
	s_nop 0
	global_load_lds_dwordx4 v[228:229], off
	s_mov_b32 m0, s35
	s_nop 0
	global_load_lds_dwordx4 v[230:231], off
	s_waitcnt vmcnt(8)
	s_waitcnt lgkmcnt(0)
	s_setprio 1
	s_barrier
; #define PG8_STAGE(bufoff, gbase, voff) do { _Pragma("unroll") for (int _i = 0; _i < 2; ++_i) \
;         __builtin_amdgcn_global_load_lds((const unsigned*)((const char*)(gbase) + (voff)[_i]), (PG8_LAS unsigned*)(lds + (bufoff) + ldsw + _i * 8192), 16, 0, 0); } while (0)
; #define PG8_LDA(dst, b, h) do { _Pragma("unroll") for (int m = 0; m < 4; ++m) _Pragma("unroll") for (int k = 0; k < 2; ++k) dst[m][k] = *(const PG8_LAS bf16x8*)(lds + PG8_SA(b, h) + aoff + m * 2048 + k * 1024); } while (0)
; #define PG8_LDB(dst, b, h) do { _Pragma("unroll") for (int n = 0; n < 2; ++n) _Pragma("unroll") for (int k = 0; k < 2; ++k) dst[n][k] = *(const PG8_LAS bf16x8*)(lds + PG8_SB(b, h) + boff + n * 2048 + k * 1024); } while (0)
; #define PG8_MMA(ai, bj, At, Bt) do { __builtin_amdgcn_s_setprio(1); _Pragma("unroll") for (int m = 0; m < 4; ++m) _Pragma("unroll") for (int n = 0; n < 2; ++n) _Pragma("unroll") for (int k = 0; k < 2; ++k) \
;         acc[ai][bj][m][n] = __builtin_amdgcn_mfma_f32_16x16x32_bf16(Bt[n][k], At[m][k], acc[ai][bj][m][n], 0, 0, 0); __builtin_amdgcn_s_setprio(0); } while (0)
; #define PG8_WAIT_V(n) asm volatile("s_waitcnt vmcnt(" #n ")" ::: "memory")
; #define PG8_WAIT_L(n) asm volatile("s_waitcnt lgkmcnt(" #n ")" ::: "memory")
; #define PG8_BAR __builtin_amdgcn_s_barrier()
; #define PG8_SCHED __builtin_amdgcn_sched_barrier(0)
; template <class Epi, class Sched, bool ALIGN_EPI = false, bool SP2 = false, bool PAIR_ACC = false>
; __device__ __forceinline__ void gemm_phase(PG8_LAS unsigned char* lds, const Gemm g, const Sched& S, const Epi& E) {
;     ...
;             PG8_WAIT_V(8); PG8_WAIT_L(0); PG8_BAR; PG8_MMA(1, 0, At, B0); PG8_MMA(1, 1, At, B1); PG8_BAR; PG8_SCHED;
;             PG8_LDB(B0, 1, 0); PG8_LDB(B1, 1, 1); PG8_SCHED; PG8_LDA(At, 1, 0); PG8_STAGE(PG8_SA(0, 1), a2 + hstep, voffA);
;             PG8_WAIT_V(8); PG8_WAIT_L(0); PG8_BAR; PG8_MMA(0, 0, At, B0); PG8_MMA(0, 1, At, B1); PG8_BAR; PG8_SCHED;
	v_mfma_f32_16x16x32_bf16 v[62:65], v[130:133], v[182:185], v[62:65]
	v_mfma_f32_16x16x32_bf16 v[58:61], v[138:141], v[182:185], v[58:61]
	v_mfma_f32_16x16x32_bf16 v[54:57], v[130:133], v[190:193], v[54:57]
	v_mfma_f32_16x16x32_bf16 v[50:53], v[138:141], v[190:193], v[50:53]
	v_mfma_f32_16x16x32_bf16 v[46:49], v[130:133], v[210:213], v[46:49]
	v_mfma_f32_16x16x32_bf16 v[42:45], v[138:141], v[210:213], v[42:45]
	v_mfma_f32_16x16x32_bf16 v[38:41], v[130:133], v[218:221], v[38:41]
	v_mfma_f32_16x16x32_bf16 v[34:37], v[138:141], v[218:221], v[34:37]
	v_mfma_f32_16x16x32_bf16 v[62:65], v[134:137], v[186:189], v[62:65]
	v_mfma_f32_16x16x32_bf16 v[58:61], v[142:145], v[186:189], v[58:61]
	v_mfma_f32_16x16x32_bf16 v[54:57], v[134:137], v[194:197], v[54:57]
	v_mfma_f32_16x16x32_bf16 v[50:53], v[142:145], v[194:197], v[50:53]
	v_mfma_f32_16x16x32_bf16 v[46:49], v[134:137], v[214:217], v[46:49]
	v_mfma_f32_16x16x32_bf16 v[42:45], v[142:145], v[214:217], v[42:45]
	v_mfma_f32_16x16x32_bf16 v[38:41], v[134:137], v[222:225], v[38:41]
	v_mfma_f32_16x16x32_bf16 v[34:37], v[142:145], v[222:225], v[34:37]
	s_setprio 0
	s_setprio 1
	v_mfma_f32_16x16x32_bf16 v[30:33], v[146:149], v[182:185], v[30:33]
	v_mfma_f32_16x16x32_bf16 v[26:29], v[154:157], v[182:185], v[26:29]
	v_mfma_f32_16x16x32_bf16 v[22:25], v[146:149], v[190:193], v[22:25]
	v_mfma_f32_16x16x32_bf16 v[18:21], v[154:157], v[190:193], v[18:21]
	v_mfma_f32_16x16x32_bf16 v[14:17], v[146:149], v[210:213], v[14:17]
	v_mfma_f32_16x16x32_bf16 v[10:13], v[154:157], v[210:213], v[10:13]
	v_mfma_f32_16x16x32_bf16 v[6:9], v[146:149], v[218:221], v[6:9]
	v_mfma_f32_16x16x32_bf16 v[2:5], v[154:157], v[218:221], v[2:5]
	v_mfma_f32_16x16x32_bf16 v[30:33], v[150:153], v[186:189], v[30:33]
	v_mfma_f32_16x16x32_bf16 v[26:29], v[178:181], v[186:189], v[26:29]
	v_mfma_f32_16x16x32_bf16 v[22:25], v[150:153], v[194:197], v[22:25]
	v_mfma_f32_16x16x32_bf16 v[18:21], v[178:181], v[194:197], v[18:21]
	v_mfma_f32_16x16x32_bf16 v[14:17], v[150:153], v[214:217], v[14:17]
	v_mfma_f32_16x16x32_bf16 v[10:13], v[178:181], v[214:217], v[10:13]
	v_mfma_f32_16x16x32_bf16 v[6:9], v[150:153], v[222:225], v[6:9]
	v_mfma_f32_16x16x32_bf16 v[2:5], v[178:181], v[222:225], v[2:5]
	s_barrier
	s_setprio 0
	s_add_i32 s57, 0, 0x18000
	s_add_i32 s58, 0, 0x1c000
	v_add_u32_e32 v142, s57, v206
	v_add_u32_e32 v166, s58, v206
	ds_read_b128 v[130:133], v142
	ds_read_b128 v[134:137], v142 offset:1024
	ds_read_b128 v[138:141], v142 offset:2048
	ds_read_b128 v[142:145], v142 offset:3072
	ds_read_b128 v[146:149], v166
	ds_read_b128 v[150:153], v166 offset:1024
	ds_read_b128 v[154:157], v166 offset:2048
	ds_read_b128 v[178:181], v166 offset:3072
	s_add_u32 s54, s54, 0x40000
	s_addc_u32 s55, s55, 0
	s_mov_b32 m0, s36
	v_lshl_add_u64 v[232:233], s[54:55], 0, v[158:159]
	ds_read_b128 v[182:185], v208 offset:32768
	ds_read_b128 v[186:189], v208 offset:33792
	ds_read_b128 v[190:193], v208 offset:34816
	ds_read_b128 v[194:197], v208 offset:35840
	ds_read_b128 v[210:213], v208 offset:36864
	ds_read_b128 v[214:217], v208 offset:37888
	ds_read_b128 v[218:221], v208 offset:38912
	ds_read_b128 v[222:225], v208 offset:39936
	global_load_lds_dwordx4 v[232:233], off
	v_lshl_add_u64 v[232:233], s[54:55], 0, v[162:163]
	s_mov_b32 m0, s37
	s_nop 0
	global_load_lds_dwordx4 v[232:233], off
	s_waitcnt vmcnt(8)
	s_waitcnt lgkmcnt(0)
	s_setprio 1
	s_barrier
	v_mfma_f32_16x16x32_bf16 v[126:129], v[130:133], v[182:185], v[126:129]
	v_mfma_f32_16x16x32_bf16 v[122:125], v[138:141], v[182:185], v[122:125]
	v_mfma_f32_16x16x32_bf16 v[118:121], v[130:133], v[190:193], v[118:121]
	v_mfma_f32_16x16x32_bf16 v[114:117], v[138:141], v[190:193], v[114:117]
	v_mfma_f32_16x16x32_bf16 v[110:113], v[130:133], v[210:213], v[110:113]
	v_mfma_f32_16x16x32_bf16 v[106:109], v[138:141], v[210:213], v[106:109]
	v_mfma_f32_16x16x32_bf16 v[102:105], v[130:133], v[218:221], v[102:105]
	v_mfma_f32_16x16x32_bf16 v[98:101], v[138:141], v[218:221], v[98:101]
	v_mfma_f32_16x16x32_bf16 v[126:129], v[134:137], v[186:189], v[126:129]
	v_mfma_f32_16x16x32_bf16 v[122:125], v[142:145], v[186:189], v[122:125]
	v_mfma_f32_16x16x32_bf16 v[118:121], v[134:137], v[194:197], v[118:121]
	v_mfma_f32_16x16x32_bf16 v[114:117], v[142:145], v[194:197], v[114:117]
	v_mfma_f32_16x16x32_bf16 v[110:113], v[134:137], v[214:217], v[110:113]
	v_mfma_f32_16x16x32_bf16 v[106:109], v[142:145], v[214:217], v[106:109]
	v_mfma_f32_16x16x32_bf16 v[102:105], v[134:137], v[222:225], v[102:105]
	v_mfma_f32_16x16x32_bf16 v[98:101], v[142:145], v[222:225], v[98:101]
	s_setprio 0
	s_setprio 1
	v_mfma_f32_16x16x32_bf16 v[94:97], v[146:149], v[182:185], v[94:97]
	v_mfma_f32_16x16x32_bf16 v[90:93], v[154:157], v[182:185], v[90:93]
	v_mfma_f32_16x16x32_bf16 v[86:89], v[146:149], v[190:193], v[86:89]
	v_mfma_f32_16x16x32_bf16 v[82:85], v[154:157], v[190:193], v[82:85]
	v_mfma_f32_16x16x32_bf16 v[78:81], v[146:149], v[210:213], v[78:81]
	v_mfma_f32_16x16x32_bf16 v[74:77], v[154:157], v[210:213], v[74:77]
	v_mfma_f32_16x16x32_bf16 v[70:73], v[146:149], v[218:221], v[70:73]
	v_mfma_f32_16x16x32_bf16 v[66:69], v[154:157], v[218:221], v[66:69]
	v_mfma_f32_16x16x32_bf16 v[94:97], v[150:153], v[186:189], v[94:97]
	v_mfma_f32_16x16x32_bf16 v[90:93], v[178:181], v[186:189], v[90:93]
	v_mfma_f32_16x16x32_bf16 v[86:89], v[150:153], v[194:197], v[86:89]
	v_mfma_f32_16x16x32_bf16 v[82:85], v[178:181], v[194:197], v[82:85]
	v_mfma_f32_16x16x32_bf16 v[78:81], v[150:153], v[214:217], v[78:81]
	v_mfma_f32_16x16x32_bf16 v[74:77], v[178:181], v[214:217], v[74:77]
	v_mfma_f32_16x16x32_bf16 v[70:73], v[150:153], v[222:225], v[70:73]
	v_mfma_f32_16x16x32_bf16 v[66:69], v[178:181], v[222:225], v[66:69]
	s_barrier
; #define PG8_STAGE(bufoff, gbase, voff) do { _Pragma("unroll") for (int _i = 0; _i < 2; ++_i) \
;         __builtin_amdgcn_global_load_lds((const unsigned*)((const char*)(gbase) + (voff)[_i]), (PG8_LAS unsigned*)(lds + (bufoff) + ldsw + _i * 8192), 16, 0, 0); } while (0)
; #define PG8_LDA(dst, b, h) do { _Pragma("unroll") for (int m = 0; m < 4; ++m) _Pragma("unroll") for (int k = 0; k < 2; ++k) dst[m][k] = *(const PG8_LAS bf16x8*)(lds + PG8_SA(b, h) + aoff + m * 2048 + k * 1024); } while (0)
; #define PG8_MMA(ai, bj, At, Bt) do { __builtin_amdgcn_s_setprio(1); _Pragma("unroll") for (int m = 0; m < 4; ++m) _Pragma("unroll") for (int n = 0; n < 2; ++n) _Pragma("unroll") for (int k = 0; k < 2; ++k) \
;         acc[ai][bj][m][n] = __builtin_amdgcn_mfma_f32_16x16x32_bf16(Bt[n][k], At[m][k], acc[ai][bj][m][n], 0, 0, 0); __builtin_amdgcn_s_setprio(0); } while (0)
; #define PG8_WAIT_V(n) asm volatile("s_waitcnt vmcnt(" #n ")" ::: "memory")
; #define PG8_WAIT_L(n) asm volatile("s_waitcnt lgkmcnt(" #n ")" ::: "memory")
; #define PG8_BAR __builtin_amdgcn_s_barrier()
; #define PG8_SCHED __builtin_amdgcn_sched_barrier(0)
; template <class Epi, class Sched, bool ALIGN_EPI = false, bool SP2 = false, bool PAIR_ACC = false>
; __device__ __forceinline__ void gemm_phase(PG8_LAS unsigned char* lds, const Gemm g, const Sched& S, const Epi& E) {
;     ...
;             PG8_LDA(At, 1, 1); PG8_STAGE(PG8_SB(1, 0), b3, voffB); PG8_STAGE(PG8_SB(1, 1), b3 + hstep, voffB); PG8_STAGE(PG8_SA(1, 0), a3, voffA);
;             PG8_WAIT_V(8); PG8_WAIT_L(0); PG8_BAR; PG8_MMA(1, 0, At, B0); PG8_MMA(1, 1, At, B1); PG8_BAR; PG8_SCHED;
;     ...
;         if constexpr (ALIGN_EPI) { if (wr == 0) PG8_BAR; }
	s_setprio 0
	s_add_i32 s54, s57, s25
	v_lshl_add_u64 v[198:199], v[198:199], 0, s[18:19]
	s_mov_b32 m0, s54
	ds_read_b128 v[182:185], v208 offset:49152
	ds_read_b128 v[186:189], v208 offset:50176
	ds_read_b128 v[190:193], v208 offset:51200
	ds_read_b128 v[194:197], v208 offset:52224
	ds_read_b128 v[210:213], v208 offset:53248
	ds_read_b128 v[214:217], v208 offset:54272
	ds_read_b128 v[218:221], v208 offset:55296
	ds_read_b128 v[222:225], v208 offset:56320
	global_load_lds_dwordx4 v[198:199], off
	s_add_i32 m0, s54, 0x2000
	s_add_u32 s38, s38, 0x40080
	v_lshl_add_u64 v[198:199], v[226:227], 0, s[18:19]
	s_addc_u32 s39, s39, 0
	s_add_i32 s54, s58, s25
	global_load_lds_dwordx4 v[198:199], off
	v_lshl_add_u64 v[198:199], s[38:39], 0, v[160:161]
	s_mov_b32 m0, s54
	s_nop 0
	global_load_lds_dwordx4 v[198:199], off
	v_lshl_add_u64 v[198:199], s[38:39], 0, v[164:165]
	s_add_i32 m0, s54, 0x2000
	s_nop 0
	global_load_lds_dwordx4 v[198:199], off
	v_lshl_add_u64 v[198:199], v[228:229], 0, s[18:19]
	s_mov_b32 m0, s41
	s_nop 0
	global_load_lds_dwordx4 v[198:199], off
	v_lshl_add_u64 v[198:199], v[230:231], 0, s[18:19]
	s_mov_b32 m0, s44
	s_nop 0
	global_load_lds_dwordx4 v[198:199], off
	s_waitcnt vmcnt(8)
	s_waitcnt lgkmcnt(0)
	s_setprio 1
	s_barrier
	v_mfma_f32_16x16x32_bf16 v[62:65], v[130:133], v[182:185], v[62:65]
	v_mfma_f32_16x16x32_bf16 v[58:61], v[138:141], v[182:185], v[58:61]
	v_mfma_f32_16x16x32_bf16 v[54:57], v[130:133], v[190:193], v[54:57]
	v_mfma_f32_16x16x32_bf16 v[50:53], v[138:141], v[190:193], v[50:53]
	v_mfma_f32_16x16x32_bf16 v[46:49], v[130:133], v[210:213], v[46:49]
	v_mfma_f32_16x16x32_bf16 v[42:45], v[138:141], v[210:213], v[42:45]
	v_mfma_f32_16x16x32_bf16 v[38:41], v[130:133], v[218:221], v[38:41]
	v_mfma_f32_16x16x32_bf16 v[34:37], v[138:141], v[218:221], v[34:37]
	v_mfma_f32_16x16x32_bf16 v[62:65], v[134:137], v[186:189], v[62:65]
	v_mfma_f32_16x16x32_bf16 v[58:61], v[142:145], v[186:189], v[58:61]
	v_mfma_f32_16x16x32_bf16 v[54:57], v[134:137], v[194:197], v[54:57]
	v_mfma_f32_16x16x32_bf16 v[50:53], v[142:145], v[194:197], v[50:53]
	v_mfma_f32_16x16x32_bf16 v[46:49], v[134:137], v[214:217], v[46:49]
	v_mfma_f32_16x16x32_bf16 v[42:45], v[142:145], v[214:217], v[42:45]
	v_mfma_f32_16x16x32_bf16 v[38:41], v[134:137], v[222:225], v[38:41]
	v_mfma_f32_16x16x32_bf16 v[34:37], v[142:145], v[222:225], v[34:37]
	s_setprio 0
	s_setprio 1
	v_mfma_f32_16x16x32_bf16 v[30:33], v[146:149], v[182:185], v[30:33]
	v_mfma_f32_16x16x32_bf16 v[26:29], v[154:157], v[182:185], v[26:29]
	v_mfma_f32_16x16x32_bf16 v[22:25], v[146:149], v[190:193], v[22:25]
	v_mfma_f32_16x16x32_bf16 v[18:21], v[154:157], v[190:193], v[18:21]
	v_mfma_f32_16x16x32_bf16 v[14:17], v[146:149], v[210:213], v[14:17]
	v_mfma_f32_16x16x32_bf16 v[10:13], v[154:157], v[210:213], v[10:13]
	v_mfma_f32_16x16x32_bf16 v[6:9], v[146:149], v[218:221], v[6:9]
	v_mfma_f32_16x16x32_bf16 v[2:5], v[154:157], v[218:221], v[2:5]
	v_mfma_f32_16x16x32_bf16 v[30:33], v[150:153], v[186:189], v[30:33]
	v_mfma_f32_16x16x32_bf16 v[26:29], v[178:181], v[186:189], v[26:29]
	v_mfma_f32_16x16x32_bf16 v[22:25], v[150:153], v[194:197], v[22:25]
	v_mfma_f32_16x16x32_bf16 v[18:21], v[178:181], v[194:197], v[18:21]
	v_mfma_f32_16x16x32_bf16 v[14:17], v[150:153], v[214:217], v[14:17]
	v_mfma_f32_16x16x32_bf16 v[10:13], v[178:181], v[214:217], v[10:13]
	v_mfma_f32_16x16x32_bf16 v[6:9], v[150:153], v[222:225], v[6:9]
	v_mfma_f32_16x16x32_bf16 v[2:5], v[178:181], v[222:225], v[2:5]
	s_barrier
	s_setprio 0
	s_add_i32 s56, s56, 2
	s_add_u32 s8, s8, 0x100
	s_addc_u32 s9, s9, 0
	s_add_u32 s51, s51, 0x100
	s_addc_u32 s53, s53, 0
	s_cmp_gt_u32 s56, 13
	s_cbranch_scc0 .LBB0_585
	s_and_b64 vcc, exec, s[20:21]
	s_cbranch_vccz .LBB0_588
	s_barrier

; #define PG8_STAGE(bufoff, gbase, voff) do { _Pragma("unroll") for (int _i = 0; _i < 2; ++_i) \
;         __builtin_amdgcn_global_load_lds((const unsigned*)((const char*)(gbase) + (voff)[_i]), (PG8_LAS unsigned*)(lds + (bufoff) + ldsw + _i * 8192), 16, 0, 0); } while (0)
; #define PG8_LDA(dst, b, h) do { _Pragma("unroll") for (int m = 0; m < 4; ++m) _Pragma("unroll") for (int k = 0; k < 2; ++k) dst[m][k] = *(const PG8_LAS bf16x8*)(lds + PG8_SA(b, h) + aoff + m * 2048 + k * 1024); } while (0)
; #define PG8_LDB(dst, b, h) do { _Pragma("unroll") for (int n = 0; n < 2; ++n) _Pragma("unroll") for (int k = 0; k < 2; ++k) dst[n][k] = *(const PG8_LAS bf16x8*)(lds + PG8_SB(b, h) + boff + n * 2048 + k * 1024); } while (0)
; #define PG8_MMA(ai, bj, At, Bt) do { __builtin_amdgcn_s_setprio(1); _Pragma("unroll") for (int m = 0; m < 4; ++m) _Pragma("unroll") for (int n = 0; n < 2; ++n) _Pragma("unroll") for (int k = 0; k < 2; ++k) \
;         acc[ai][bj][m][n] = __builtin_amdgcn_mfma_f32_16x16x32_bf16(Bt[n][k], At[m][k], acc[ai][bj][m][n], 0, 0, 0); __builtin_amdgcn_s_setprio(0); } while (0)
; #define PG8_WAIT_V(n) asm volatile("s_waitcnt vmcnt(" #n ")" ::: "memory")
; #define PG8_WAIT_L(n) asm volatile("s_waitcnt lgkmcnt(" #n ")" ::: "memory")
; template <class Epi, class Sched, bool ALIGN_EPI = false, bool SP2 = false, bool PAIR_ACC = false>
; __device__ __forceinline__ void gemm_phase(PG8_LAS unsigned char* lds, const Gemm g, const Sched& S, const Epi& E) {
;     ...
;             const bool last = (t == nt - 2);
;             const char* a1 = cA + (size_t)(t + 1) * kstep;
;             const char* a2 = last ? nA : cA + (size_t)(t + 2) * kstep; const char* b2 = last ? nB : cB + (size_t)(t + 2) * kstep;
;             const char* a3 = a2 + kstep; const char* b3 = b2 + kstep;
;             if (last && has_next) S.a_ready(nxt);
;             if constexpr (SP2) {
;             PG8_LDB(B0, 0, 0); PG8_LDB(B1, 0, 1); PG8_SCHED; PG8_LDA(At, 0, 0); PG8_STAGE(PG8_SA(1, 1), a1 + hstep, voffA);
;             PG8_WAIT_V(8); PG8_WAIT_L(0); PG8_BAR; PG8_MMA(0, 0, At, B0); PG8_MMA(0, 1, At, B1); PG8_BAR; PG8_SCHED;
;             PG8_LDA(At, 0, 1); PG8_STAGE(PG8_SB(0, 0), b2, voffB); PG8_STAGE(PG8_SB(0, 1), b2 + hstep, voffB); PG8_STAGE(PG8_SA(0, 0), a2, voffA);
;             PG8_WAIT_V(8); PG8_WAIT_L(0); PG8_BAR; PG8_MMA(1, 0, At, B0); PG8_MMA(1, 1, At, B1); PG8_BAR; PG8_SCHED;
.LBB0_727:
	v_add_u32_e32 v164, s57, v150
	ds_read_b128 v[152:155], v164
	ds_read_b128 v[156:159], v164 offset:1024
	ds_read_b128 v[160:163], v164 offset:2048
	ds_read_b128 v[174:177], v164 offset:3072
	v_add_u32_e32 v164, s58, v150
	s_add_u32 s38, s20, s52
	ds_read_b128 v[178:181], v164
	ds_read_b128 v[182:185], v164 offset:1024
	ds_read_b128 v[186:189], v164 offset:2048
	ds_read_b128 v[190:193], v164 offset:3072
	s_addc_u32 s39, s21, s53
	s_add_u32 s38, s38, 0x100
	s_addc_u32 s39, s39, 0
	s_add_u32 s65, s60, s52
	s_addc_u32 s66, s61, s53
	s_cmpk_eq_i32 s52, 0x700
	s_cselect_b32 s55, s43, s39
	s_cselect_b32 s54, s62, s38
	s_cselect_b32 s39, s31, s66
	s_cselect_b32 s38, s63, s65
	v_lshl_add_u64 v[164:165], v[146:147], 0, s[52:53]
	s_add_i32 m0, s40, 0xc000
	ds_read_b128 v[194:197], v151
	ds_read_b128 v[206:209], v151 offset:1024
	ds_read_b128 v[210:213], v151 offset:2048
	ds_read_b128 v[214:217], v151 offset:3072
	ds_read_b128 v[218:221], v151 offset:4096
	ds_read_b128 v[222:225], v151 offset:5120
	ds_read_b128 v[226:229], v151 offset:6144
	ds_read_b128 v[230:233], v151 offset:7168
	global_load_lds_dwordx4 v[164:165], off
	v_lshl_add_u64 v[164:165], v[148:149], 0, s[52:53]
	s_add_i32 m0, s40, 0xe000
	s_nop 0
	global_load_lds_dwordx4 v[164:165], off
	s_waitcnt vmcnt(8)
	s_waitcnt lgkmcnt(0)
	s_setprio 1
	s_barrier
	v_mfma_f32_16x16x32_bf16 v[122:125], v[152:155], v[194:197], v[122:125]
	v_mfma_f32_16x16x32_bf16 v[126:129], v[160:163], v[194:197], v[126:129]
	v_mfma_f32_16x16x32_bf16 v[110:113], v[152:155], v[210:213], v[110:113]
	v_mfma_f32_16x16x32_bf16 v[106:109], v[160:163], v[210:213], v[106:109]
	v_mfma_f32_16x16x32_bf16 v[102:105], v[152:155], v[218:221], v[102:105]
	v_mfma_f32_16x16x32_bf16 v[98:101], v[160:163], v[218:221], v[98:101]
	v_mfma_f32_16x16x32_bf16 v[94:97], v[152:155], v[226:229], v[94:97]
	v_mfma_f32_16x16x32_bf16 v[90:93], v[160:163], v[226:229], v[90:93]
	v_mfma_f32_16x16x32_bf16 v[122:125], v[156:159], v[206:209], v[122:125]
	v_mfma_f32_16x16x32_bf16 v[126:129], v[174:177], v[206:209], v[126:129]
	v_mfma_f32_16x16x32_bf16 v[110:113], v[156:159], v[214:217], v[110:113]
	v_mfma_f32_16x16x32_bf16 v[106:109], v[174:177], v[214:217], v[106:109]
	v_mfma_f32_16x16x32_bf16 v[102:105], v[156:159], v[222:225], v[102:105]
	v_mfma_f32_16x16x32_bf16 v[98:101], v[174:177], v[222:225], v[98:101]
	v_mfma_f32_16x16x32_bf16 v[94:97], v[156:159], v[230:233], v[94:97]
	v_mfma_f32_16x16x32_bf16 v[90:93], v[174:177], v[230:233], v[90:93]
	s_setprio 0
	s_setprio 1
	v_mfma_f32_16x16x32_bf16 v[118:121], v[178:181], v[194:197], v[118:121]
	v_mfma_f32_16x16x32_bf16 v[114:117], v[186:189], v[194:197], v[114:117]
	v_mfma_f32_16x16x32_bf16 v[70:73], v[178:181], v[210:213], v[70:73]
	v_mfma_f32_16x16x32_bf16 v[66:69], v[186:189], v[210:213], v[66:69]
	v_mfma_f32_16x16x32_bf16 v[62:65], v[178:181], v[218:221], v[62:65]
	v_mfma_f32_16x16x32_bf16 v[58:61], v[186:189], v[218:221], v[58:61]
	v_mfma_f32_16x16x32_bf16 v[54:57], v[178:181], v[226:229], v[54:57]
	v_mfma_f32_16x16x32_bf16 v[50:53], v[186:189], v[226:229], v[50:53]
	v_mfma_f32_16x16x32_bf16 v[118:121], v[182:185], v[206:209], v[118:121]
	v_mfma_f32_16x16x32_bf16 v[114:117], v[190:193], v[206:209], v[114:117]
	v_mfma_f32_16x16x32_bf16 v[70:73], v[182:185], v[214:217], v[70:73]
	v_mfma_f32_16x16x32_bf16 v[66:69], v[190:193], v[214:217], v[66:69]
	v_mfma_f32_16x16x32_bf16 v[62:65], v[182:185], v[222:225], v[62:65]
	v_mfma_f32_16x16x32_bf16 v[58:61], v[190:193], v[222:225], v[58:61]
	v_mfma_f32_16x16x32_bf16 v[54:57], v[182:185], v[230:233], v[54:57]
	v_mfma_f32_16x16x32_bf16 v[50:53], v[190:193], v[230:233], v[50:53]
	s_barrier
	s_setprio 0
	s_add_i32 s65, s57, s37
	v_lshl_add_u64 v[164:165], s[38:39], 0, v[132:133]
	s_mov_b32 m0, s65
	ds_read_b128 v[194:197], v151 offset:16384
	ds_read_b128 v[206:209], v151 offset:17408
	ds_read_b128 v[210:213], v151 offset:18432
	ds_read_b128 v[214:217], v151 offset:19456
	ds_read_b128 v[218:221], v151 offset:20480
	ds_read_b128 v[222:225], v151 offset:21504
	ds_read_b128 v[226:229], v151 offset:22528
	ds_read_b128 v[230:233], v151 offset:23552
	global_load_lds_dwordx4 v[164:165], off
	s_add_i32 m0, s65, 0x2000
	s_add_u32 s66, s38, 0x40000
	v_lshl_add_u64 v[168:169], s[38:39], 0, v[136:137]
	s_addc_u32 s67, s39, 0
	s_add_i32 s65, s58, s37
	global_load_lds_dwordx4 v[168:169], off
	v_lshl_add_u64 v[198:199], s[66:67], 0, v[132:133]
	s_mov_b32 m0, s65
	v_lshl_add_u64 v[234:235], s[54:55], 0, v[134:135]
	global_load_lds_dwordx4 v[198:199], off
	v_lshl_add_u64 v[198:199], s[66:67], 0, v[136:137]
	s_add_i32 m0, s65, 0x2000
	s_nop 0
	global_load_lds_dwordx4 v[198:199], off
	v_lshl_add_u64 v[198:199], s[54:55], 0, v[130:131]
	s_mov_b32 m0, s40
	s_nop 0
	global_load_lds_dwordx4 v[198:199], off
	s_mov_b32 m0, s41
	s_nop 0
	global_load_lds_dwordx4 v[234:235], off
	s_waitcnt vmcnt(8)
	s_waitcnt lgkmcnt(0)
	s_setprio 1
	s_barrier
; #define PG8_STAGE(bufoff, gbase, voff) do { _Pragma("unroll") for (int _i = 0; _i < 2; ++_i) \
;         __builtin_amdgcn_global_load_lds((const unsigned*)((const char*)(gbase) + (voff)[_i]), (PG8_LAS unsigned*)(lds + (bufoff) + ldsw + _i * 8192), 16, 0, 0); } while (0)
; #define PG8_LDA(dst, b, h) do { _Pragma("unroll") for (int m = 0; m < 4; ++m) _Pragma("unroll") for (int k = 0; k < 2; ++k) dst[m][k] = *(const PG8_LAS bf16x8*)(lds + PG8_SA(b, h) + aoff + m * 2048 + k * 1024); } while (0)
; #define PG8_LDB(dst, b, h) do { _Pragma("unroll") for (int n = 0; n < 2; ++n) _Pragma("unroll") for (int k = 0; k < 2; ++k) dst[n][k] = *(const PG8_LAS bf16x8*)(lds + PG8_SB(b, h) + boff + n * 2048 + k * 1024); } while (0)
; #define PG8_MMA(ai, bj, At, Bt) do { __builtin_amdgcn_s_setprio(1); _Pragma("unroll") for (int m = 0; m < 4; ++m) _Pragma("unroll") for (int n = 0; n < 2; ++n) _Pragma("unroll") for (int k = 0; k < 2; ++k) \
;         acc[ai][bj][m][n] = __builtin_amdgcn_mfma_f32_16x16x32_bf16(Bt[n][k], At[m][k], acc[ai][bj][m][n], 0, 0, 0); __builtin_amdgcn_s_setprio(0); } while (0)
; #define PG8_WAIT_V(n) asm volatile("s_waitcnt vmcnt(" #n ")" ::: "memory")
; #define PG8_WAIT_L(n) asm volatile("s_waitcnt lgkmcnt(" #n ")" ::: "memory")
; #define PG8_BAR __builtin_amdgcn_s_barrier()
; #define PG8_SCHED __builtin_amdgcn_sched_barrier(0)
; template <class Epi, class Sched, bool ALIGN_EPI = false, bool SP2 = false, bool PAIR_ACC = false>
; __device__ __forceinline__ void gemm_phase(PG8_LAS unsigned char* lds, const Gemm g, const Sched& S, const Epi& E) {
;     ...
;             PG8_WAIT_V(8); PG8_WAIT_L(0); PG8_BAR; PG8_MMA(1, 0, At, B0); PG8_MMA(1, 1, At, B1); PG8_BAR; PG8_SCHED;
;             PG8_LDB(B0, 1, 0); PG8_LDB(B1, 1, 1); PG8_SCHED; PG8_LDA(At, 1, 0); PG8_STAGE(PG8_SA(0, 1), a2 + hstep, voffA);
;             PG8_WAIT_V(8); PG8_WAIT_L(0); PG8_BAR; PG8_MMA(0, 0, At, B0); PG8_MMA(0, 1, At, B1); PG8_BAR; PG8_SCHED;
	v_mfma_f32_16x16x32_bf16 v[86:89], v[152:155], v[194:197], v[86:89]
	v_mfma_f32_16x16x32_bf16 v[82:85], v[160:163], v[194:197], v[82:85]
	v_mfma_f32_16x16x32_bf16 v[78:81], v[152:155], v[210:213], v[78:81]
	v_mfma_f32_16x16x32_bf16 v[74:77], v[160:163], v[210:213], v[74:77]
	v_mfma_f32_16x16x32_bf16 v[30:33], v[152:155], v[218:221], v[30:33]
	v_mfma_f32_16x16x32_bf16 v[26:29], v[160:163], v[218:221], v[26:29]
	v_mfma_f32_16x16x32_bf16 v[14:17], v[152:155], v[226:229], v[14:17]
	v_mfma_f32_16x16x32_bf16 v[10:13], v[160:163], v[226:229], v[10:13]
	v_mfma_f32_16x16x32_bf16 v[86:89], v[156:159], v[206:209], v[86:89]
	v_mfma_f32_16x16x32_bf16 v[82:85], v[174:177], v[206:209], v[82:85]
	v_mfma_f32_16x16x32_bf16 v[78:81], v[156:159], v[214:217], v[78:81]
	v_mfma_f32_16x16x32_bf16 v[74:77], v[174:177], v[214:217], v[74:77]
	v_mfma_f32_16x16x32_bf16 v[30:33], v[156:159], v[222:225], v[30:33]
	v_mfma_f32_16x16x32_bf16 v[26:29], v[174:177], v[222:225], v[26:29]
	v_mfma_f32_16x16x32_bf16 v[14:17], v[156:159], v[230:233], v[14:17]
	v_mfma_f32_16x16x32_bf16 v[10:13], v[174:177], v[230:233], v[10:13]
	s_setprio 0
	s_setprio 1
	v_mfma_f32_16x16x32_bf16 v[46:49], v[178:181], v[194:197], v[46:49]
	v_mfma_f32_16x16x32_bf16 v[42:45], v[186:189], v[194:197], v[42:45]
	v_mfma_f32_16x16x32_bf16 v[38:41], v[178:181], v[210:213], v[38:41]
	v_mfma_f32_16x16x32_bf16 v[34:37], v[186:189], v[210:213], v[34:37]
	v_mfma_f32_16x16x32_bf16 v[22:25], v[178:181], v[218:221], v[22:25]
	v_mfma_f32_16x16x32_bf16 v[18:21], v[186:189], v[218:221], v[18:21]
	v_mfma_f32_16x16x32_bf16 v[6:9], v[178:181], v[226:229], v[6:9]
	v_mfma_f32_16x16x32_bf16 v[2:5], v[186:189], v[226:229], v[2:5]
	v_mfma_f32_16x16x32_bf16 v[46:49], v[182:185], v[206:209], v[46:49]
	v_mfma_f32_16x16x32_bf16 v[42:45], v[190:193], v[206:209], v[42:45]
	v_mfma_f32_16x16x32_bf16 v[38:41], v[182:185], v[214:217], v[38:41]
	v_mfma_f32_16x16x32_bf16 v[34:37], v[190:193], v[214:217], v[34:37]
	v_mfma_f32_16x16x32_bf16 v[22:25], v[182:185], v[222:225], v[22:25]
	v_mfma_f32_16x16x32_bf16 v[18:21], v[190:193], v[222:225], v[18:21]
	v_mfma_f32_16x16x32_bf16 v[6:9], v[182:185], v[230:233], v[6:9]
	v_mfma_f32_16x16x32_bf16 v[2:5], v[190:193], v[230:233], v[2:5]
	s_barrier
	s_setprio 0
	s_add_i32 s65, 0, 0x18000
	v_add_u32_e32 v167, s65, v150
	s_add_i32 s66, 0, 0x1c000
	ds_read_b128 v[152:155], v167
	ds_read_b128 v[156:159], v167 offset:1024
	ds_read_b128 v[160:163], v167 offset:2048
	ds_read_b128 v[174:177], v167 offset:3072
	v_add_u32_e32 v167, s66, v150
	ds_read_b128 v[178:181], v167
	ds_read_b128 v[182:185], v167 offset:1024
	ds_read_b128 v[186:189], v167 offset:2048
	ds_read_b128 v[190:193], v167 offset:3072
	s_add_u32 s54, s54, 0x40000
	s_addc_u32 s55, s55, 0
	s_mov_b32 m0, s44
	v_lshl_add_u64 v[236:237], s[54:55], 0, v[130:131]
	ds_read_b128 v[194:197], v151 offset:32768
	ds_read_b128 v[206:209], v151 offset:33792
	ds_read_b128 v[210:213], v151 offset:34816
	ds_read_b128 v[214:217], v151 offset:35840
	ds_read_b128 v[218:221], v151 offset:36864
	ds_read_b128 v[222:225], v151 offset:37888
	ds_read_b128 v[226:229], v151 offset:38912
	ds_read_b128 v[230:233], v151 offset:39936
	global_load_lds_dwordx4 v[236:237], off
	v_lshl_add_u64 v[236:237], s[54:55], 0, v[134:135]
	s_mov_b32 m0, s45
	s_nop 0
	global_load_lds_dwordx4 v[236:237], off
	s_waitcnt vmcnt(8)
	s_waitcnt lgkmcnt(0)
	s_setprio 1
	s_barrier
	v_mfma_f32_16x16x32_bf16 v[122:125], v[152:155], v[194:197], v[122:125]
	v_mfma_f32_16x16x32_bf16 v[126:129], v[160:163], v[194:197], v[126:129]
	v_mfma_f32_16x16x32_bf16 v[110:113], v[152:155], v[210:213], v[110:113]
	v_mfma_f32_16x16x32_bf16 v[106:109], v[160:163], v[210:213], v[106:109]
	v_mfma_f32_16x16x32_bf16 v[102:105], v[152:155], v[218:221], v[102:105]
	v_mfma_f32_16x16x32_bf16 v[98:101], v[160:163], v[218:221], v[98:101]
	v_mfma_f32_16x16x32_bf16 v[94:97], v[152:155], v[226:229], v[94:97]
	v_mfma_f32_16x16x32_bf16 v[90:93], v[160:163], v[226:229], v[90:93]
	v_mfma_f32_16x16x32_bf16 v[122:125], v[156:159], v[206:209], v[122:125]
	v_mfma_f32_16x16x32_bf16 v[126:129], v[174:177], v[206:209], v[126:129]
	v_mfma_f32_16x16x32_bf16 v[110:113], v[156:159], v[214:217], v[110:113]
	v_mfma_f32_16x16x32_bf16 v[106:109], v[174:177], v[214:217], v[106:109]
	v_mfma_f32_16x16x32_bf16 v[102:105], v[156:159], v[222:225], v[102:105]
	v_mfma_f32_16x16x32_bf16 v[98:101], v[174:177], v[222:225], v[98:101]
	v_mfma_f32_16x16x32_bf16 v[94:97], v[156:159], v[230:233], v[94:97]
	v_mfma_f32_16x16x32_bf16 v[90:93], v[174:177], v[230:233], v[90:93]
	s_setprio 0
	s_setprio 1
	v_mfma_f32_16x16x32_bf16 v[118:121], v[178:181], v[194:197], v[118:121]
	v_mfma_f32_16x16x32_bf16 v[114:117], v[186:189], v[194:197], v[114:117]
	v_mfma_f32_16x16x32_bf16 v[70:73], v[178:181], v[210:213], v[70:73]
	v_mfma_f32_16x16x32_bf16 v[66:69], v[186:189], v[210:213], v[66:69]
	v_mfma_f32_16x16x32_bf16 v[62:65], v[178:181], v[218:221], v[62:65]
	v_mfma_f32_16x16x32_bf16 v[58:61], v[186:189], v[218:221], v[58:61]
	v_mfma_f32_16x16x32_bf16 v[54:57], v[178:181], v[226:229], v[54:57]
	v_mfma_f32_16x16x32_bf16 v[50:53], v[186:189], v[226:229], v[50:53]
	v_mfma_f32_16x16x32_bf16 v[118:121], v[182:185], v[206:209], v[118:121]
	v_mfma_f32_16x16x32_bf16 v[114:117], v[190:193], v[206:209], v[114:117]
	v_mfma_f32_16x16x32_bf16 v[70:73], v[182:185], v[214:217], v[70:73]
	v_mfma_f32_16x16x32_bf16 v[66:69], v[190:193], v[214:217], v[66:69]
	v_mfma_f32_16x16x32_bf16 v[62:65], v[182:185], v[222:225], v[62:65]
	v_mfma_f32_16x16x32_bf16 v[58:61], v[190:193], v[222:225], v[58:61]
	v_mfma_f32_16x16x32_bf16 v[54:57], v[182:185], v[230:233], v[54:57]
	v_mfma_f32_16x16x32_bf16 v[50:53], v[190:193], v[230:233], v[50:53]
	s_barrier
; #define PG8_STAGE(bufoff, gbase, voff) do { _Pragma("unroll") for (int _i = 0; _i < 2; ++_i) \
;         __builtin_amdgcn_global_load_lds((const unsigned*)((const char*)(gbase) + (voff)[_i]), (PG8_LAS unsigned*)(lds + (bufoff) + ldsw + _i * 8192), 16, 0, 0); } while (0)
; #define PG8_LDA(dst, b, h) do { _Pragma("unroll") for (int m = 0; m < 4; ++m) _Pragma("unroll") for (int k = 0; k < 2; ++k) dst[m][k] = *(const PG8_LAS bf16x8*)(lds + PG8_SA(b, h) + aoff + m * 2048 + k * 1024); } while (0)
; #define PG8_MMA(ai, bj, At, Bt) do { __builtin_amdgcn_s_setprio(1); _Pragma("unroll") for (int m = 0; m < 4; ++m) _Pragma("unroll") for (int n = 0; n < 2; ++n) _Pragma("unroll") for (int k = 0; k < 2; ++k) \
;         acc[ai][bj][m][n] = __builtin_amdgcn_mfma_f32_16x16x32_bf16(Bt[n][k], At[m][k], acc[ai][bj][m][n], 0, 0, 0); __builtin_amdgcn_s_setprio(0); } while (0)
; #define PG8_WAIT_V(n) asm volatile("s_waitcnt vmcnt(" #n ")" ::: "memory")
; #define PG8_WAIT_L(n) asm volatile("s_waitcnt lgkmcnt(" #n ")" ::: "memory")
; #define PG8_BAR __builtin_amdgcn_s_barrier()
; #define PG8_SCHED __builtin_amdgcn_sched_barrier(0)
; template <class Epi, class Sched, bool ALIGN_EPI = false, bool SP2 = false, bool PAIR_ACC = false>
; __device__ __forceinline__ void gemm_phase(PG8_LAS unsigned char* lds, const Gemm g, const Sched& S, const Epi& E) {
;     ...
;             PG8_LDA(At, 1, 1); PG8_STAGE(PG8_SB(1, 0), b3, voffB); PG8_STAGE(PG8_SB(1, 1), b3 + hstep, voffB); PG8_STAGE(PG8_SA(1, 0), a3, voffA);
;             PG8_WAIT_V(8); PG8_WAIT_L(0); PG8_BAR; PG8_MMA(1, 0, At, B0); PG8_MMA(1, 1, At, B1); PG8_BAR; PG8_SCHED;
;     ...
;         if (!has_next) break;
;         if (!(PAIR_ACC && cur.pn < 4)) {
; #pragma unroll
;         for (int a = 0; a < 2; ++a)
; #pragma unroll
;             for (int b = 0; b < 2; ++b)
; #pragma unroll
;                 for (int m = 0; m < 4; ++m)
; #pragma unroll
;                     for (int n = 0; n < 2; ++n) acc[a][b][m][n] = (f32x4){0.f, 0.f, 0.f, 0.f};
;         }
;         cur = nxt; cA = nA; cB = nB; ++ui;
	s_setprio 0
	s_add_i32 s54, s65, s37
	v_lshl_add_u64 v[164:165], v[164:165], 0, s[28:29]
	s_mov_b32 m0, s54
	ds_read_b128 v[194:197], v151 offset:49152
	ds_read_b128 v[206:209], v151 offset:50176
	ds_read_b128 v[210:213], v151 offset:51200
	ds_read_b128 v[214:217], v151 offset:52224
	ds_read_b128 v[218:221], v151 offset:53248
	ds_read_b128 v[222:225], v151 offset:54272
	ds_read_b128 v[226:229], v151 offset:55296
	ds_read_b128 v[230:233], v151 offset:56320
	global_load_lds_dwordx4 v[164:165], off
	s_add_i32 m0, s54, 0x2000
	s_add_u32 s38, s38, 0x40080
	v_lshl_add_u64 v[164:165], v[168:169], 0, s[28:29]
	s_addc_u32 s39, s39, 0
	s_add_i32 s54, s66, s37
	global_load_lds_dwordx4 v[164:165], off
	v_lshl_add_u64 v[164:165], s[38:39], 0, v[132:133]
	s_mov_b32 m0, s54
	s_nop 0
	global_load_lds_dwordx4 v[164:165], off
	v_lshl_add_u64 v[164:165], s[38:39], 0, v[136:137]
	s_add_i32 m0, s54, 0x2000
	s_nop 0
	global_load_lds_dwordx4 v[164:165], off
	v_lshl_add_u64 v[164:165], v[198:199], 0, s[28:29]
	s_mov_b32 m0, s47
	s_nop 0
	global_load_lds_dwordx4 v[164:165], off
	v_lshl_add_u64 v[164:165], v[234:235], 0, s[28:29]
	s_mov_b32 m0, s56
	s_nop 0
	global_load_lds_dwordx4 v[164:165], off
	s_waitcnt vmcnt(8)
	s_waitcnt lgkmcnt(0)
	s_setprio 1
	s_barrier
	v_mfma_f32_16x16x32_bf16 v[86:89], v[152:155], v[194:197], v[86:89]
	v_mfma_f32_16x16x32_bf16 v[82:85], v[160:163], v[194:197], v[82:85]
	v_mfma_f32_16x16x32_bf16 v[78:81], v[152:155], v[210:213], v[78:81]
	v_mfma_f32_16x16x32_bf16 v[74:77], v[160:163], v[210:213], v[74:77]
	v_mfma_f32_16x16x32_bf16 v[30:33], v[152:155], v[218:221], v[30:33]
	v_mfma_f32_16x16x32_bf16 v[26:29], v[160:163], v[218:221], v[26:29]
	v_mfma_f32_16x16x32_bf16 v[14:17], v[152:155], v[226:229], v[14:17]
	v_mfma_f32_16x16x32_bf16 v[10:13], v[160:163], v[226:229], v[10:13]
	v_mfma_f32_16x16x32_bf16 v[86:89], v[156:159], v[206:209], v[86:89]
	v_mfma_f32_16x16x32_bf16 v[82:85], v[174:177], v[206:209], v[82:85]
	v_mfma_f32_16x16x32_bf16 v[78:81], v[156:159], v[214:217], v[78:81]
	v_mfma_f32_16x16x32_bf16 v[74:77], v[174:177], v[214:217], v[74:77]
	v_mfma_f32_16x16x32_bf16 v[30:33], v[156:159], v[222:225], v[30:33]
	v_mfma_f32_16x16x32_bf16 v[26:29], v[174:177], v[222:225], v[26:29]
	v_mfma_f32_16x16x32_bf16 v[14:17], v[156:159], v[230:233], v[14:17]
	v_mfma_f32_16x16x32_bf16 v[10:13], v[174:177], v[230:233], v[10:13]
	s_setprio 0
	s_setprio 1
	v_mfma_f32_16x16x32_bf16 v[46:49], v[178:181], v[194:197], v[46:49]
	v_mfma_f32_16x16x32_bf16 v[42:45], v[186:189], v[194:197], v[42:45]
	v_mfma_f32_16x16x32_bf16 v[38:41], v[178:181], v[210:213], v[38:41]
	v_mfma_f32_16x16x32_bf16 v[34:37], v[186:189], v[210:213], v[34:37]
	v_mfma_f32_16x16x32_bf16 v[22:25], v[178:181], v[218:221], v[22:25]
	v_mfma_f32_16x16x32_bf16 v[18:21], v[186:189], v[218:221], v[18:21]
	v_mfma_f32_16x16x32_bf16 v[6:9], v[178:181], v[226:229], v[6:9]
	v_mfma_f32_16x16x32_bf16 v[2:5], v[186:189], v[226:229], v[2:5]
	v_mfma_f32_16x16x32_bf16 v[46:49], v[182:185], v[206:209], v[46:49]
	v_mfma_f32_16x16x32_bf16 v[42:45], v[190:193], v[206:209], v[42:45]
	v_mfma_f32_16x16x32_bf16 v[38:41], v[182:185], v[214:217], v[38:41]
	v_mfma_f32_16x16x32_bf16 v[34:37], v[190:193], v[214:217], v[34:37]
	v_mfma_f32_16x16x32_bf16 v[22:25], v[182:185], v[222:225], v[22:25]
	v_mfma_f32_16x16x32_bf16 v[18:21], v[190:193], v[222:225], v[18:21]
	v_mfma_f32_16x16x32_bf16 v[6:9], v[182:185], v[230:233], v[6:9]
	v_mfma_f32_16x16x32_bf16 v[2:5], v[190:193], v[230:233], v[2:5]
	s_barrier
	s_setprio 0
	s_add_i32 s64, s64, 2
	s_add_u32 s52, s52, 0x100
	s_addc_u32 s53, s53, 0
	s_cmp_gt_u32 s64, 13
	s_cbranch_scc0 .LBB0_727
	s_add_u32 s38, s60, 0xffffff00
	s_addc_u32 s39, s61, -1
	s_andn2_b64 vcc, exec, s[8:9]
	s_cbranch_vccnz .LBB0_718
	v_mov_b32_e32 v2, 0
	s_mov_b32 s10, s30
	s_mov_b32 s16, s42
	s_mov_b64 s[20:21], s[50:51]
	s_mov_b32 s46, s59
	v_mov_b32_e32 v3, v2
	v_mov_b32_e32 v4, v2
	v_mov_b32_e32 v5, v2
	v_mov_b32_e32 v6, v2
	v_mov_b32_e32 v7, v2
	v_mov_b32_e32 v8, v2
	v_mov_b32_e32 v9, v2
	v_mov_b32_e32 v18, v2
	v_mov_b32_e32 v19, v2
	v_mov_b32_e32 v20, v2
	v_mov_b32_e32 v21, v2
	v_mov_b32_e32 v22, v2
	v_mov_b32_e32 v23, v2
	v_mov_b32_e32 v24, v2
	v_mov_b32_e32 v25, v2
	v_mov_b32_e32 v34, v2
	v_mov_b32_e32 v35, v2
	v_mov_b32_e32 v36, v2
	v_mov_b32_e32 v37, v2
	v_mov_b32_e32 v38, v2
	v_mov_b32_e32 v39, v2
	v_mov_b32_e32 v40, v2
	v_mov_b32_e32 v41, v2
	v_mov_b32_e32 v42, v2
	v_mov_b32_e32 v43, v2
	v_mov_b32_e32 v44, v2
	v_mov_b32_e32 v45, v2
	v_mov_b32_e32 v46, v2
	v_mov_b32_e32 v47, v2
	v_mov_b32_e32 v48, v2
	v_mov_b32_e32 v49, v2
	v_mov_b32_e32 v10, v2
	v_mov_b32_e32 v11, v2
	v_mov_b32_e32 v12, v2
	v_mov_b32_e32 v13, v2
	v_mov_b32_e32 v14, v2
	v_mov_b32_e32 v15, v2
	v_mov_b32_e32 v16, v2
	v_mov_b32_e32 v17, v2
	v_mov_b32_e32 v26, v2
	v_mov_b32_e32 v27, v2
	v_mov_b32_e32 v28, v2
	v_mov_b32_e32 v29, v2
	v_mov_b32_e32 v30, v2
	v_mov_b32_e32 v31, v2
	v_mov_b32_e32 v32, v2
	v_mov_b32_e32 v33, v2
	v_mov_b32_e32 v74, v2
	v_mov_b32_e32 v75, v2
	v_mov_b32_e32 v76, v2
	v_mov_b32_e32 v77, v2
	v_mov_b32_e32 v78, v2
	v_mov_b32_e32 v79, v2
	v_mov_b32_e32 v80, v2
	v_mov_b32_e32 v81, v2
	v_mov_b32_e32 v82, v2
	v_mov_b32_e32 v83, v2
	v_mov_b32_e32 v84, v2
	v_mov_b32_e32 v85, v2
	v_mov_b32_e32 v86, v2
	v_mov_b32_e32 v87, v2
	v_mov_b32_e32 v88, v2
	v_mov_b32_e32 v89, v2
	v_mov_b32_e32 v50, v2
	v_mov_b32_e32 v51, v2
	v_mov_b32_e32 v52, v2
	v_mov_b32_e32 v53, v2
	v_mov_b32_e32 v54, v2
	v_mov_b32_e32 v55, v2
	v_mov_b32_e32 v56, v2
	v_mov_b32_e32 v57, v2
	v_mov_b32_e32 v58, v2
	v_mov_b32_e32 v59, v2
	v_mov_b32_e32 v60, v2
	v_mov_b32_e32 v61, v2
	v_mov_b32_e32 v62, v2
	v_mov_b32_e32 v63, v2
	v_mov_b32_e32 v64, v2
	v_mov_b32_e32 v65, v2
	v_mov_b32_e32 v66, v2
	v_mov_b32_e32 v67, v2
	v_mov_b32_e32 v68, v2
	v_mov_b32_e32 v69, v2
	v_mov_b32_e32 v70, v2
	v_mov_b32_e32 v71, v2
	v_mov_b32_e32 v72, v2
	v_mov_b32_e32 v73, v2
	v_mov_b32_e32 v114, v2
	v_mov_b32_e32 v115, v2
	v_mov_b32_e32 v116, v2
	v_mov_b32_e32 v117, v2
	v_mov_b32_e32 v118, v2
	v_mov_b32_e32 v119, v2
	v_mov_b32_e32 v120, v2
	v_mov_b32_e32 v121, v2
	v_mov_b32_e32 v90, v2
	v_mov_b32_e32 v91, v2
	v_mov_b32_e32 v92, v2
	v_mov_b32_e32 v93, v2
	v_mov_b32_e32 v94, v2
	v_mov_b32_e32 v95, v2
	v_mov_b32_e32 v96, v2
	v_mov_b32_e32 v97, v2
	v_mov_b32_e32 v98, v2
	v_mov_b32_e32 v99, v2
	v_mov_b32_e32 v100, v2
	v_mov_b32_e32 v101, v2
	v_mov_b32_e32 v102, v2
	v_mov_b32_e32 v103, v2
	v_mov_b32_e32 v104, v2
	v_mov_b32_e32 v105, v2
	v_mov_b32_e32 v106, v2
	v_mov_b32_e32 v107, v2
	v_mov_b32_e32 v108, v2
	v_mov_b32_e32 v109, v2
	v_mov_b32_e32 v110, v2
	v_mov_b32_e32 v111, v2
	v_mov_b32_e32 v112, v2
	v_mov_b32_e32 v113, v2
	v_mov_b32_e32 v126, v2
	v_mov_b32_e32 v127, v2
	v_mov_b32_e32 v128, v2
	v_mov_b32_e32 v129, v2
	v_mov_b32_e32 v122, v2
	v_mov_b32_e32 v123, v2
	v_mov_b32_e32 v124, v2
	v_mov_b32_e32 v125, v2
	s_andn2_b64 vcc, exec, s[6:7]
	s_cbranch_vccnz .LBB0_719

; #define PG8_STAGE(bufoff, gbase, voff) do { _Pragma("unroll") for (int _i = 0; _i < 2; ++_i) \
;         __builtin_amdgcn_global_load_lds((const unsigned*)((const char*)(gbase) + (voff)[_i]), (PG8_LAS unsigned*)(lds + (bufoff) + ldsw + _i * 8192), 16, 0, 0); } while (0)
; #define PG8_LDA(dst, b, h) do { _Pragma("unroll") for (int m = 0; m < 4; ++m) _Pragma("unroll") for (int k = 0; k < 2; ++k) dst[m][k] = *(const PG8_LAS bf16x8*)(lds + PG8_SA(b, h) + aoff + m * 2048 + k * 1024); } while (0)
; #define PG8_LDB(dst, b, h) do { _Pragma("unroll") for (int n = 0; n < 2; ++n) _Pragma("unroll") for (int k = 0; k < 2; ++k) dst[n][k] = *(const PG8_LAS bf16x8*)(lds + PG8_SB(b, h) + boff + n * 2048 + k * 1024); } while (0)
; #define PG8_WAIT_V(n) asm volatile("s_waitcnt vmcnt(" #n ")" ::: "memory")
; #define PG8_WAIT_L(n) asm volatile("s_waitcnt lgkmcnt(" #n ")" ::: "memory")
; #define PG8_BAR __builtin_amdgcn_s_barrier()
; template <class Epi, class Sched, bool ALIGN_EPI = false, bool SP2 = false, bool PAIR_ACC = false>
; __device__ __forceinline__ void gemm_phase(PG8_LAS unsigned char* lds, const Gemm g, const Sched& S, const Epi& E) {
;     ...
;         const bool has_next = S.next(ui + 1, nxt);
;         const char* nA = has_next ? (const char*)g.A + (size_t)nxt.pm * tstep + (size_t)(nxt.pn / g.a_div) * g.a_sel : cA; const char* nB = has_next ? (const char*)g.Bt + (size_t)nxt.pn * tstep : cB;
;         for (int t = 0; t < nt; t += 2) {
;             const bool last = (t == nt - 2);
;             const char* a1 = cA + (size_t)(t + 1) * kstep;
;             const char* a2 = last ? nA : cA + (size_t)(t + 2) * kstep; const char* b2 = last ? nB : cB + (size_t)(t + 2) * kstep;
;             const char* a3 = a2 + kstep; const char* b3 = b2 + kstep;
;             if (last && has_next) S.a_ready(nxt);
;             if constexpr (SP2) {
;             PG8_LDB(B0, 0, 0); PG8_LDB(B1, 0, 1); PG8_SCHED; PG8_LDA(At, 0, 0); PG8_STAGE(PG8_SA(1, 1), a1 + hstep, voffA);
;             PG8_WAIT_V(8); PG8_WAIT_L(0); PG8_BAR; PG8_MMA(0, 0, At, B0); PG8_MMA(0, 1, At, B1); PG8_BAR; PG8_SCHED;
;             PG8_LDA(At, 0, 1); PG8_STAGE(PG8_SB(0, 0), b2, voffB); PG8_STAGE(PG8_SB(0, 1), b2 + hstep, voffB); PG8_STAGE(PG8_SA(0, 0), a2, voffA);
;             PG8_WAIT_V(8); PG8_WAIT_L(0); PG8_BAR; PG8_MMA(1, 0, At, B0); PG8_MMA(1, 1, At, B1); PG8_BAR; PG8_SCHED;
.LBB0_833:
	s_ashr_i32 s65, s64, 31
	s_lshl_b64 s[40:41], s[64:65], 19
	s_add_u32 s66, s4, s40
	s_addc_u32 s67, s5, s41
	s_and_b64 s[40:41], s[8:9], exec
	s_cselect_b32 s40, s67, s11
	s_cselect_b32 s41, s66, s10
	s_ashr_i32 s63, s62, 31
	s_lshl_b64 s[68:69], s[62:63], 19
	s_add_u32 s68, s23, s68
	s_addc_u32 s69, s24, s69
	s_and_b64 s[72:73], s[8:9], exec
	s_cselect_b32 s63, s69, s39
	s_cselect_b32 s65, s68, s38
	s_add_u32 s10, s10, 0x40080
	s_addc_u32 s11, s11, 0
	s_add_u32 s78, s38, 0x100
	s_addc_u32 s79, s39, 0
	s_mov_b32 s80, -2
	ds_read_b128 v[74:77], v197
	ds_read_b128 v[78:81], v197 offset:1024
	ds_read_b128 v[82:85], v197 offset:2048
	ds_read_b128 v[86:89], v197 offset:3072
	ds_read_b128 v[90:93], v198
	ds_read_b128 v[94:97], v198 offset:1024
	ds_read_b128 v[98:101], v198 offset:2048
	ds_read_b128 v[106:109], v198 offset:3072
	s_add_u32 s38, s10, 0xfffc0080
	s_addc_u32 s39, s11, -1
	s_cmp_eq_u32 s80, 12
	s_cselect_b32 s73, s40, s39
	s_cselect_b32 s72, s41, s38
	s_cselect_b32 s39, s63, s79
	s_cselect_b32 s38, s65, s78
	v_lshl_add_u64 v[170:171], s[10:11], 0, v[186:187]
	s_add_i32 m0, s36, 0xc000
	ds_read_b128 v[162:165], v199
	ds_read_b128 v[166:169], v199 offset:1024
	ds_read_b128 v[210:213], v199 offset:2048
	ds_read_b128 v[214:217], v199 offset:3072
	ds_read_b128 v[218:221], v199 offset:4096
	ds_read_b128 v[222:225], v199 offset:5120
	ds_read_b128 v[226:229], v199 offset:6144
	ds_read_b128 v[230:233], v199 offset:7168
	global_load_lds_dwordx4 v[170:171], off
	v_lshl_add_u64 v[170:171], s[10:11], 0, v[188:189]
	s_add_i32 m0, s36, 0xe000
	s_nop 0
	global_load_lds_dwordx4 v[170:171], off
	s_waitcnt vmcnt(8)
	s_waitcnt lgkmcnt(0)
	s_setprio 1
	s_barrier
	v_mfma_f32_16x16x32_bf16 v[150:153], v[74:77], v[162:165], 0
	v_mfma_f32_16x16x32_bf16 v[146:149], v[82:85], v[162:165], 0
	v_mfma_f32_16x16x32_bf16 v[134:137], v[74:77], v[210:213], 0
	v_mfma_f32_16x16x32_bf16 v[130:133], v[82:85], v[210:213], 0
	v_mfma_f32_16x16x32_bf16 v[118:121], v[74:77], v[218:221], 0
	v_mfma_f32_16x16x32_bf16 v[110:113], v[82:85], v[218:221], 0
	v_mfma_f32_16x16x32_bf16 v[114:117], v[74:77], v[226:229], 0
	v_mfma_f32_16x16x32_bf16 v[102:105], v[82:85], v[226:229], 0
	v_mfma_f32_16x16x32_bf16 v[150:153], v[78:81], v[166:169], v[150:153]
	v_mfma_f32_16x16x32_bf16 v[146:149], v[86:89], v[166:169], v[146:149]
	v_mfma_f32_16x16x32_bf16 v[134:137], v[78:81], v[214:217], v[134:137]
	v_mfma_f32_16x16x32_bf16 v[130:133], v[86:89], v[214:217], v[130:133]
	v_mfma_f32_16x16x32_bf16 v[118:121], v[78:81], v[222:225], v[118:121]
	v_mfma_f32_16x16x32_bf16 v[110:113], v[86:89], v[222:225], v[110:113]
	v_mfma_f32_16x16x32_bf16 v[114:117], v[78:81], v[230:233], v[114:117]
	v_mfma_f32_16x16x32_bf16 v[102:105], v[86:89], v[230:233], v[102:105]
	s_setprio 0
	s_setprio 1
	v_mfma_f32_16x16x32_bf16 v[158:161], v[90:93], v[162:165], 0
	v_mfma_f32_16x16x32_bf16 v[154:157], v[98:101], v[162:165], 0
	v_mfma_f32_16x16x32_bf16 v[142:145], v[90:93], v[210:213], 0
	v_mfma_f32_16x16x32_bf16 v[138:141], v[98:101], v[210:213], 0
	v_mfma_f32_16x16x32_bf16 v[126:129], v[90:93], v[218:221], 0
	v_mfma_f32_16x16x32_bf16 v[122:125], v[98:101], v[218:221], 0
	v_mfma_f32_16x16x32_bf16 v[70:73], v[90:93], v[226:229], 0
	v_mfma_f32_16x16x32_bf16 v[66:69], v[98:101], v[226:229], 0
	v_mfma_f32_16x16x32_bf16 v[158:161], v[94:97], v[166:169], v[158:161]
	v_mfma_f32_16x16x32_bf16 v[154:157], v[106:109], v[166:169], v[154:157]
	v_mfma_f32_16x16x32_bf16 v[142:145], v[94:97], v[214:217], v[142:145]
	v_mfma_f32_16x16x32_bf16 v[138:141], v[106:109], v[214:217], v[138:141]
	v_mfma_f32_16x16x32_bf16 v[126:129], v[94:97], v[222:225], v[126:129]
	v_mfma_f32_16x16x32_bf16 v[122:125], v[106:109], v[222:225], v[122:125]
	v_mfma_f32_16x16x32_bf16 v[70:73], v[94:97], v[230:233], v[70:73]
	v_mfma_f32_16x16x32_bf16 v[66:69], v[106:109], v[230:233], v[66:69]
	s_barrier
	s_setprio 0
	s_add_i32 s81, s61, s25
	v_lshl_add_u64 v[170:171], s[38:39], 0, v[178:179]
	s_mov_b32 m0, s81
	ds_read_b128 v[162:165], v199 offset:16384
	ds_read_b128 v[166:169], v199 offset:17408
	ds_read_b128 v[210:213], v199 offset:18432
	ds_read_b128 v[214:217], v199 offset:19456
	ds_read_b128 v[218:221], v199 offset:20480
	ds_read_b128 v[222:225], v199 offset:21504
	ds_read_b128 v[226:229], v199 offset:22528
	ds_read_b128 v[230:233], v199 offset:23552
	global_load_lds_dwordx4 v[170:171], off
	s_add_i32 m0, s81, 0x2000
	s_add_u32 s82, s38, 0x40000
	v_lshl_add_u64 v[194:195], s[38:39], 0, v[174:175]
	s_addc_u32 s83, s39, 0
	s_add_i32 s81, s74, s25
	global_load_lds_dwordx4 v[194:195], off
	v_lshl_add_u64 v[234:235], s[82:83], 0, v[178:179]
	s_mov_b32 m0, s81
	v_lshl_add_u64 v[236:237], s[72:73], 0, v[176:177]
	global_load_lds_dwordx4 v[234:235], off
	v_lshl_add_u64 v[234:235], s[82:83], 0, v[174:175]
	s_add_i32 m0, s81, 0x2000
	s_nop 0
	global_load_lds_dwordx4 v[234:235], off
	v_lshl_add_u64 v[234:235], s[72:73], 0, v[180:181]
	s_mov_b32 m0, s36
	s_nop 0
	global_load_lds_dwordx4 v[234:235], off
	s_mov_b32 m0, s37
	s_nop 0
	global_load_lds_dwordx4 v[236:237], off
	s_waitcnt vmcnt(8)
	s_waitcnt lgkmcnt(0)
	s_setprio 1
	s_barrier
; #define PG8_STAGE(bufoff, gbase, voff) do { _Pragma("unroll") for (int _i = 0; _i < 2; ++_i) \
;         __builtin_amdgcn_global_load_lds((const unsigned*)((const char*)(gbase) + (voff)[_i]), (PG8_LAS unsigned*)(lds + (bufoff) + ldsw + _i * 8192), 16, 0, 0); } while (0)
; #define PG8_LDA(dst, b, h) do { _Pragma("unroll") for (int m = 0; m < 4; ++m) _Pragma("unroll") for (int k = 0; k < 2; ++k) dst[m][k] = *(const PG8_LAS bf16x8*)(lds + PG8_SA(b, h) + aoff + m * 2048 + k * 1024); } while (0)
; #define PG8_LDB(dst, b, h) do { _Pragma("unroll") for (int n = 0; n < 2; ++n) _Pragma("unroll") for (int k = 0; k < 2; ++k) dst[n][k] = *(const PG8_LAS bf16x8*)(lds + PG8_SB(b, h) + boff + n * 2048 + k * 1024); } while (0)
; #define PG8_MMA(ai, bj, At, Bt) do { __builtin_amdgcn_s_setprio(1); _Pragma("unroll") for (int m = 0; m < 4; ++m) _Pragma("unroll") for (int n = 0; n < 2; ++n) _Pragma("unroll") for (int k = 0; k < 2; ++k) \
;         acc[ai][bj][m][n] = __builtin_amdgcn_mfma_f32_16x16x32_bf16(Bt[n][k], At[m][k], acc[ai][bj][m][n], 0, 0, 0); __builtin_amdgcn_s_setprio(0); } while (0)
; #define PG8_WAIT_V(n) asm volatile("s_waitcnt vmcnt(" #n ")" ::: "memory")
; #define PG8_WAIT_L(n) asm volatile("s_waitcnt lgkmcnt(" #n ")" ::: "memory")
; #define PG8_BAR __builtin_amdgcn_s_barrier()
; #define PG8_SCHED __builtin_amdgcn_sched_barrier(0)
; template <class Epi, class Sched, bool ALIGN_EPI = false, bool SP2 = false, bool PAIR_ACC = false>
; __device__ __forceinline__ void gemm_phase(PG8_LAS unsigned char* lds, const Gemm g, const Sched& S, const Epi& E) {
;     ...
;             PG8_LDB(B0, 0, 0); PG8_LDB(B1, 0, 1); PG8_SCHED; PG8_LDA(At, 0, 0); PG8_STAGE(PG8_SA(1, 1), a1 + hstep, voffA);
;             PG8_WAIT_V(8); PG8_WAIT_L(0); PG8_BAR; PG8_MMA(0, 0, At, B0); PG8_MMA(0, 1, At, B1); PG8_BAR; PG8_SCHED;
;             PG8_LDA(At, 0, 1); PG8_STAGE(PG8_SB(0, 0), b2, voffB); PG8_STAGE(PG8_SB(0, 1), b2 + hstep, voffB); PG8_STAGE(PG8_SA(0, 0), a2, voffA);
;             PG8_WAIT_V(8); PG8_WAIT_L(0); PG8_BAR; PG8_MMA(1, 0, At, B0); PG8_MMA(1, 1, At, B1); PG8_BAR; PG8_SCHED;
	v_mfma_f32_16x16x32_bf16 v[54:57], v[74:77], v[162:165], 0
	v_mfma_f32_16x16x32_bf16 v[50:53], v[82:85], v[162:165], 0
	v_mfma_f32_16x16x32_bf16 v[38:41], v[74:77], v[210:213], 0
	v_mfma_f32_16x16x32_bf16 v[34:37], v[82:85], v[210:213], 0
	v_mfma_f32_16x16x32_bf16 v[22:25], v[74:77], v[218:221], 0
	v_mfma_f32_16x16x32_bf16 v[14:17], v[82:85], v[218:221], 0
	v_mfma_f32_16x16x32_bf16 v[18:21], v[74:77], v[226:229], 0
	v_mfma_f32_16x16x32_bf16 v[10:13], v[82:85], v[226:229], 0
	v_mfma_f32_16x16x32_bf16 v[54:57], v[78:81], v[166:169], v[54:57]
	v_mfma_f32_16x16x32_bf16 v[50:53], v[86:89], v[166:169], v[50:53]
	v_mfma_f32_16x16x32_bf16 v[38:41], v[78:81], v[214:217], v[38:41]
	v_mfma_f32_16x16x32_bf16 v[34:37], v[86:89], v[214:217], v[34:37]
	v_mfma_f32_16x16x32_bf16 v[22:25], v[78:81], v[222:225], v[22:25]
	v_mfma_f32_16x16x32_bf16 v[14:17], v[86:89], v[222:225], v[14:17]
	v_mfma_f32_16x16x32_bf16 v[18:21], v[78:81], v[230:233], v[18:21]
	v_mfma_f32_16x16x32_bf16 v[10:13], v[86:89], v[230:233], v[10:13]
	s_setprio 0
	s_setprio 1
	v_mfma_f32_16x16x32_bf16 v[62:65], v[90:93], v[162:165], 0
	v_mfma_f32_16x16x32_bf16 v[58:61], v[98:101], v[162:165], 0
	v_mfma_f32_16x16x32_bf16 v[46:49], v[90:93], v[210:213], 0
	v_mfma_f32_16x16x32_bf16 v[42:45], v[98:101], v[210:213], 0
	v_mfma_f32_16x16x32_bf16 v[30:33], v[90:93], v[218:221], 0
	v_mfma_f32_16x16x32_bf16 v[26:29], v[98:101], v[218:221], 0
	v_mfma_f32_16x16x32_bf16 v[6:9], v[90:93], v[226:229], 0
	v_mfma_f32_16x16x32_bf16 v[2:5], v[98:101], v[226:229], 0
	v_mfma_f32_16x16x32_bf16 v[62:65], v[94:97], v[166:169], v[62:65]
	v_mfma_f32_16x16x32_bf16 v[58:61], v[106:109], v[166:169], v[58:61]
	v_mfma_f32_16x16x32_bf16 v[46:49], v[94:97], v[214:217], v[46:49]
	v_mfma_f32_16x16x32_bf16 v[42:45], v[106:109], v[214:217], v[42:45]
	v_mfma_f32_16x16x32_bf16 v[30:33], v[94:97], v[222:225], v[30:33]
	v_mfma_f32_16x16x32_bf16 v[26:29], v[106:109], v[222:225], v[26:29]
	v_mfma_f32_16x16x32_bf16 v[6:9], v[94:97], v[230:233], v[6:9]
	v_mfma_f32_16x16x32_bf16 v[2:5], v[106:109], v[230:233], v[2:5]
	s_barrier
	s_setprio 0
	s_branch .Lpeel_mid_834
.LBB0_834:
	ds_read_b128 v[74:77], v197
	ds_read_b128 v[78:81], v197 offset:1024
	ds_read_b128 v[82:85], v197 offset:2048
	ds_read_b128 v[86:89], v197 offset:3072
	ds_read_b128 v[90:93], v198
	ds_read_b128 v[94:97], v198 offset:1024
	ds_read_b128 v[98:101], v198 offset:2048
	ds_read_b128 v[106:109], v198 offset:3072
	s_add_u32 s38, s10, 0xfffc0080
	s_addc_u32 s39, s11, -1
	s_cmp_eq_u32 s80, 12
	s_cselect_b32 s73, s40, s39
	s_cselect_b32 s72, s41, s38
	s_cselect_b32 s39, s63, s79
	s_cselect_b32 s38, s65, s78
	v_lshl_add_u64 v[170:171], s[10:11], 0, v[186:187]
	s_add_i32 m0, s36, 0xc000
	ds_read_b128 v[162:165], v199
	ds_read_b128 v[166:169], v199 offset:1024
	ds_read_b128 v[210:213], v199 offset:2048
	ds_read_b128 v[214:217], v199 offset:3072
	ds_read_b128 v[218:221], v199 offset:4096
	ds_read_b128 v[222:225], v199 offset:5120
	ds_read_b128 v[226:229], v199 offset:6144
	ds_read_b128 v[230:233], v199 offset:7168
	global_load_lds_dwordx4 v[170:171], off
	v_lshl_add_u64 v[170:171], s[10:11], 0, v[188:189]
	s_add_i32 m0, s36, 0xe000
	s_nop 0
	global_load_lds_dwordx4 v[170:171], off
	s_waitcnt vmcnt(8)
	s_waitcnt lgkmcnt(0)
	s_setprio 1
	s_barrier
	v_mfma_f32_16x16x32_bf16 v[150:153], v[74:77], v[162:165], v[150:153]
	v_mfma_f32_16x16x32_bf16 v[146:149], v[82:85], v[162:165], v[146:149]
	v_mfma_f32_16x16x32_bf16 v[134:137], v[74:77], v[210:213], v[134:137]
	v_mfma_f32_16x16x32_bf16 v[130:133], v[82:85], v[210:213], v[130:133]
	v_mfma_f32_16x16x32_bf16 v[118:121], v[74:77], v[218:221], v[118:121]
	v_mfma_f32_16x16x32_bf16 v[110:113], v[82:85], v[218:221], v[110:113]
	v_mfma_f32_16x16x32_bf16 v[114:117], v[74:77], v[226:229], v[114:117]
	v_mfma_f32_16x16x32_bf16 v[102:105], v[82:85], v[226:229], v[102:105]
	v_mfma_f32_16x16x32_bf16 v[150:153], v[78:81], v[166:169], v[150:153]
	v_mfma_f32_16x16x32_bf16 v[146:149], v[86:89], v[166:169], v[146:149]
	v_mfma_f32_16x16x32_bf16 v[134:137], v[78:81], v[214:217], v[134:137]
	v_mfma_f32_16x16x32_bf16 v[130:133], v[86:89], v[214:217], v[130:133]
	v_mfma_f32_16x16x32_bf16 v[118:121], v[78:81], v[222:225], v[118:121]
	v_mfma_f32_16x16x32_bf16 v[110:113], v[86:89], v[222:225], v[110:113]
	v_mfma_f32_16x16x32_bf16 v[114:117], v[78:81], v[230:233], v[114:117]
	v_mfma_f32_16x16x32_bf16 v[102:105], v[86:89], v[230:233], v[102:105]
	s_setprio 0
	s_setprio 1
	v_mfma_f32_16x16x32_bf16 v[158:161], v[90:93], v[162:165], v[158:161]
	v_mfma_f32_16x16x32_bf16 v[154:157], v[98:101], v[162:165], v[154:157]
	v_mfma_f32_16x16x32_bf16 v[142:145], v[90:93], v[210:213], v[142:145]
	v_mfma_f32_16x16x32_bf16 v[138:141], v[98:101], v[210:213], v[138:141]
	v_mfma_f32_16x16x32_bf16 v[126:129], v[90:93], v[218:221], v[126:129]
	v_mfma_f32_16x16x32_bf16 v[122:125], v[98:101], v[218:221], v[122:125]
	v_mfma_f32_16x16x32_bf16 v[70:73], v[90:93], v[226:229], v[70:73]
	v_mfma_f32_16x16x32_bf16 v[66:69], v[98:101], v[226:229], v[66:69]
	v_mfma_f32_16x16x32_bf16 v[158:161], v[94:97], v[166:169], v[158:161]
	v_mfma_f32_16x16x32_bf16 v[154:157], v[106:109], v[166:169], v[154:157]
	v_mfma_f32_16x16x32_bf16 v[142:145], v[94:97], v[214:217], v[142:145]
	v_mfma_f32_16x16x32_bf16 v[138:141], v[106:109], v[214:217], v[138:141]
	v_mfma_f32_16x16x32_bf16 v[126:129], v[94:97], v[222:225], v[126:129]
	v_mfma_f32_16x16x32_bf16 v[122:125], v[106:109], v[222:225], v[122:125]
	v_mfma_f32_16x16x32_bf16 v[70:73], v[94:97], v[230:233], v[70:73]
	v_mfma_f32_16x16x32_bf16 v[66:69], v[106:109], v[230:233], v[66:69]
	s_barrier
; #define PG8_STAGE(bufoff, gbase, voff) do { _Pragma("unroll") for (int _i = 0; _i < 2; ++_i) \
;         __builtin_amdgcn_global_load_lds((const unsigned*)((const char*)(gbase) + (voff)[_i]), (PG8_LAS unsigned*)(lds + (bufoff) + ldsw + _i * 8192), 16, 0, 0); } while (0)
; #define PG8_LDA(dst, b, h) do { _Pragma("unroll") for (int m = 0; m < 4; ++m) _Pragma("unroll") for (int k = 0; k < 2; ++k) dst[m][k] = *(const PG8_LAS bf16x8*)(lds + PG8_SA(b, h) + aoff + m * 2048 + k * 1024); } while (0)
; #define PG8_LDB(dst, b, h) do { _Pragma("unroll") for (int n = 0; n < 2; ++n) _Pragma("unroll") for (int k = 0; k < 2; ++k) dst[n][k] = *(const PG8_LAS bf16x8*)(lds + PG8_SB(b, h) + boff + n * 2048 + k * 1024); } while (0)
; #define PG8_MMA(ai, bj, At, Bt) do { __builtin_amdgcn_s_setprio(1); _Pragma("unroll") for (int m = 0; m < 4; ++m) _Pragma("unroll") for (int n = 0; n < 2; ++n) _Pragma("unroll") for (int k = 0; k < 2; ++k) \
;         acc[ai][bj][m][n] = __builtin_amdgcn_mfma_f32_16x16x32_bf16(Bt[n][k], At[m][k], acc[ai][bj][m][n], 0, 0, 0); __builtin_amdgcn_s_setprio(0); } while (0)
; #define PG8_WAIT_V(n) asm volatile("s_waitcnt vmcnt(" #n ")" ::: "memory")
; #define PG8_WAIT_L(n) asm volatile("s_waitcnt lgkmcnt(" #n ")" ::: "memory")
; #define PG8_BAR __builtin_amdgcn_s_barrier()
; #define PG8_SCHED __builtin_amdgcn_sched_barrier(0)
; template <class Epi, class Sched, bool ALIGN_EPI = false, bool SP2 = false, bool PAIR_ACC = false>
; __device__ __forceinline__ void gemm_phase(PG8_LAS unsigned char* lds, const Gemm g, const Sched& S, const Epi& E) {
;     ...
;             PG8_LDA(At, 0, 1); PG8_STAGE(PG8_SB(0, 0), b2, voffB); PG8_STAGE(PG8_SB(0, 1), b2 + hstep, voffB); PG8_STAGE(PG8_SA(0, 0), a2, voffA);
;             PG8_WAIT_V(8); PG8_WAIT_L(0); PG8_BAR; PG8_MMA(1, 0, At, B0); PG8_MMA(1, 1, At, B1); PG8_BAR; PG8_SCHED;
;             PG8_LDB(B0, 1, 0); PG8_LDB(B1, 1, 1); PG8_SCHED; PG8_LDA(At, 1, 0); PG8_STAGE(PG8_SA(0, 1), a2 + hstep, voffA);
	s_setprio 0
	s_add_i32 s81, s61, s25
	v_lshl_add_u64 v[170:171], s[38:39], 0, v[178:179]
	s_mov_b32 m0, s81
	ds_read_b128 v[162:165], v199 offset:16384
	ds_read_b128 v[166:169], v199 offset:17408
	ds_read_b128 v[210:213], v199 offset:18432
	ds_read_b128 v[214:217], v199 offset:19456
	ds_read_b128 v[218:221], v199 offset:20480
	ds_read_b128 v[222:225], v199 offset:21504
	ds_read_b128 v[226:229], v199 offset:22528
	ds_read_b128 v[230:233], v199 offset:23552
	global_load_lds_dwordx4 v[170:171], off
	s_add_i32 m0, s81, 0x2000
	s_add_u32 s82, s38, 0x40000
	v_lshl_add_u64 v[194:195], s[38:39], 0, v[174:175]
	s_addc_u32 s83, s39, 0
	s_add_i32 s81, s74, s25
	global_load_lds_dwordx4 v[194:195], off
	v_lshl_add_u64 v[234:235], s[82:83], 0, v[178:179]
	s_mov_b32 m0, s81
	v_lshl_add_u64 v[236:237], s[72:73], 0, v[176:177]
	global_load_lds_dwordx4 v[234:235], off
	v_lshl_add_u64 v[234:235], s[82:83], 0, v[174:175]
	s_add_i32 m0, s81, 0x2000
	s_nop 0
	global_load_lds_dwordx4 v[234:235], off
	v_lshl_add_u64 v[234:235], s[72:73], 0, v[180:181]
	s_mov_b32 m0, s36
	s_nop 0
	global_load_lds_dwordx4 v[234:235], off
	s_mov_b32 m0, s37
	s_nop 0
	global_load_lds_dwordx4 v[236:237], off
	s_waitcnt vmcnt(8)
	s_waitcnt lgkmcnt(0)
	s_setprio 1
	s_barrier
	v_mfma_f32_16x16x32_bf16 v[54:57], v[74:77], v[162:165], v[54:57]
	v_mfma_f32_16x16x32_bf16 v[50:53], v[82:85], v[162:165], v[50:53]
	v_mfma_f32_16x16x32_bf16 v[38:41], v[74:77], v[210:213], v[38:41]
	v_mfma_f32_16x16x32_bf16 v[34:37], v[82:85], v[210:213], v[34:37]
	v_mfma_f32_16x16x32_bf16 v[22:25], v[74:77], v[218:221], v[22:25]
	v_mfma_f32_16x16x32_bf16 v[14:17], v[82:85], v[218:221], v[14:17]
	v_mfma_f32_16x16x32_bf16 v[18:21], v[74:77], v[226:229], v[18:21]
	v_mfma_f32_16x16x32_bf16 v[10:13], v[82:85], v[226:229], v[10:13]
	v_mfma_f32_16x16x32_bf16 v[54:57], v[78:81], v[166:169], v[54:57]
	v_mfma_f32_16x16x32_bf16 v[50:53], v[86:89], v[166:169], v[50:53]
	v_mfma_f32_16x16x32_bf16 v[38:41], v[78:81], v[214:217], v[38:41]
	v_mfma_f32_16x16x32_bf16 v[34:37], v[86:89], v[214:217], v[34:37]
	v_mfma_f32_16x16x32_bf16 v[22:25], v[78:81], v[222:225], v[22:25]
	v_mfma_f32_16x16x32_bf16 v[14:17], v[86:89], v[222:225], v[14:17]
	v_mfma_f32_16x16x32_bf16 v[18:21], v[78:81], v[230:233], v[18:21]
	v_mfma_f32_16x16x32_bf16 v[10:13], v[86:89], v[230:233], v[10:13]
	s_setprio 0
	s_setprio 1
	v_mfma_f32_16x16x32_bf16 v[62:65], v[90:93], v[162:165], v[62:65]
	v_mfma_f32_16x16x32_bf16 v[58:61], v[98:101], v[162:165], v[58:61]
	v_mfma_f32_16x16x32_bf16 v[46:49], v[90:93], v[210:213], v[46:49]
	v_mfma_f32_16x16x32_bf16 v[42:45], v[98:101], v[210:213], v[42:45]
	v_mfma_f32_16x16x32_bf16 v[30:33], v[90:93], v[218:221], v[30:33]
	v_mfma_f32_16x16x32_bf16 v[26:29], v[98:101], v[218:221], v[26:29]
	v_mfma_f32_16x16x32_bf16 v[6:9], v[90:93], v[226:229], v[6:9]
	v_mfma_f32_16x16x32_bf16 v[2:5], v[98:101], v[226:229], v[2:5]
	v_mfma_f32_16x16x32_bf16 v[62:65], v[94:97], v[166:169], v[62:65]
	v_mfma_f32_16x16x32_bf16 v[58:61], v[106:109], v[166:169], v[58:61]
	v_mfma_f32_16x16x32_bf16 v[46:49], v[94:97], v[214:217], v[46:49]
	v_mfma_f32_16x16x32_bf16 v[42:45], v[106:109], v[214:217], v[42:45]
	v_mfma_f32_16x16x32_bf16 v[30:33], v[94:97], v[222:225], v[30:33]
	v_mfma_f32_16x16x32_bf16 v[26:29], v[106:109], v[222:225], v[26:29]
	v_mfma_f32_16x16x32_bf16 v[6:9], v[94:97], v[230:233], v[6:9]
	v_mfma_f32_16x16x32_bf16 v[2:5], v[106:109], v[230:233], v[2:5]
	s_barrier
	s_setprio 0
.Lpeel_mid_834:
	s_add_i32 s81, 0, 0x18000
	s_add_i32 s82, 0, 0x1c000
	v_add_u32_e32 v86, s81, v183
	v_add_u32_e32 v106, s82, v183
	ds_read_b128 v[74:77], v86
	ds_read_b128 v[78:81], v86 offset:1024
	ds_read_b128 v[82:85], v86 offset:2048
	ds_read_b128 v[86:89], v86 offset:3072
	ds_read_b128 v[90:93], v106
	ds_read_b128 v[94:97], v106 offset:1024
	ds_read_b128 v[98:101], v106 offset:2048
	ds_read_b128 v[106:109], v106 offset:3072
	s_add_u32 s72, s72, 0x40000
	s_addc_u32 s73, s73, 0
	s_mov_b32 m0, s42
	v_lshl_add_u64 v[238:239], s[72:73], 0, v[180:181]
	ds_read_b128 v[162:165], v199 offset:32768
	ds_read_b128 v[166:169], v199 offset:33792
	ds_read_b128 v[210:213], v199 offset:34816
	ds_read_b128 v[214:217], v199 offset:35840
	ds_read_b128 v[218:221], v199 offset:36864
	ds_read_b128 v[222:225], v199 offset:37888
	ds_read_b128 v[226:229], v199 offset:38912
	ds_read_b128 v[230:233], v199 offset:39936
	global_load_lds_dwordx4 v[238:239], off
	v_lshl_add_u64 v[238:239], s[72:73], 0, v[176:177]
	s_mov_b32 m0, s43
	s_nop 0
	global_load_lds_dwordx4 v[238:239], off
	s_waitcnt vmcnt(8)
	s_waitcnt lgkmcnt(0)
	s_setprio 1
	s_barrier
; #define PG8_STAGE(bufoff, gbase, voff) do { _Pragma("unroll") for (int _i = 0; _i < 2; ++_i) \
;         __builtin_amdgcn_global_load_lds((const unsigned*)((const char*)(gbase) + (voff)[_i]), (PG8_LAS unsigned*)(lds + (bufoff) + ldsw + _i * 8192), 16, 0, 0); } while (0)
; #define PG8_LDA(dst, b, h) do { _Pragma("unroll") for (int m = 0; m < 4; ++m) _Pragma("unroll") for (int k = 0; k < 2; ++k) dst[m][k] = *(const PG8_LAS bf16x8*)(lds + PG8_SA(b, h) + aoff + m * 2048 + k * 1024); } while (0)
; #define PG8_MMA(ai, bj, At, Bt) do { __builtin_amdgcn_s_setprio(1); _Pragma("unroll") for (int m = 0; m < 4; ++m) _Pragma("unroll") for (int n = 0; n < 2; ++n) _Pragma("unroll") for (int k = 0; k < 2; ++k) \
;         acc[ai][bj][m][n] = __builtin_amdgcn_mfma_f32_16x16x32_bf16(Bt[n][k], At[m][k], acc[ai][bj][m][n], 0, 0, 0); __builtin_amdgcn_s_setprio(0); } while (0)
; #define PG8_WAIT_V(n) asm volatile("s_waitcnt vmcnt(" #n ")" ::: "memory")
; #define PG8_WAIT_L(n) asm volatile("s_waitcnt lgkmcnt(" #n ")" ::: "memory")
; #define PG8_BAR __builtin_amdgcn_s_barrier()
; #define PG8_SCHED __builtin_amdgcn_sched_barrier(0)
; template <class Epi, class Sched, bool ALIGN_EPI = false, bool SP2 = false, bool PAIR_ACC = false>
; __device__ __forceinline__ void gemm_phase(PG8_LAS unsigned char* lds, const Gemm g, const Sched& S, const Epi& E) {
;     ...
;             PG8_WAIT_V(8); PG8_WAIT_L(0); PG8_BAR; PG8_MMA(0, 0, At, B0); PG8_MMA(0, 1, At, B1); PG8_BAR; PG8_SCHED;
;             PG8_LDA(At, 1, 1); PG8_STAGE(PG8_SB(1, 0), b3, voffB); PG8_STAGE(PG8_SB(1, 1), b3 + hstep, voffB); PG8_STAGE(PG8_SA(1, 0), a3, voffA);
;             PG8_WAIT_V(8); PG8_WAIT_L(0); PG8_BAR; PG8_MMA(1, 0, At, B0); PG8_MMA(1, 1, At, B1); PG8_BAR; PG8_SCHED;
;     ...
;         if constexpr (ALIGN_EPI) { if (wr == 0) PG8_BAR; }
	v_mfma_f32_16x16x32_bf16 v[150:153], v[74:77], v[162:165], v[150:153]
	v_mfma_f32_16x16x32_bf16 v[146:149], v[82:85], v[162:165], v[146:149]
	v_mfma_f32_16x16x32_bf16 v[134:137], v[74:77], v[210:213], v[134:137]
	v_mfma_f32_16x16x32_bf16 v[130:133], v[82:85], v[210:213], v[130:133]
	v_mfma_f32_16x16x32_bf16 v[118:121], v[74:77], v[218:221], v[118:121]
	v_mfma_f32_16x16x32_bf16 v[110:113], v[82:85], v[218:221], v[110:113]
	v_mfma_f32_16x16x32_bf16 v[114:117], v[74:77], v[226:229], v[114:117]
	v_mfma_f32_16x16x32_bf16 v[102:105], v[82:85], v[226:229], v[102:105]
	v_mfma_f32_16x16x32_bf16 v[150:153], v[78:81], v[166:169], v[150:153]
	v_mfma_f32_16x16x32_bf16 v[146:149], v[86:89], v[166:169], v[146:149]
	v_mfma_f32_16x16x32_bf16 v[134:137], v[78:81], v[214:217], v[134:137]
	v_mfma_f32_16x16x32_bf16 v[130:133], v[86:89], v[214:217], v[130:133]
	v_mfma_f32_16x16x32_bf16 v[118:121], v[78:81], v[222:225], v[118:121]
	v_mfma_f32_16x16x32_bf16 v[110:113], v[86:89], v[222:225], v[110:113]
	v_mfma_f32_16x16x32_bf16 v[114:117], v[78:81], v[230:233], v[114:117]
	v_mfma_f32_16x16x32_bf16 v[102:105], v[86:89], v[230:233], v[102:105]
	s_setprio 0
	s_setprio 1
	v_mfma_f32_16x16x32_bf16 v[158:161], v[90:93], v[162:165], v[158:161]
	v_mfma_f32_16x16x32_bf16 v[154:157], v[98:101], v[162:165], v[154:157]
	v_mfma_f32_16x16x32_bf16 v[142:145], v[90:93], v[210:213], v[142:145]
	v_mfma_f32_16x16x32_bf16 v[138:141], v[98:101], v[210:213], v[138:141]
	v_mfma_f32_16x16x32_bf16 v[126:129], v[90:93], v[218:221], v[126:129]
	v_mfma_f32_16x16x32_bf16 v[122:125], v[98:101], v[218:221], v[122:125]
	v_mfma_f32_16x16x32_bf16 v[70:73], v[90:93], v[226:229], v[70:73]
	v_mfma_f32_16x16x32_bf16 v[66:69], v[98:101], v[226:229], v[66:69]
	v_mfma_f32_16x16x32_bf16 v[158:161], v[94:97], v[166:169], v[158:161]
	v_mfma_f32_16x16x32_bf16 v[154:157], v[106:109], v[166:169], v[154:157]
	v_mfma_f32_16x16x32_bf16 v[142:145], v[94:97], v[214:217], v[142:145]
	v_mfma_f32_16x16x32_bf16 v[138:141], v[106:109], v[214:217], v[138:141]
	v_mfma_f32_16x16x32_bf16 v[126:129], v[94:97], v[222:225], v[126:129]
	v_mfma_f32_16x16x32_bf16 v[122:125], v[106:109], v[222:225], v[122:125]
	v_mfma_f32_16x16x32_bf16 v[70:73], v[94:97], v[230:233], v[70:73]
	v_mfma_f32_16x16x32_bf16 v[66:69], v[106:109], v[230:233], v[66:69]
	s_barrier
	s_setprio 0
	s_add_i32 s72, s81, s25
	v_lshl_add_u64 v[170:171], v[170:171], 0, s[48:49]
	s_mov_b32 m0, s72
	ds_read_b128 v[162:165], v199 offset:49152
	ds_read_b128 v[166:169], v199 offset:50176
	ds_read_b128 v[210:213], v199 offset:51200
	ds_read_b128 v[214:217], v199 offset:52224
	ds_read_b128 v[218:221], v199 offset:53248
	ds_read_b128 v[222:225], v199 offset:54272
	ds_read_b128 v[226:229], v199 offset:55296
	ds_read_b128 v[230:233], v199 offset:56320
	global_load_lds_dwordx4 v[170:171], off
	s_add_i32 m0, s72, 0x2000
	s_add_u32 s38, s38, 0x40080
	v_lshl_add_u64 v[170:171], v[194:195], 0, s[48:49]
	s_addc_u32 s39, s39, 0
	s_add_i32 s72, s82, s25
	global_load_lds_dwordx4 v[170:171], off
	v_lshl_add_u64 v[170:171], s[38:39], 0, v[178:179]
	s_mov_b32 m0, s72
	s_nop 0
	global_load_lds_dwordx4 v[170:171], off
	v_lshl_add_u64 v[170:171], s[38:39], 0, v[174:175]
	s_add_i32 m0, s72, 0x2000
	s_nop 0
	global_load_lds_dwordx4 v[170:171], off
	v_lshl_add_u64 v[170:171], v[234:235], 0, s[48:49]
	s_mov_b32 m0, s45
	s_nop 0
	global_load_lds_dwordx4 v[170:171], off
	v_lshl_add_u64 v[170:171], v[236:237], 0, s[48:49]
	s_mov_b32 m0, s46
	s_nop 0
	global_load_lds_dwordx4 v[170:171], off
	s_waitcnt vmcnt(8)
	s_waitcnt lgkmcnt(0)
	s_setprio 1
	s_barrier
	v_mfma_f32_16x16x32_bf16 v[54:57], v[74:77], v[162:165], v[54:57]
	v_mfma_f32_16x16x32_bf16 v[50:53], v[82:85], v[162:165], v[50:53]
	v_mfma_f32_16x16x32_bf16 v[38:41], v[74:77], v[210:213], v[38:41]
	v_mfma_f32_16x16x32_bf16 v[34:37], v[82:85], v[210:213], v[34:37]
	v_mfma_f32_16x16x32_bf16 v[22:25], v[74:77], v[218:221], v[22:25]
	v_mfma_f32_16x16x32_bf16 v[14:17], v[82:85], v[218:221], v[14:17]
	v_mfma_f32_16x16x32_bf16 v[18:21], v[74:77], v[226:229], v[18:21]
	v_mfma_f32_16x16x32_bf16 v[10:13], v[82:85], v[226:229], v[10:13]
	v_mfma_f32_16x16x32_bf16 v[54:57], v[78:81], v[166:169], v[54:57]
	v_mfma_f32_16x16x32_bf16 v[50:53], v[86:89], v[166:169], v[50:53]
	v_mfma_f32_16x16x32_bf16 v[38:41], v[78:81], v[214:217], v[38:41]
	v_mfma_f32_16x16x32_bf16 v[34:37], v[86:89], v[214:217], v[34:37]
	v_mfma_f32_16x16x32_bf16 v[22:25], v[78:81], v[222:225], v[22:25]
	v_mfma_f32_16x16x32_bf16 v[14:17], v[86:89], v[222:225], v[14:17]
	v_mfma_f32_16x16x32_bf16 v[18:21], v[78:81], v[230:233], v[18:21]
	v_mfma_f32_16x16x32_bf16 v[10:13], v[86:89], v[230:233], v[10:13]
	s_setprio 0
	s_setprio 1
	v_mfma_f32_16x16x32_bf16 v[62:65], v[90:93], v[162:165], v[62:65]
	v_mfma_f32_16x16x32_bf16 v[58:61], v[98:101], v[162:165], v[58:61]
	v_mfma_f32_16x16x32_bf16 v[46:49], v[90:93], v[210:213], v[46:49]
	v_mfma_f32_16x16x32_bf16 v[42:45], v[98:101], v[210:213], v[42:45]
	v_mfma_f32_16x16x32_bf16 v[30:33], v[90:93], v[218:221], v[30:33]
	v_mfma_f32_16x16x32_bf16 v[26:29], v[98:101], v[218:221], v[26:29]
	v_mfma_f32_16x16x32_bf16 v[6:9], v[90:93], v[226:229], v[6:9]
	v_mfma_f32_16x16x32_bf16 v[2:5], v[98:101], v[226:229], v[2:5]
	v_mfma_f32_16x16x32_bf16 v[62:65], v[94:97], v[166:169], v[62:65]
	v_mfma_f32_16x16x32_bf16 v[58:61], v[106:109], v[166:169], v[58:61]
	v_mfma_f32_16x16x32_bf16 v[46:49], v[94:97], v[214:217], v[46:49]
	v_mfma_f32_16x16x32_bf16 v[42:45], v[106:109], v[214:217], v[42:45]
	v_mfma_f32_16x16x32_bf16 v[30:33], v[94:97], v[222:225], v[30:33]
	v_mfma_f32_16x16x32_bf16 v[26:29], v[106:109], v[222:225], v[26:29]
	v_mfma_f32_16x16x32_bf16 v[6:9], v[94:97], v[230:233], v[6:9]
	v_mfma_f32_16x16x32_bf16 v[2:5], v[106:109], v[230:233], v[2:5]
	s_barrier
	s_setprio 0
	s_add_i32 s80, s80, 2
	s_add_u32 s10, s10, 0x100
	s_addc_u32 s11, s11, 0
	s_add_u32 s78, s78, 0x100
	s_addc_u32 s79, s79, 0
	s_cmp_gt_u32 s80, 13
	s_cbranch_scc0 .LBB0_834
	s_and_b64 vcc, exec, s[50:51]
	s_cbranch_vccz .LBB0_837
	s_barrier

; #define PG8_STAGE(bufoff, gbase, voff) do { _Pragma("unroll") for (int _i = 0; _i < 2; ++_i) \
;         __builtin_amdgcn_global_load_lds((const unsigned*)((const char*)(gbase) + (voff)[_i]), (PG8_LAS unsigned*)(lds + (bufoff) + ldsw + _i * 8192), 16, 0, 0); } while (0)
; #define PG8_LDA(dst, b, h) do { _Pragma("unroll") for (int m = 0; m < 4; ++m) _Pragma("unroll") for (int k = 0; k < 2; ++k) dst[m][k] = *(const PG8_LAS bf16x8*)(lds + PG8_SA(b, h) + aoff + m * 2048 + k * 1024); } while (0)
; #define PG8_LDB(dst, b, h) do { _Pragma("unroll") for (int n = 0; n < 2; ++n) _Pragma("unroll") for (int k = 0; k < 2; ++k) dst[n][k] = *(const PG8_LAS bf16x8*)(lds + PG8_SB(b, h) + boff + n * 2048 + k * 1024); } while (0)
; #define PG8_MMA(ai, bj, At, Bt) do { __builtin_amdgcn_s_setprio(1); _Pragma("unroll") for (int m = 0; m < 4; ++m) _Pragma("unroll") for (int n = 0; n < 2; ++n) _Pragma("unroll") for (int k = 0; k < 2; ++k) \
;         acc[ai][bj][m][n] = __builtin_amdgcn_mfma_f32_16x16x32_bf16(Bt[n][k], At[m][k], acc[ai][bj][m][n], 0, 0, 0); __builtin_amdgcn_s_setprio(0); } while (0)
; #define PG8_WAIT_V(n) asm volatile("s_waitcnt vmcnt(" #n ")" ::: "memory")
; #define PG8_WAIT_L(n) asm volatile("s_waitcnt lgkmcnt(" #n ")" ::: "memory")
; template <class Epi, class Sched, bool ALIGN_EPI = false, bool SP2 = false, bool PAIR_ACC = false>
; __device__ __forceinline__ void gemm_phase(PG8_LAS unsigned char* lds, const Gemm g, const Sched& S, const Epi& E) {
;     ...
;             const bool last = (t == nt - 2);
;             const char* a1 = cA + (size_t)(t + 1) * kstep;
;             const char* a2 = last ? nA : cA + (size_t)(t + 2) * kstep; const char* b2 = last ? nB : cB + (size_t)(t + 2) * kstep;
;             const char* a3 = a2 + kstep; const char* b3 = b2 + kstep;
;             if (last && has_next) S.a_ready(nxt);
;             if constexpr (SP2) {
;             PG8_LDB(B0, 0, 0); PG8_LDB(B1, 0, 1); PG8_SCHED; PG8_LDA(At, 0, 0); PG8_STAGE(PG8_SA(1, 1), a1 + hstep, voffA);
;             PG8_WAIT_V(8); PG8_WAIT_L(0); PG8_BAR; PG8_MMA(0, 0, At, B0); PG8_MMA(0, 1, At, B1); PG8_BAR; PG8_SCHED;
;             PG8_LDA(At, 0, 1); PG8_STAGE(PG8_SB(0, 0), b2, voffB); PG8_STAGE(PG8_SB(0, 1), b2 + hstep, voffB); PG8_STAGE(PG8_SA(0, 0), a2, voffA);
;             PG8_WAIT_V(8); PG8_WAIT_L(0); PG8_BAR; PG8_MMA(1, 0, At, B0); PG8_MMA(1, 1, At, B1); PG8_BAR; PG8_SCHED;
.LBB0_937:
	v_add_u32_e32 v164, s46, v150
	ds_read_b128 v[152:155], v164
	ds_read_b128 v[156:159], v164 offset:1024
	ds_read_b128 v[160:163], v164 offset:2048
	ds_read_b128 v[174:177], v164 offset:3072
	v_add_u32_e32 v164, s47, v150
	s_add_u32 s38, s28, s50
	ds_read_b128 v[178:181], v164
	ds_read_b128 v[182:185], v164 offset:1024
	ds_read_b128 v[186:189], v164 offset:2048
	ds_read_b128 v[190:193], v164 offset:3072
	s_addc_u32 s39, s29, s51
	s_add_u32 s38, s38, 0x100
	s_addc_u32 s39, s39, 0
	s_add_u32 s60, s57, s50
	s_addc_u32 s61, s58, s51
	s_cmpk_eq_i32 s50, 0x1500
	s_cselect_b32 s53, s49, s39
	s_cselect_b32 s52, s48, s38
	s_cselect_b32 s39, s11, s61
	s_cselect_b32 s38, s10, s60
	v_lshl_add_u64 v[164:165], v[146:147], 0, s[50:51]
	s_add_i32 m0, s37, 0xc000
	ds_read_b128 v[194:197], v151
	ds_read_b128 v[206:209], v151 offset:1024
	ds_read_b128 v[210:213], v151 offset:2048
	ds_read_b128 v[214:217], v151 offset:3072
	ds_read_b128 v[218:221], v151 offset:4096
	ds_read_b128 v[222:225], v151 offset:5120
	ds_read_b128 v[226:229], v151 offset:6144
	ds_read_b128 v[230:233], v151 offset:7168
	global_load_lds_dwordx4 v[164:165], off
	v_lshl_add_u64 v[164:165], v[148:149], 0, s[50:51]
	s_add_i32 m0, s37, 0xe000
	s_nop 0
	global_load_lds_dwordx4 v[164:165], off
	s_waitcnt vmcnt(8)
	s_waitcnt lgkmcnt(0)
	s_setprio 1
	s_barrier
	v_mfma_f32_16x16x32_bf16 v[58:61], v[152:155], v[194:197], v[58:61]
	v_mfma_f32_16x16x32_bf16 v[62:65], v[160:163], v[194:197], v[62:65]
	v_mfma_f32_16x16x32_bf16 v[82:85], v[152:155], v[210:213], v[82:85]
	v_mfma_f32_16x16x32_bf16 v[74:77], v[160:163], v[210:213], v[74:77]
	v_mfma_f32_16x16x32_bf16 v[98:101], v[152:155], v[218:221], v[98:101]
	v_mfma_f32_16x16x32_bf16 v[90:93], v[160:163], v[218:221], v[90:93]
	v_mfma_f32_16x16x32_bf16 v[114:117], v[152:155], v[226:229], v[114:117]
	v_mfma_f32_16x16x32_bf16 v[110:113], v[160:163], v[226:229], v[110:113]
	v_mfma_f32_16x16x32_bf16 v[58:61], v[156:159], v[206:209], v[58:61]
	v_mfma_f32_16x16x32_bf16 v[62:65], v[174:177], v[206:209], v[62:65]
	v_mfma_f32_16x16x32_bf16 v[82:85], v[156:159], v[214:217], v[82:85]
	v_mfma_f32_16x16x32_bf16 v[74:77], v[174:177], v[214:217], v[74:77]
	v_mfma_f32_16x16x32_bf16 v[98:101], v[156:159], v[222:225], v[98:101]
	v_mfma_f32_16x16x32_bf16 v[90:93], v[174:177], v[222:225], v[90:93]
	v_mfma_f32_16x16x32_bf16 v[114:117], v[156:159], v[230:233], v[114:117]
	v_mfma_f32_16x16x32_bf16 v[110:113], v[174:177], v[230:233], v[110:113]
	s_setprio 0
	s_setprio 1
	v_mfma_f32_16x16x32_bf16 v[54:57], v[178:181], v[194:197], v[54:57]
	v_mfma_f32_16x16x32_bf16 v[46:49], v[186:189], v[194:197], v[46:49]
	v_mfma_f32_16x16x32_bf16 v[50:53], v[178:181], v[210:213], v[50:53]
	v_mfma_f32_16x16x32_bf16 v[42:45], v[186:189], v[210:213], v[42:45]
	v_mfma_f32_16x16x32_bf16 v[78:81], v[178:181], v[218:221], v[78:81]
	v_mfma_f32_16x16x32_bf16 v[70:73], v[186:189], v[218:221], v[70:73]
	v_mfma_f32_16x16x32_bf16 v[102:105], v[178:181], v[226:229], v[102:105]
	v_mfma_f32_16x16x32_bf16 v[94:97], v[186:189], v[226:229], v[94:97]
	v_mfma_f32_16x16x32_bf16 v[54:57], v[182:185], v[206:209], v[54:57]
	v_mfma_f32_16x16x32_bf16 v[46:49], v[190:193], v[206:209], v[46:49]
	v_mfma_f32_16x16x32_bf16 v[50:53], v[182:185], v[214:217], v[50:53]
	v_mfma_f32_16x16x32_bf16 v[42:45], v[190:193], v[214:217], v[42:45]
	v_mfma_f32_16x16x32_bf16 v[78:81], v[182:185], v[222:225], v[78:81]
	v_mfma_f32_16x16x32_bf16 v[70:73], v[190:193], v[222:225], v[70:73]
	v_mfma_f32_16x16x32_bf16 v[102:105], v[182:185], v[230:233], v[102:105]
	v_mfma_f32_16x16x32_bf16 v[94:97], v[190:193], v[230:233], v[94:97]
	s_barrier
	s_setprio 0
	s_add_i32 s60, s46, s36
	v_lshl_add_u64 v[164:165], s[38:39], 0, v[132:133]
	s_mov_b32 m0, s60
	ds_read_b128 v[194:197], v151 offset:16384
	ds_read_b128 v[206:209], v151 offset:17408
	ds_read_b128 v[210:213], v151 offset:18432
	ds_read_b128 v[214:217], v151 offset:19456
	ds_read_b128 v[218:221], v151 offset:20480
	ds_read_b128 v[222:225], v151 offset:21504
	ds_read_b128 v[226:229], v151 offset:22528
	ds_read_b128 v[230:233], v151 offset:23552
	global_load_lds_dwordx4 v[164:165], off
	s_add_i32 m0, s60, 0x2000
	s_add_u32 s60, s38, 0xb0000
	v_lshl_add_u64 v[170:171], s[38:39], 0, v[136:137]
	s_addc_u32 s61, s39, 0
	s_add_i32 s62, s47, s36
	global_load_lds_dwordx4 v[170:171], off
	v_lshl_add_u64 v[198:199], s[60:61], 0, v[132:133]
	s_mov_b32 m0, s62
	v_lshl_add_u64 v[234:235], s[52:53], 0, v[134:135]
	global_load_lds_dwordx4 v[198:199], off
	v_lshl_add_u64 v[198:199], s[60:61], 0, v[136:137]
	s_add_i32 m0, s62, 0x2000
	s_nop 0
	global_load_lds_dwordx4 v[198:199], off
	v_lshl_add_u64 v[198:199], s[52:53], 0, v[130:131]
	s_mov_b32 m0, s37
	s_nop 0
	global_load_lds_dwordx4 v[198:199], off
	s_mov_b32 m0, s40
	s_nop 0
	global_load_lds_dwordx4 v[234:235], off
	s_waitcnt vmcnt(8)
	s_waitcnt lgkmcnt(0)
	s_setprio 1
	s_barrier
; #define PG8_STAGE(bufoff, gbase, voff) do { _Pragma("unroll") for (int _i = 0; _i < 2; ++_i) \
;         __builtin_amdgcn_global_load_lds((const unsigned*)((const char*)(gbase) + (voff)[_i]), (PG8_LAS unsigned*)(lds + (bufoff) + ldsw + _i * 8192), 16, 0, 0); } while (0)
; #define PG8_LDA(dst, b, h) do { _Pragma("unroll") for (int m = 0; m < 4; ++m) _Pragma("unroll") for (int k = 0; k < 2; ++k) dst[m][k] = *(const PG8_LAS bf16x8*)(lds + PG8_SA(b, h) + aoff + m * 2048 + k * 1024); } while (0)
; #define PG8_LDB(dst, b, h) do { _Pragma("unroll") for (int n = 0; n < 2; ++n) _Pragma("unroll") for (int k = 0; k < 2; ++k) dst[n][k] = *(const PG8_LAS bf16x8*)(lds + PG8_SB(b, h) + boff + n * 2048 + k * 1024); } while (0)
; #define PG8_MMA(ai, bj, At, Bt) do { __builtin_amdgcn_s_setprio(1); _Pragma("unroll") for (int m = 0; m < 4; ++m) _Pragma("unroll") for (int n = 0; n < 2; ++n) _Pragma("unroll") for (int k = 0; k < 2; ++k) \
;         acc[ai][bj][m][n] = __builtin_amdgcn_mfma_f32_16x16x32_bf16(Bt[n][k], At[m][k], acc[ai][bj][m][n], 0, 0, 0); __builtin_amdgcn_s_setprio(0); } while (0)
; #define PG8_WAIT_V(n) asm volatile("s_waitcnt vmcnt(" #n ")" ::: "memory")
; #define PG8_WAIT_L(n) asm volatile("s_waitcnt lgkmcnt(" #n ")" ::: "memory")
; #define PG8_BAR __builtin_amdgcn_s_barrier()
; #define PG8_SCHED __builtin_amdgcn_sched_barrier(0)
; template <class Epi, class Sched, bool ALIGN_EPI = false, bool SP2 = false, bool PAIR_ACC = false>
; __device__ __forceinline__ void gemm_phase(PG8_LAS unsigned char* lds, const Gemm g, const Sched& S, const Epi& E) {
;     ...
;             PG8_WAIT_V(8); PG8_WAIT_L(0); PG8_BAR; PG8_MMA(1, 0, At, B0); PG8_MMA(1, 1, At, B1); PG8_BAR; PG8_SCHED;
;             PG8_LDB(B0, 1, 0); PG8_LDB(B1, 1, 1); PG8_SCHED; PG8_LDA(At, 1, 0); PG8_STAGE(PG8_SA(0, 1), a2 + hstep, voffA);
;             PG8_WAIT_V(8); PG8_WAIT_L(0); PG8_BAR; PG8_MMA(0, 0, At, B0); PG8_MMA(0, 1, At, B1); PG8_BAR; PG8_SCHED;
	v_mfma_f32_16x16x32_bf16 v[126:129], v[152:155], v[194:197], v[126:129]
	v_mfma_f32_16x16x32_bf16 v[122:125], v[160:163], v[194:197], v[122:125]
	v_mfma_f32_16x16x32_bf16 v[86:89], v[152:155], v[210:213], v[86:89]
	v_mfma_f32_16x16x32_bf16 v[66:69], v[160:163], v[210:213], v[66:69]
	v_mfma_f32_16x16x32_bf16 v[30:33], v[152:155], v[218:221], v[30:33]
	v_mfma_f32_16x16x32_bf16 v[26:29], v[160:163], v[218:221], v[26:29]
	v_mfma_f32_16x16x32_bf16 v[14:17], v[152:155], v[226:229], v[14:17]
	v_mfma_f32_16x16x32_bf16 v[10:13], v[160:163], v[226:229], v[10:13]
	v_mfma_f32_16x16x32_bf16 v[126:129], v[156:159], v[206:209], v[126:129]
	v_mfma_f32_16x16x32_bf16 v[122:125], v[174:177], v[206:209], v[122:125]
	v_mfma_f32_16x16x32_bf16 v[86:89], v[156:159], v[214:217], v[86:89]
	v_mfma_f32_16x16x32_bf16 v[66:69], v[174:177], v[214:217], v[66:69]
	v_mfma_f32_16x16x32_bf16 v[30:33], v[156:159], v[222:225], v[30:33]
	v_mfma_f32_16x16x32_bf16 v[26:29], v[174:177], v[222:225], v[26:29]
	v_mfma_f32_16x16x32_bf16 v[14:17], v[156:159], v[230:233], v[14:17]
	v_mfma_f32_16x16x32_bf16 v[10:13], v[174:177], v[230:233], v[10:13]
	s_setprio 0
	s_setprio 1
	v_mfma_f32_16x16x32_bf16 v[118:121], v[178:181], v[194:197], v[118:121]
	v_mfma_f32_16x16x32_bf16 v[106:109], v[186:189], v[194:197], v[106:109]
	v_mfma_f32_16x16x32_bf16 v[38:41], v[178:181], v[210:213], v[38:41]
	v_mfma_f32_16x16x32_bf16 v[34:37], v[186:189], v[210:213], v[34:37]
	v_mfma_f32_16x16x32_bf16 v[22:25], v[178:181], v[218:221], v[22:25]
	v_mfma_f32_16x16x32_bf16 v[18:21], v[186:189], v[218:221], v[18:21]
	v_mfma_f32_16x16x32_bf16 v[6:9], v[178:181], v[226:229], v[6:9]
	v_mfma_f32_16x16x32_bf16 v[2:5], v[186:189], v[226:229], v[2:5]
	v_mfma_f32_16x16x32_bf16 v[118:121], v[182:185], v[206:209], v[118:121]
	v_mfma_f32_16x16x32_bf16 v[106:109], v[190:193], v[206:209], v[106:109]
	v_mfma_f32_16x16x32_bf16 v[38:41], v[182:185], v[214:217], v[38:41]
	v_mfma_f32_16x16x32_bf16 v[34:37], v[190:193], v[214:217], v[34:37]
	v_mfma_f32_16x16x32_bf16 v[22:25], v[182:185], v[222:225], v[22:25]
	v_mfma_f32_16x16x32_bf16 v[18:21], v[190:193], v[222:225], v[18:21]
	v_mfma_f32_16x16x32_bf16 v[6:9], v[182:185], v[230:233], v[6:9]
	v_mfma_f32_16x16x32_bf16 v[2:5], v[190:193], v[230:233], v[2:5]
	s_barrier
	s_setprio 0
	s_add_i32 s60, 0, 0x18000
	v_add_u32_e32 v169, s60, v150
	s_add_i32 s61, 0, 0x1c000
	ds_read_b128 v[152:155], v169
	ds_read_b128 v[156:159], v169 offset:1024
	ds_read_b128 v[160:163], v169 offset:2048
	ds_read_b128 v[174:177], v169 offset:3072
	v_add_u32_e32 v169, s61, v150
	ds_read_b128 v[178:181], v169
	ds_read_b128 v[182:185], v169 offset:1024
	ds_read_b128 v[186:189], v169 offset:2048
	ds_read_b128 v[190:193], v169 offset:3072
	s_add_u32 s52, s52, 0xb0000
	s_addc_u32 s53, s53, 0
	s_mov_b32 m0, s41
	v_lshl_add_u64 v[236:237], s[52:53], 0, v[130:131]
	ds_read_b128 v[194:197], v151 offset:32768
	ds_read_b128 v[206:209], v151 offset:33792
	ds_read_b128 v[210:213], v151 offset:34816
	ds_read_b128 v[214:217], v151 offset:35840
	ds_read_b128 v[218:221], v151 offset:36864
	ds_read_b128 v[222:225], v151 offset:37888
	ds_read_b128 v[226:229], v151 offset:38912
	ds_read_b128 v[230:233], v151 offset:39936
	global_load_lds_dwordx4 v[236:237], off
	v_lshl_add_u64 v[236:237], s[52:53], 0, v[134:135]
	s_mov_b32 m0, s42
	s_nop 0
	global_load_lds_dwordx4 v[236:237], off
	s_waitcnt vmcnt(8)
	s_waitcnt lgkmcnt(0)
	s_setprio 1
	s_barrier
	v_mfma_f32_16x16x32_bf16 v[58:61], v[152:155], v[194:197], v[58:61]
	v_mfma_f32_16x16x32_bf16 v[62:65], v[160:163], v[194:197], v[62:65]
	v_mfma_f32_16x16x32_bf16 v[82:85], v[152:155], v[210:213], v[82:85]
	v_mfma_f32_16x16x32_bf16 v[74:77], v[160:163], v[210:213], v[74:77]
	v_mfma_f32_16x16x32_bf16 v[98:101], v[152:155], v[218:221], v[98:101]
	v_mfma_f32_16x16x32_bf16 v[90:93], v[160:163], v[218:221], v[90:93]
	v_mfma_f32_16x16x32_bf16 v[114:117], v[152:155], v[226:229], v[114:117]
	v_mfma_f32_16x16x32_bf16 v[110:113], v[160:163], v[226:229], v[110:113]
	v_mfma_f32_16x16x32_bf16 v[58:61], v[156:159], v[206:209], v[58:61]
	v_mfma_f32_16x16x32_bf16 v[62:65], v[174:177], v[206:209], v[62:65]
	v_mfma_f32_16x16x32_bf16 v[82:85], v[156:159], v[214:217], v[82:85]
	v_mfma_f32_16x16x32_bf16 v[74:77], v[174:177], v[214:217], v[74:77]
	v_mfma_f32_16x16x32_bf16 v[98:101], v[156:159], v[222:225], v[98:101]
	v_mfma_f32_16x16x32_bf16 v[90:93], v[174:177], v[222:225], v[90:93]
	v_mfma_f32_16x16x32_bf16 v[114:117], v[156:159], v[230:233], v[114:117]
	v_mfma_f32_16x16x32_bf16 v[110:113], v[174:177], v[230:233], v[110:113]
	s_setprio 0
	s_setprio 1
	v_mfma_f32_16x16x32_bf16 v[54:57], v[178:181], v[194:197], v[54:57]
	v_mfma_f32_16x16x32_bf16 v[46:49], v[186:189], v[194:197], v[46:49]
	v_mfma_f32_16x16x32_bf16 v[50:53], v[178:181], v[210:213], v[50:53]
	v_mfma_f32_16x16x32_bf16 v[42:45], v[186:189], v[210:213], v[42:45]
	v_mfma_f32_16x16x32_bf16 v[78:81], v[178:181], v[218:221], v[78:81]
	v_mfma_f32_16x16x32_bf16 v[70:73], v[186:189], v[218:221], v[70:73]
	v_mfma_f32_16x16x32_bf16 v[102:105], v[178:181], v[226:229], v[102:105]
	v_mfma_f32_16x16x32_bf16 v[94:97], v[186:189], v[226:229], v[94:97]
	v_mfma_f32_16x16x32_bf16 v[54:57], v[182:185], v[206:209], v[54:57]
	v_mfma_f32_16x16x32_bf16 v[46:49], v[190:193], v[206:209], v[46:49]
	v_mfma_f32_16x16x32_bf16 v[50:53], v[182:185], v[214:217], v[50:53]
	v_mfma_f32_16x16x32_bf16 v[42:45], v[190:193], v[214:217], v[42:45]
	v_mfma_f32_16x16x32_bf16 v[78:81], v[182:185], v[222:225], v[78:81]
	v_mfma_f32_16x16x32_bf16 v[70:73], v[190:193], v[222:225], v[70:73]
	v_mfma_f32_16x16x32_bf16 v[102:105], v[182:185], v[230:233], v[102:105]
	v_mfma_f32_16x16x32_bf16 v[94:97], v[190:193], v[230:233], v[94:97]
	s_barrier
; #define PG8_STAGE(bufoff, gbase, voff) do { _Pragma("unroll") for (int _i = 0; _i < 2; ++_i) \
;         __builtin_amdgcn_global_load_lds((const unsigned*)((const char*)(gbase) + (voff)[_i]), (PG8_LAS unsigned*)(lds + (bufoff) + ldsw + _i * 8192), 16, 0, 0); } while (0)
; #define PG8_LDA(dst, b, h) do { _Pragma("unroll") for (int m = 0; m < 4; ++m) _Pragma("unroll") for (int k = 0; k < 2; ++k) dst[m][k] = *(const PG8_LAS bf16x8*)(lds + PG8_SA(b, h) + aoff + m * 2048 + k * 1024); } while (0)
; #define PG8_MMA(ai, bj, At, Bt) do { __builtin_amdgcn_s_setprio(1); _Pragma("unroll") for (int m = 0; m < 4; ++m) _Pragma("unroll") for (int n = 0; n < 2; ++n) _Pragma("unroll") for (int k = 0; k < 2; ++k) \
;         acc[ai][bj][m][n] = __builtin_amdgcn_mfma_f32_16x16x32_bf16(Bt[n][k], At[m][k], acc[ai][bj][m][n], 0, 0, 0); __builtin_amdgcn_s_setprio(0); } while (0)
; #define PG8_WAIT_V(n) asm volatile("s_waitcnt vmcnt(" #n ")" ::: "memory")
; #define PG8_WAIT_L(n) asm volatile("s_waitcnt lgkmcnt(" #n ")" ::: "memory")
; #define PG8_BAR __builtin_amdgcn_s_barrier()
; #define PG8_SCHED __builtin_amdgcn_sched_barrier(0)
; template <class Epi, class Sched, bool ALIGN_EPI = false, bool SP2 = false, bool PAIR_ACC = false>
; __device__ __forceinline__ void gemm_phase(PG8_LAS unsigned char* lds, const Gemm g, const Sched& S, const Epi& E) {
;     ...
;             PG8_LDA(At, 1, 1); PG8_STAGE(PG8_SB(1, 0), b3, voffB); PG8_STAGE(PG8_SB(1, 1), b3 + hstep, voffB); PG8_STAGE(PG8_SA(1, 0), a3, voffA);
;             PG8_WAIT_V(8); PG8_WAIT_L(0); PG8_BAR; PG8_MMA(1, 0, At, B0); PG8_MMA(1, 1, At, B1); PG8_BAR; PG8_SCHED;
;     ...
;         if (!has_next) break;
;         if (!(PAIR_ACC && cur.pn < 4)) {
; #pragma unroll
;         for (int a = 0; a < 2; ++a)
; #pragma unroll
;             for (int b = 0; b < 2; ++b)
; #pragma unroll
;                 for (int m = 0; m < 4; ++m)
; #pragma unroll
;                     for (int n = 0; n < 2; ++n) acc[a][b][m][n] = (f32x4){0.f, 0.f, 0.f, 0.f};
;         }
;         cur = nxt; cA = nA; cB = nB; ++ui;
	s_setprio 0
	s_add_i32 s52, s60, s36
	v_lshl_add_u64 v[164:165], v[164:165], 0, s[30:31]
	s_mov_b32 m0, s52
	ds_read_b128 v[194:197], v151 offset:49152
	ds_read_b128 v[206:209], v151 offset:50176
	ds_read_b128 v[210:213], v151 offset:51200
	ds_read_b128 v[214:217], v151 offset:52224
	ds_read_b128 v[218:221], v151 offset:53248
	ds_read_b128 v[222:225], v151 offset:54272
	ds_read_b128 v[226:229], v151 offset:55296
	ds_read_b128 v[230:233], v151 offset:56320
	global_load_lds_dwordx4 v[164:165], off
	s_add_i32 m0, s52, 0x2000
	s_add_u32 s38, s38, 0xb0080
	v_lshl_add_u64 v[164:165], v[170:171], 0, s[30:31]
	s_addc_u32 s39, s39, 0
	s_add_i32 s52, s61, s36
	global_load_lds_dwordx4 v[164:165], off
	v_lshl_add_u64 v[164:165], s[38:39], 0, v[132:133]
	s_mov_b32 m0, s52
	s_nop 0
	global_load_lds_dwordx4 v[164:165], off
	v_lshl_add_u64 v[164:165], s[38:39], 0, v[136:137]
	s_add_i32 m0, s52, 0x2000
	s_nop 0
	global_load_lds_dwordx4 v[164:165], off
	v_lshl_add_u64 v[164:165], v[198:199], 0, s[30:31]
	s_mov_b32 m0, s44
	s_nop 0
	global_load_lds_dwordx4 v[164:165], off
	v_lshl_add_u64 v[164:165], v[234:235], 0, s[30:31]
	s_mov_b32 m0, s45
	s_nop 0
	global_load_lds_dwordx4 v[164:165], off
	s_waitcnt vmcnt(8)
	s_waitcnt lgkmcnt(0)
	s_setprio 1
	s_barrier
	v_mfma_f32_16x16x32_bf16 v[126:129], v[152:155], v[194:197], v[126:129]
	v_mfma_f32_16x16x32_bf16 v[122:125], v[160:163], v[194:197], v[122:125]
	v_mfma_f32_16x16x32_bf16 v[86:89], v[152:155], v[210:213], v[86:89]
	v_mfma_f32_16x16x32_bf16 v[66:69], v[160:163], v[210:213], v[66:69]
	v_mfma_f32_16x16x32_bf16 v[30:33], v[152:155], v[218:221], v[30:33]
	v_mfma_f32_16x16x32_bf16 v[26:29], v[160:163], v[218:221], v[26:29]
	v_mfma_f32_16x16x32_bf16 v[14:17], v[152:155], v[226:229], v[14:17]
	v_mfma_f32_16x16x32_bf16 v[10:13], v[160:163], v[226:229], v[10:13]
	v_mfma_f32_16x16x32_bf16 v[126:129], v[156:159], v[206:209], v[126:129]
	v_mfma_f32_16x16x32_bf16 v[122:125], v[174:177], v[206:209], v[122:125]
	v_mfma_f32_16x16x32_bf16 v[86:89], v[156:159], v[214:217], v[86:89]
	v_mfma_f32_16x16x32_bf16 v[66:69], v[174:177], v[214:217], v[66:69]
	v_mfma_f32_16x16x32_bf16 v[30:33], v[156:159], v[222:225], v[30:33]
	v_mfma_f32_16x16x32_bf16 v[26:29], v[174:177], v[222:225], v[26:29]
	v_mfma_f32_16x16x32_bf16 v[14:17], v[156:159], v[230:233], v[14:17]
	v_mfma_f32_16x16x32_bf16 v[10:13], v[174:177], v[230:233], v[10:13]
	s_setprio 0
	s_setprio 1
	v_mfma_f32_16x16x32_bf16 v[118:121], v[178:181], v[194:197], v[118:121]
	v_mfma_f32_16x16x32_bf16 v[106:109], v[186:189], v[194:197], v[106:109]
	v_mfma_f32_16x16x32_bf16 v[38:41], v[178:181], v[210:213], v[38:41]
	v_mfma_f32_16x16x32_bf16 v[34:37], v[186:189], v[210:213], v[34:37]
	v_mfma_f32_16x16x32_bf16 v[22:25], v[178:181], v[218:221], v[22:25]
	v_mfma_f32_16x16x32_bf16 v[18:21], v[186:189], v[218:221], v[18:21]
	v_mfma_f32_16x16x32_bf16 v[6:9], v[178:181], v[226:229], v[6:9]
	v_mfma_f32_16x16x32_bf16 v[2:5], v[186:189], v[226:229], v[2:5]
	v_mfma_f32_16x16x32_bf16 v[118:121], v[182:185], v[206:209], v[118:121]
	v_mfma_f32_16x16x32_bf16 v[106:109], v[190:193], v[206:209], v[106:109]
	v_mfma_f32_16x16x32_bf16 v[38:41], v[182:185], v[214:217], v[38:41]
	v_mfma_f32_16x16x32_bf16 v[34:37], v[190:193], v[214:217], v[34:37]
	v_mfma_f32_16x16x32_bf16 v[22:25], v[182:185], v[222:225], v[22:25]
	v_mfma_f32_16x16x32_bf16 v[18:21], v[190:193], v[222:225], v[18:21]
	v_mfma_f32_16x16x32_bf16 v[6:9], v[182:185], v[230:233], v[6:9]
	v_mfma_f32_16x16x32_bf16 v[2:5], v[190:193], v[230:233], v[2:5]
	s_barrier
	s_setprio 0
	s_add_i32 s59, s59, 2
	s_add_u32 s50, s50, 0x100
	s_addc_u32 s51, s51, 0
	s_cmp_gt_u32 s59, 41
	s_cbranch_scc0 .LBB0_937
	s_add_u32 s38, s57, 0xffffff00
	s_addc_u32 s39, s58, -1
	s_and_b64 vcc, exec, s[8:9]
	s_cbranch_vccnz .LBB0_924
	v_mov_b32_e32 v2, 0
	s_mov_b32 s18, s54
	s_mov_b32 s5, s55
	s_mov_b64 s[28:29], s[48:49]
	s_mov_b32 s43, s56
	v_mov_b32_e32 v3, v2
	v_mov_b32_e32 v4, v2
	v_mov_b32_e32 v5, v2
	v_mov_b32_e32 v6, v2
	v_mov_b32_e32 v7, v2
	v_mov_b32_e32 v8, v2
	v_mov_b32_e32 v9, v2
	v_mov_b32_e32 v18, v2
	v_mov_b32_e32 v19, v2
	v_mov_b32_e32 v20, v2
	v_mov_b32_e32 v21, v2
	v_mov_b32_e32 v22, v2
	v_mov_b32_e32 v23, v2
	v_mov_b32_e32 v24, v2
	v_mov_b32_e32 v25, v2
	v_mov_b32_e32 v34, v2
	v_mov_b32_e32 v35, v2
	v_mov_b32_e32 v36, v2
	v_mov_b32_e32 v37, v2
	v_mov_b32_e32 v38, v2
	v_mov_b32_e32 v39, v2
	v_mov_b32_e32 v40, v2
	v_mov_b32_e32 v41, v2
	v_mov_b32_e32 v106, v2
	v_mov_b32_e32 v107, v2
	v_mov_b32_e32 v108, v2
	v_mov_b32_e32 v109, v2
	v_mov_b32_e32 v118, v2
	v_mov_b32_e32 v119, v2
	v_mov_b32_e32 v120, v2
	v_mov_b32_e32 v121, v2
	v_mov_b32_e32 v10, v2
	v_mov_b32_e32 v11, v2
	v_mov_b32_e32 v12, v2
	v_mov_b32_e32 v13, v2
	v_mov_b32_e32 v14, v2
	v_mov_b32_e32 v15, v2
	v_mov_b32_e32 v16, v2
	v_mov_b32_e32 v17, v2
	v_mov_b32_e32 v26, v2
	v_mov_b32_e32 v27, v2
	v_mov_b32_e32 v28, v2
	v_mov_b32_e32 v29, v2
	v_mov_b32_e32 v30, v2
	v_mov_b32_e32 v31, v2
	v_mov_b32_e32 v32, v2
	v_mov_b32_e32 v33, v2
	v_mov_b32_e32 v66, v2
	v_mov_b32_e32 v67, v2
	v_mov_b32_e32 v68, v2
	v_mov_b32_e32 v69, v2
	v_mov_b32_e32 v86, v2
	v_mov_b32_e32 v87, v2
	v_mov_b32_e32 v88, v2
	v_mov_b32_e32 v89, v2
	v_mov_b32_e32 v122, v2
	v_mov_b32_e32 v123, v2
	v_mov_b32_e32 v124, v2
	v_mov_b32_e32 v125, v2
	v_mov_b32_e32 v126, v2
	v_mov_b32_e32 v127, v2
	v_mov_b32_e32 v128, v2
	v_mov_b32_e32 v129, v2
	v_mov_b32_e32 v94, v2
	v_mov_b32_e32 v95, v2
	v_mov_b32_e32 v96, v2
	v_mov_b32_e32 v97, v2
	v_mov_b32_e32 v102, v2
	v_mov_b32_e32 v103, v2
	v_mov_b32_e32 v104, v2
	v_mov_b32_e32 v105, v2
	v_mov_b32_e32 v70, v2
	v_mov_b32_e32 v71, v2
	v_mov_b32_e32 v72, v2
	v_mov_b32_e32 v73, v2
	v_mov_b32_e32 v78, v2
	v_mov_b32_e32 v79, v2
	v_mov_b32_e32 v80, v2
	v_mov_b32_e32 v81, v2
	v_mov_b32_e32 v42, v2
	v_mov_b32_e32 v43, v2
	v_mov_b32_e32 v44, v2
	v_mov_b32_e32 v45, v2
	v_mov_b32_e32 v50, v2
	v_mov_b32_e32 v51, v2
	v_mov_b32_e32 v52, v2
	v_mov_b32_e32 v53, v2
	v_mov_b32_e32 v46, v2
	v_mov_b32_e32 v47, v2
	v_mov_b32_e32 v48, v2
	v_mov_b32_e32 v49, v2
	v_mov_b32_e32 v54, v2
	v_mov_b32_e32 v55, v2
	v_mov_b32_e32 v56, v2
	v_mov_b32_e32 v57, v2
	v_mov_b32_e32 v110, v2
	v_mov_b32_e32 v111, v2
	v_mov_b32_e32 v112, v2
	v_mov_b32_e32 v113, v2
	v_mov_b32_e32 v114, v2
	v_mov_b32_e32 v115, v2
	v_mov_b32_e32 v116, v2
	v_mov_b32_e32 v117, v2
	v_mov_b32_e32 v90, v2
	v_mov_b32_e32 v91, v2
	v_mov_b32_e32 v92, v2
	v_mov_b32_e32 v93, v2
	v_mov_b32_e32 v98, v2
	v_mov_b32_e32 v99, v2
	v_mov_b32_e32 v100, v2
	v_mov_b32_e32 v101, v2
	v_mov_b32_e32 v74, v2
	v_mov_b32_e32 v75, v2
	v_mov_b32_e32 v76, v2
	v_mov_b32_e32 v77, v2
	v_mov_b32_e32 v82, v2
	v_mov_b32_e32 v83, v2
	v_mov_b32_e32 v84, v2
	v_mov_b32_e32 v85, v2
	v_mov_b32_e32 v62, v2
	v_mov_b32_e32 v63, v2
	v_mov_b32_e32 v64, v2
	v_mov_b32_e32 v65, v2
	v_mov_b32_e32 v58, v2
	v_mov_b32_e32 v59, v2
	v_mov_b32_e32 v60, v2
	v_mov_b32_e32 v61, v2
	s_andn2_b64 vcc, exec, s[6:7]
	s_cbranch_vccnz .LBB0_925

; #define PG8_STAGE(bufoff, gbase, voff) do { _Pragma("unroll") for (int _i = 0; _i < 2; ++_i) \
;         __builtin_amdgcn_global_load_lds((const unsigned*)((const char*)(gbase) + (voff)[_i]), (PG8_LAS unsigned*)(lds + (bufoff) + ldsw + _i * 8192), 16, 0, 0); } while (0)
; #define PG8_LDA(dst, b, h) do { _Pragma("unroll") for (int m = 0; m < 4; ++m) _Pragma("unroll") for (int k = 0; k < 2; ++k) dst[m][k] = *(const PG8_LAS bf16x8*)(lds + PG8_SA(b, h) + aoff + m * 2048 + k * 1024); } while (0)
; #define PG8_LDB(dst, b, h) do { _Pragma("unroll") for (int n = 0; n < 2; ++n) _Pragma("unroll") for (int k = 0; k < 2; ++k) dst[n][k] = *(const PG8_LAS bf16x8*)(lds + PG8_SB(b, h) + boff + n * 2048 + k * 1024); } while (0)
; #define PG8_WAIT_V(n) asm volatile("s_waitcnt vmcnt(" #n ")" ::: "memory")
; #define PG8_WAIT_L(n) asm volatile("s_waitcnt lgkmcnt(" #n ")" ::: "memory")
; #define PG8_BAR __builtin_amdgcn_s_barrier()
; template <class Epi, class Sched, bool ALIGN_EPI = false, bool SP2 = false, bool PAIR_ACC = false>
; __device__ __forceinline__ void gemm_phase(PG8_LAS unsigned char* lds, const Gemm g, const Sched& S, const Epi& E) {
;     ...
;         const bool has_next = S.next(ui + 1, nxt);
;         const char* nA = has_next ? (const char*)g.A + (size_t)nxt.pm * tstep + (size_t)(nxt.pn / g.a_div) * g.a_sel : cA; const char* nB = has_next ? (const char*)g.Bt + (size_t)nxt.pn * tstep : cB;
;         for (int t = 0; t < nt; t += 2) {
;             const bool last = (t == nt - 2);
;             const char* a1 = cA + (size_t)(t + 1) * kstep;
;             const char* a2 = last ? nA : cA + (size_t)(t + 2) * kstep; const char* b2 = last ? nB : cB + (size_t)(t + 2) * kstep;
;             const char* a3 = a2 + kstep; const char* b3 = b2 + kstep;
;             if (last && has_next) S.a_ready(nxt);
;             if constexpr (SP2) {
;             PG8_LDB(B0, 0, 0); PG8_LDB(B1, 0, 1); PG8_SCHED; PG8_LDA(At, 0, 0); PG8_STAGE(PG8_SA(1, 1), a1 + hstep, voffA);
;             PG8_WAIT_V(8); PG8_WAIT_L(0); PG8_BAR; PG8_MMA(0, 0, At, B0); PG8_MMA(0, 1, At, B1); PG8_BAR; PG8_SCHED;
;             PG8_LDA(At, 0, 1); PG8_STAGE(PG8_SB(0, 0), b2, voffB); PG8_STAGE(PG8_SB(0, 1), b2 + hstep, voffB); PG8_STAGE(PG8_SA(0, 0), a2, voffA);
;             PG8_WAIT_V(8); PG8_WAIT_L(0); PG8_BAR; PG8_MMA(1, 0, At, B0); PG8_MMA(1, 1, At, B1); PG8_BAR; PG8_SCHED;
.LBB0_1092:
	s_mov_b32 s78, s23
	s_ashr_i32 s79, s23, 31
	s_lshl_b64 s[20:21], s[78:79], 19
	s_add_u32 s82, s59, s20
	s_addc_u32 s83, s61, s21
	s_mov_b32 s76, s19
	s_and_b64 s[20:21], s[80:81], exec
	s_cselect_b32 s15, s83, s13
	s_cselect_b32 s19, s82, s12
	s_ashr_i32 s77, s76, 31
	s_lshl_b64 s[20:21], s[76:77], 19
	s_add_u32 s84, s63, s20
	s_addc_u32 s85, s69, s21
	s_and_b64 s[20:21], s[80:81], exec
	s_cselect_b32 s22, s85, s17
	s_cselect_b32 s23, s84, s16
	s_add_u32 s12, s12, 0x40080
	s_addc_u32 s13, s13, 0
	s_add_u32 s30, s16, 0x100
	s_addc_u32 s42, s17, 0
	s_mov_b32 s43, -2
	s_waitcnt lgkmcnt(0)
	ds_read_b128 v[130:133], v195
	ds_read_b128 v[134:137], v195 offset:1024
	ds_read_b128 v[138:141], v195 offset:2048
	ds_read_b128 v[142:145], v195 offset:3072
	ds_read_b128 v[176:179], v196
	ds_read_b128 v[180:183], v196 offset:1024
	ds_read_b128 v[184:187], v196 offset:2048
	ds_read_b128 v[188:191], v196 offset:3072
	s_add_u32 s16, s12, 0xfffc0080
	s_addc_u32 s17, s13, -1
	s_cmp_eq_u32 s43, 12
	s_cselect_b32 s21, s15, s17
	s_cselect_b32 s20, s19, s16
	s_cselect_b32 s17, s22, s42
	s_cselect_b32 s16, s23, s30
	v_lshl_add_u64 v[192:193], s[12:13], 0, v[170:171]
	s_add_i32 m0, s73, 0xc000
	ds_read_b128 v[200:203], v197
	ds_read_b128 v[204:207], v197 offset:1024
	ds_read_b128 v[208:211], v197 offset:2048
	ds_read_b128 v[212:215], v197 offset:3072
	ds_read_b128 v[216:219], v197 offset:4096
	ds_read_b128 v[220:223], v197 offset:5120
	ds_read_b128 v[224:227], v197 offset:6144
	ds_read_b128 v[228:231], v197 offset:7168
	global_load_lds_dwordx4 v[192:193], off
	v_lshl_add_u64 v[192:193], s[12:13], 0, v[172:173]
	s_add_i32 m0, s73, 0xe000
	s_nop 0
	global_load_lds_dwordx4 v[192:193], off
	s_waitcnt vmcnt(8)
	s_waitcnt lgkmcnt(0)
	s_setprio 1
	s_barrier
	v_mfma_f32_16x16x32_bf16 v[126:129], v[130:133], v[200:203], 0
	v_mfma_f32_16x16x32_bf16 v[122:125], v[138:141], v[200:203], 0
	v_mfma_f32_16x16x32_bf16 v[110:113], v[130:133], v[208:211], 0
	v_mfma_f32_16x16x32_bf16 v[106:109], v[138:141], v[208:211], 0
	v_mfma_f32_16x16x32_bf16 v[94:97], v[130:133], v[216:219], 0
	v_mfma_f32_16x16x32_bf16 v[90:93], v[138:141], v[216:219], 0
	v_mfma_f32_16x16x32_bf16 v[78:81], v[130:133], v[224:227], 0
	v_mfma_f32_16x16x32_bf16 v[74:77], v[138:141], v[224:227], 0
	v_mfma_f32_16x16x32_bf16 v[126:129], v[134:137], v[204:207], v[126:129]
	v_mfma_f32_16x16x32_bf16 v[122:125], v[142:145], v[204:207], v[122:125]
	v_mfma_f32_16x16x32_bf16 v[110:113], v[134:137], v[212:215], v[110:113]
	v_mfma_f32_16x16x32_bf16 v[106:109], v[142:145], v[212:215], v[106:109]
	v_mfma_f32_16x16x32_bf16 v[94:97], v[134:137], v[220:223], v[94:97]
	v_mfma_f32_16x16x32_bf16 v[90:93], v[142:145], v[220:223], v[90:93]
	v_mfma_f32_16x16x32_bf16 v[78:81], v[134:137], v[228:231], v[78:81]
	v_mfma_f32_16x16x32_bf16 v[74:77], v[142:145], v[228:231], v[74:77]
	s_setprio 0
	s_setprio 1
	v_mfma_f32_16x16x32_bf16 v[118:121], v[176:179], v[200:203], 0
	v_mfma_f32_16x16x32_bf16 v[114:117], v[184:187], v[200:203], 0
	v_mfma_f32_16x16x32_bf16 v[102:105], v[176:179], v[208:211], 0
	v_mfma_f32_16x16x32_bf16 v[98:101], v[184:187], v[208:211], 0
	v_mfma_f32_16x16x32_bf16 v[86:89], v[176:179], v[216:219], 0
	v_mfma_f32_16x16x32_bf16 v[82:85], v[184:187], v[216:219], 0
	v_mfma_f32_16x16x32_bf16 v[70:73], v[176:179], v[224:227], 0
	v_mfma_f32_16x16x32_bf16 v[66:69], v[184:187], v[224:227], 0
	v_mfma_f32_16x16x32_bf16 v[118:121], v[180:183], v[204:207], v[118:121]
	v_mfma_f32_16x16x32_bf16 v[114:117], v[188:191], v[204:207], v[114:117]
	v_mfma_f32_16x16x32_bf16 v[102:105], v[180:183], v[212:215], v[102:105]
	v_mfma_f32_16x16x32_bf16 v[98:101], v[188:191], v[212:215], v[98:101]
	v_mfma_f32_16x16x32_bf16 v[86:89], v[180:183], v[220:223], v[86:89]
	v_mfma_f32_16x16x32_bf16 v[82:85], v[188:191], v[220:223], v[82:85]
	v_mfma_f32_16x16x32_bf16 v[70:73], v[180:183], v[228:231], v[70:73]
	v_mfma_f32_16x16x32_bf16 v[66:69], v[188:191], v[228:231], v[66:69]
	s_barrier
	s_setprio 0
	s_add_i32 s77, s34, s71
	v_lshl_add_u64 v[192:193], s[16:17], 0, v[148:149]
	s_mov_b32 m0, s77
	ds_read_b128 v[200:203], v197 offset:16384
	ds_read_b128 v[204:207], v197 offset:17408
	ds_read_b128 v[208:211], v197 offset:18432
	ds_read_b128 v[212:215], v197 offset:19456
	ds_read_b128 v[216:219], v197 offset:20480
	ds_read_b128 v[220:223], v197 offset:21504
	ds_read_b128 v[224:227], v197 offset:22528
	ds_read_b128 v[228:231], v197 offset:23552
	global_load_lds_dwordx4 v[192:193], off
	s_add_i32 m0, s77, 0x2000
	s_add_u32 s86, s16, 0x40000
	v_lshl_add_u64 v[232:233], s[16:17], 0, v[152:153]
	s_addc_u32 s87, s17, 0
	s_add_i32 s77, s35, s71
	global_load_lds_dwordx4 v[232:233], off
	v_lshl_add_u64 v[234:235], s[86:87], 0, v[148:149]
	s_mov_b32 m0, s77
	v_lshl_add_u64 v[236:237], s[20:21], 0, v[150:151]
	global_load_lds_dwordx4 v[234:235], off
	v_lshl_add_u64 v[234:235], s[86:87], 0, v[152:153]
	s_add_i32 m0, s77, 0x2000
	s_nop 0
	global_load_lds_dwordx4 v[234:235], off
	v_lshl_add_u64 v[234:235], s[20:21], 0, v[146:147]
	s_mov_b32 m0, s73
	s_nop 0
	global_load_lds_dwordx4 v[234:235], off
	s_mov_b32 m0, s75
	s_nop 0
	global_load_lds_dwordx4 v[236:237], off
	s_waitcnt vmcnt(8)
	s_waitcnt lgkmcnt(0)
	s_setprio 1
	s_barrier
; #define PG8_STAGE(bufoff, gbase, voff) do { _Pragma("unroll") for (int _i = 0; _i < 2; ++_i) \
;         __builtin_amdgcn_global_load_lds((const unsigned*)((const char*)(gbase) + (voff)[_i]), (PG8_LAS unsigned*)(lds + (bufoff) + ldsw + _i * 8192), 16, 0, 0); } while (0)
; #define PG8_LDA(dst, b, h) do { _Pragma("unroll") for (int m = 0; m < 4; ++m) _Pragma("unroll") for (int k = 0; k < 2; ++k) dst[m][k] = *(const PG8_LAS bf16x8*)(lds + PG8_SA(b, h) + aoff + m * 2048 + k * 1024); } while (0)
; #define PG8_LDB(dst, b, h) do { _Pragma("unroll") for (int n = 0; n < 2; ++n) _Pragma("unroll") for (int k = 0; k < 2; ++k) dst[n][k] = *(const PG8_LAS bf16x8*)(lds + PG8_SB(b, h) + boff + n * 2048 + k * 1024); } while (0)
; #define PG8_MMA(ai, bj, At, Bt) do { __builtin_amdgcn_s_setprio(1); _Pragma("unroll") for (int m = 0; m < 4; ++m) _Pragma("unroll") for (int n = 0; n < 2; ++n) _Pragma("unroll") for (int k = 0; k < 2; ++k) \
;         acc[ai][bj][m][n] = __builtin_amdgcn_mfma_f32_16x16x32_bf16(Bt[n][k], At[m][k], acc[ai][bj][m][n], 0, 0, 0); __builtin_amdgcn_s_setprio(0); } while (0)
; #define PG8_WAIT_V(n) asm volatile("s_waitcnt vmcnt(" #n ")" ::: "memory")
; #define PG8_WAIT_L(n) asm volatile("s_waitcnt lgkmcnt(" #n ")" ::: "memory")
; #define PG8_BAR __builtin_amdgcn_s_barrier()
; #define PG8_SCHED __builtin_amdgcn_sched_barrier(0)
; template <class Epi, class Sched, bool ALIGN_EPI = false, bool SP2 = false, bool PAIR_ACC = false>
; __device__ __forceinline__ void gemm_phase(PG8_LAS unsigned char* lds, const Gemm g, const Sched& S, const Epi& E) {
;     ...
;             PG8_LDB(B0, 0, 0); PG8_LDB(B1, 0, 1); PG8_SCHED; PG8_LDA(At, 0, 0); PG8_STAGE(PG8_SA(1, 1), a1 + hstep, voffA);
;             PG8_WAIT_V(8); PG8_WAIT_L(0); PG8_BAR; PG8_MMA(0, 0, At, B0); PG8_MMA(0, 1, At, B1); PG8_BAR; PG8_SCHED;
;             PG8_LDA(At, 0, 1); PG8_STAGE(PG8_SB(0, 0), b2, voffB); PG8_STAGE(PG8_SB(0, 1), b2 + hstep, voffB); PG8_STAGE(PG8_SA(0, 0), a2, voffA);
;             PG8_WAIT_V(8); PG8_WAIT_L(0); PG8_BAR; PG8_MMA(1, 0, At, B0); PG8_MMA(1, 1, At, B1); PG8_BAR; PG8_SCHED;
	v_mfma_f32_16x16x32_bf16 v[62:65], v[130:133], v[200:203], 0
	v_mfma_f32_16x16x32_bf16 v[58:61], v[138:141], v[200:203], 0
	v_mfma_f32_16x16x32_bf16 v[46:49], v[130:133], v[208:211], 0
	v_mfma_f32_16x16x32_bf16 v[42:45], v[138:141], v[208:211], 0
	v_mfma_f32_16x16x32_bf16 v[30:33], v[130:133], v[216:219], 0
	v_mfma_f32_16x16x32_bf16 v[26:29], v[138:141], v[216:219], 0
	v_mfma_f32_16x16x32_bf16 v[14:17], v[130:133], v[224:227], 0
	v_mfma_f32_16x16x32_bf16 v[10:13], v[138:141], v[224:227], 0
	v_mfma_f32_16x16x32_bf16 v[62:65], v[134:137], v[204:207], v[62:65]
	v_mfma_f32_16x16x32_bf16 v[58:61], v[142:145], v[204:207], v[58:61]
	v_mfma_f32_16x16x32_bf16 v[46:49], v[134:137], v[212:215], v[46:49]
	v_mfma_f32_16x16x32_bf16 v[42:45], v[142:145], v[212:215], v[42:45]
	v_mfma_f32_16x16x32_bf16 v[30:33], v[134:137], v[220:223], v[30:33]
	v_mfma_f32_16x16x32_bf16 v[26:29], v[142:145], v[220:223], v[26:29]
	v_mfma_f32_16x16x32_bf16 v[14:17], v[134:137], v[228:231], v[14:17]
	v_mfma_f32_16x16x32_bf16 v[10:13], v[142:145], v[228:231], v[10:13]
	s_setprio 0
	s_setprio 1
	v_mfma_f32_16x16x32_bf16 v[54:57], v[176:179], v[200:203], 0
	v_mfma_f32_16x16x32_bf16 v[50:53], v[184:187], v[200:203], 0
	v_mfma_f32_16x16x32_bf16 v[38:41], v[176:179], v[208:211], 0
	v_mfma_f32_16x16x32_bf16 v[34:37], v[184:187], v[208:211], 0
	v_mfma_f32_16x16x32_bf16 v[22:25], v[176:179], v[216:219], 0
	v_mfma_f32_16x16x32_bf16 v[18:21], v[184:187], v[216:219], 0
	v_mfma_f32_16x16x32_bf16 v[6:9], v[176:179], v[224:227], 0
	v_mfma_f32_16x16x32_bf16 v[2:5], v[184:187], v[224:227], 0
	v_mfma_f32_16x16x32_bf16 v[54:57], v[180:183], v[204:207], v[54:57]
	v_mfma_f32_16x16x32_bf16 v[50:53], v[188:191], v[204:207], v[50:53]
	v_mfma_f32_16x16x32_bf16 v[38:41], v[180:183], v[212:215], v[38:41]
	v_mfma_f32_16x16x32_bf16 v[34:37], v[188:191], v[212:215], v[34:37]
	v_mfma_f32_16x16x32_bf16 v[22:25], v[180:183], v[220:223], v[22:25]
	v_mfma_f32_16x16x32_bf16 v[18:21], v[188:191], v[220:223], v[18:21]
	v_mfma_f32_16x16x32_bf16 v[6:9], v[180:183], v[228:231], v[6:9]
	v_mfma_f32_16x16x32_bf16 v[2:5], v[188:191], v[228:231], v[2:5]
	s_barrier
	s_setprio 0
	s_branch .Lpeel_mid_1093
.LBB0_1093:
	ds_read_b128 v[130:133], v195
	ds_read_b128 v[134:137], v195 offset:1024
	ds_read_b128 v[138:141], v195 offset:2048
	ds_read_b128 v[142:145], v195 offset:3072
	ds_read_b128 v[176:179], v196
	ds_read_b128 v[180:183], v196 offset:1024
	ds_read_b128 v[184:187], v196 offset:2048
	ds_read_b128 v[188:191], v196 offset:3072
	s_add_u32 s16, s12, 0xfffc0080
	s_addc_u32 s17, s13, -1
	s_cmp_eq_u32 s43, 12
	s_cselect_b32 s21, s15, s17
	s_cselect_b32 s20, s19, s16
	s_cselect_b32 s17, s22, s42
	s_cselect_b32 s16, s23, s30
	v_lshl_add_u64 v[192:193], s[12:13], 0, v[170:171]
	s_add_i32 m0, s73, 0xc000
	ds_read_b128 v[200:203], v197
	ds_read_b128 v[204:207], v197 offset:1024
	ds_read_b128 v[208:211], v197 offset:2048
	ds_read_b128 v[212:215], v197 offset:3072
	ds_read_b128 v[216:219], v197 offset:4096
	ds_read_b128 v[220:223], v197 offset:5120
	ds_read_b128 v[224:227], v197 offset:6144
	ds_read_b128 v[228:231], v197 offset:7168
	global_load_lds_dwordx4 v[192:193], off
	v_lshl_add_u64 v[192:193], s[12:13], 0, v[172:173]
	s_add_i32 m0, s73, 0xe000
	s_nop 0
	global_load_lds_dwordx4 v[192:193], off
	s_waitcnt vmcnt(8)
	s_waitcnt lgkmcnt(0)
	s_setprio 1
	s_barrier
	v_mfma_f32_16x16x32_bf16 v[126:129], v[130:133], v[200:203], v[126:129]
	v_mfma_f32_16x16x32_bf16 v[122:125], v[138:141], v[200:203], v[122:125]
	v_mfma_f32_16x16x32_bf16 v[110:113], v[130:133], v[208:211], v[110:113]
	v_mfma_f32_16x16x32_bf16 v[106:109], v[138:141], v[208:211], v[106:109]
	v_mfma_f32_16x16x32_bf16 v[94:97], v[130:133], v[216:219], v[94:97]
	v_mfma_f32_16x16x32_bf16 v[90:93], v[138:141], v[216:219], v[90:93]
	v_mfma_f32_16x16x32_bf16 v[78:81], v[130:133], v[224:227], v[78:81]
	v_mfma_f32_16x16x32_bf16 v[74:77], v[138:141], v[224:227], v[74:77]
	v_mfma_f32_16x16x32_bf16 v[126:129], v[134:137], v[204:207], v[126:129]
	v_mfma_f32_16x16x32_bf16 v[122:125], v[142:145], v[204:207], v[122:125]
	v_mfma_f32_16x16x32_bf16 v[110:113], v[134:137], v[212:215], v[110:113]
	v_mfma_f32_16x16x32_bf16 v[106:109], v[142:145], v[212:215], v[106:109]
	v_mfma_f32_16x16x32_bf16 v[94:97], v[134:137], v[220:223], v[94:97]
	v_mfma_f32_16x16x32_bf16 v[90:93], v[142:145], v[220:223], v[90:93]
	v_mfma_f32_16x16x32_bf16 v[78:81], v[134:137], v[228:231], v[78:81]
	v_mfma_f32_16x16x32_bf16 v[74:77], v[142:145], v[228:231], v[74:77]
	s_setprio 0
	s_setprio 1
	v_mfma_f32_16x16x32_bf16 v[118:121], v[176:179], v[200:203], v[118:121]
	v_mfma_f32_16x16x32_bf16 v[114:117], v[184:187], v[200:203], v[114:117]
	v_mfma_f32_16x16x32_bf16 v[102:105], v[176:179], v[208:211], v[102:105]
	v_mfma_f32_16x16x32_bf16 v[98:101], v[184:187], v[208:211], v[98:101]
	v_mfma_f32_16x16x32_bf16 v[86:89], v[176:179], v[216:219], v[86:89]
	v_mfma_f32_16x16x32_bf16 v[82:85], v[184:187], v[216:219], v[82:85]
	v_mfma_f32_16x16x32_bf16 v[70:73], v[176:179], v[224:227], v[70:73]
	v_mfma_f32_16x16x32_bf16 v[66:69], v[184:187], v[224:227], v[66:69]
	v_mfma_f32_16x16x32_bf16 v[118:121], v[180:183], v[204:207], v[118:121]
	v_mfma_f32_16x16x32_bf16 v[114:117], v[188:191], v[204:207], v[114:117]
	v_mfma_f32_16x16x32_bf16 v[102:105], v[180:183], v[212:215], v[102:105]
	v_mfma_f32_16x16x32_bf16 v[98:101], v[188:191], v[212:215], v[98:101]
	v_mfma_f32_16x16x32_bf16 v[86:89], v[180:183], v[220:223], v[86:89]
	v_mfma_f32_16x16x32_bf16 v[82:85], v[188:191], v[220:223], v[82:85]
	v_mfma_f32_16x16x32_bf16 v[70:73], v[180:183], v[228:231], v[70:73]
	v_mfma_f32_16x16x32_bf16 v[66:69], v[188:191], v[228:231], v[66:69]
	s_barrier
; #define PG8_STAGE(bufoff, gbase, voff) do { _Pragma("unroll") for (int _i = 0; _i < 2; ++_i) \
;         __builtin_amdgcn_global_load_lds((const unsigned*)((const char*)(gbase) + (voff)[_i]), (PG8_LAS unsigned*)(lds + (bufoff) + ldsw + _i * 8192), 16, 0, 0); } while (0)
; #define PG8_LDA(dst, b, h) do { _Pragma("unroll") for (int m = 0; m < 4; ++m) _Pragma("unroll") for (int k = 0; k < 2; ++k) dst[m][k] = *(const PG8_LAS bf16x8*)(lds + PG8_SA(b, h) + aoff + m * 2048 + k * 1024); } while (0)
; #define PG8_LDB(dst, b, h) do { _Pragma("unroll") for (int n = 0; n < 2; ++n) _Pragma("unroll") for (int k = 0; k < 2; ++k) dst[n][k] = *(const PG8_LAS bf16x8*)(lds + PG8_SB(b, h) + boff + n * 2048 + k * 1024); } while (0)
; #define PG8_MMA(ai, bj, At, Bt) do { __builtin_amdgcn_s_setprio(1); _Pragma("unroll") for (int m = 0; m < 4; ++m) _Pragma("unroll") for (int n = 0; n < 2; ++n) _Pragma("unroll") for (int k = 0; k < 2; ++k) \
;         acc[ai][bj][m][n] = __builtin_amdgcn_mfma_f32_16x16x32_bf16(Bt[n][k], At[m][k], acc[ai][bj][m][n], 0, 0, 0); __builtin_amdgcn_s_setprio(0); } while (0)
; #define PG8_WAIT_V(n) asm volatile("s_waitcnt vmcnt(" #n ")" ::: "memory")
; #define PG8_WAIT_L(n) asm volatile("s_waitcnt lgkmcnt(" #n ")" ::: "memory")
; #define PG8_BAR __builtin_amdgcn_s_barrier()
; #define PG8_SCHED __builtin_amdgcn_sched_barrier(0)
; template <class Epi, class Sched, bool ALIGN_EPI = false, bool SP2 = false, bool PAIR_ACC = false>
; __device__ __forceinline__ void gemm_phase(PG8_LAS unsigned char* lds, const Gemm g, const Sched& S, const Epi& E) {
;     ...
;             PG8_LDA(At, 0, 1); PG8_STAGE(PG8_SB(0, 0), b2, voffB); PG8_STAGE(PG8_SB(0, 1), b2 + hstep, voffB); PG8_STAGE(PG8_SA(0, 0), a2, voffA);
;             PG8_WAIT_V(8); PG8_WAIT_L(0); PG8_BAR; PG8_MMA(1, 0, At, B0); PG8_MMA(1, 1, At, B1); PG8_BAR; PG8_SCHED;
;             PG8_LDB(B0, 1, 0); PG8_LDB(B1, 1, 1); PG8_SCHED; PG8_LDA(At, 1, 0); PG8_STAGE(PG8_SA(0, 1), a2 + hstep, voffA);
	s_setprio 0
	s_add_i32 s77, s34, s71
	v_lshl_add_u64 v[192:193], s[16:17], 0, v[148:149]
	s_mov_b32 m0, s77
	ds_read_b128 v[200:203], v197 offset:16384
	ds_read_b128 v[204:207], v197 offset:17408
	ds_read_b128 v[208:211], v197 offset:18432
	ds_read_b128 v[212:215], v197 offset:19456
	ds_read_b128 v[216:219], v197 offset:20480
	ds_read_b128 v[220:223], v197 offset:21504
	ds_read_b128 v[224:227], v197 offset:22528
	ds_read_b128 v[228:231], v197 offset:23552
	global_load_lds_dwordx4 v[192:193], off
	s_add_i32 m0, s77, 0x2000
	s_add_u32 s86, s16, 0x40000
	v_lshl_add_u64 v[232:233], s[16:17], 0, v[152:153]
	s_addc_u32 s87, s17, 0
	s_add_i32 s77, s35, s71
	global_load_lds_dwordx4 v[232:233], off
	v_lshl_add_u64 v[234:235], s[86:87], 0, v[148:149]
	s_mov_b32 m0, s77
	v_lshl_add_u64 v[236:237], s[20:21], 0, v[150:151]
	global_load_lds_dwordx4 v[234:235], off
	v_lshl_add_u64 v[234:235], s[86:87], 0, v[152:153]
	s_add_i32 m0, s77, 0x2000
	s_nop 0
	global_load_lds_dwordx4 v[234:235], off
	v_lshl_add_u64 v[234:235], s[20:21], 0, v[146:147]
	s_mov_b32 m0, s73
	s_nop 0
	global_load_lds_dwordx4 v[234:235], off
	s_mov_b32 m0, s75
	s_nop 0
	global_load_lds_dwordx4 v[236:237], off
	s_waitcnt vmcnt(8)
	s_waitcnt lgkmcnt(0)
	s_setprio 1
	s_barrier
	v_mfma_f32_16x16x32_bf16 v[62:65], v[130:133], v[200:203], v[62:65]
	v_mfma_f32_16x16x32_bf16 v[58:61], v[138:141], v[200:203], v[58:61]
	v_mfma_f32_16x16x32_bf16 v[46:49], v[130:133], v[208:211], v[46:49]
	v_mfma_f32_16x16x32_bf16 v[42:45], v[138:141], v[208:211], v[42:45]
	v_mfma_f32_16x16x32_bf16 v[30:33], v[130:133], v[216:219], v[30:33]
	v_mfma_f32_16x16x32_bf16 v[26:29], v[138:141], v[216:219], v[26:29]
	v_mfma_f32_16x16x32_bf16 v[14:17], v[130:133], v[224:227], v[14:17]
	v_mfma_f32_16x16x32_bf16 v[10:13], v[138:141], v[224:227], v[10:13]
	v_mfma_f32_16x16x32_bf16 v[62:65], v[134:137], v[204:207], v[62:65]
	v_mfma_f32_16x16x32_bf16 v[58:61], v[142:145], v[204:207], v[58:61]
	v_mfma_f32_16x16x32_bf16 v[46:49], v[134:137], v[212:215], v[46:49]
	v_mfma_f32_16x16x32_bf16 v[42:45], v[142:145], v[212:215], v[42:45]
	v_mfma_f32_16x16x32_bf16 v[30:33], v[134:137], v[220:223], v[30:33]
	v_mfma_f32_16x16x32_bf16 v[26:29], v[142:145], v[220:223], v[26:29]
	v_mfma_f32_16x16x32_bf16 v[14:17], v[134:137], v[228:231], v[14:17]
	v_mfma_f32_16x16x32_bf16 v[10:13], v[142:145], v[228:231], v[10:13]
	s_setprio 0
	s_setprio 1
	v_mfma_f32_16x16x32_bf16 v[54:57], v[176:179], v[200:203], v[54:57]
	v_mfma_f32_16x16x32_bf16 v[50:53], v[184:187], v[200:203], v[50:53]
	v_mfma_f32_16x16x32_bf16 v[38:41], v[176:179], v[208:211], v[38:41]
	v_mfma_f32_16x16x32_bf16 v[34:37], v[184:187], v[208:211], v[34:37]
	v_mfma_f32_16x16x32_bf16 v[22:25], v[176:179], v[216:219], v[22:25]
	v_mfma_f32_16x16x32_bf16 v[18:21], v[184:187], v[216:219], v[18:21]
	v_mfma_f32_16x16x32_bf16 v[6:9], v[176:179], v[224:227], v[6:9]
	v_mfma_f32_16x16x32_bf16 v[2:5], v[184:187], v[224:227], v[2:5]
	v_mfma_f32_16x16x32_bf16 v[54:57], v[180:183], v[204:207], v[54:57]
	v_mfma_f32_16x16x32_bf16 v[50:53], v[188:191], v[204:207], v[50:53]
	v_mfma_f32_16x16x32_bf16 v[38:41], v[180:183], v[212:215], v[38:41]
	v_mfma_f32_16x16x32_bf16 v[34:37], v[188:191], v[212:215], v[34:37]
	v_mfma_f32_16x16x32_bf16 v[22:25], v[180:183], v[220:223], v[22:25]
	v_mfma_f32_16x16x32_bf16 v[18:21], v[188:191], v[220:223], v[18:21]
	v_mfma_f32_16x16x32_bf16 v[6:9], v[180:183], v[228:231], v[6:9]
	v_mfma_f32_16x16x32_bf16 v[2:5], v[188:191], v[228:231], v[2:5]
	s_barrier
	s_setprio 0
.Lpeel_mid_1093:
	s_add_i32 s77, 0, 0x18000
	s_add_i32 s79, 0, 0x1c000
	v_add_u32_e32 v142, s77, v194
	v_add_u32_e32 v154, s79, v194
	ds_read_b128 v[130:133], v142
	ds_read_b128 v[134:137], v142 offset:1024
	ds_read_b128 v[138:141], v142 offset:2048
	ds_read_b128 v[142:145], v142 offset:3072
	ds_read_b128 v[176:179], v154
	ds_read_b128 v[180:183], v154 offset:1024
	ds_read_b128 v[184:187], v154 offset:2048
	ds_read_b128 v[188:191], v154 offset:3072
	s_add_u32 s20, s20, 0x40000
	s_addc_u32 s21, s21, 0
	s_mov_b32 m0, s44
	v_lshl_add_u64 v[238:239], s[20:21], 0, v[146:147]
	ds_read_b128 v[200:203], v197 offset:32768
	ds_read_b128 v[204:207], v197 offset:33792
	ds_read_b128 v[208:211], v197 offset:34816
	ds_read_b128 v[212:215], v197 offset:35840
	ds_read_b128 v[216:219], v197 offset:36864
	ds_read_b128 v[220:223], v197 offset:37888
	ds_read_b128 v[224:227], v197 offset:38912
	ds_read_b128 v[228:231], v197 offset:39936
	global_load_lds_dwordx4 v[238:239], off
	v_lshl_add_u64 v[238:239], s[20:21], 0, v[150:151]
	s_mov_b32 m0, s45
	s_nop 0
	global_load_lds_dwordx4 v[238:239], off
	s_waitcnt vmcnt(8)
	s_waitcnt lgkmcnt(0)
	s_setprio 1
	s_barrier
; #define PG8_STAGE(bufoff, gbase, voff) do { _Pragma("unroll") for (int _i = 0; _i < 2; ++_i) \
;         __builtin_amdgcn_global_load_lds((const unsigned*)((const char*)(gbase) + (voff)[_i]), (PG8_LAS unsigned*)(lds + (bufoff) + ldsw + _i * 8192), 16, 0, 0); } while (0)
; #define PG8_LDA(dst, b, h) do { _Pragma("unroll") for (int m = 0; m < 4; ++m) _Pragma("unroll") for (int k = 0; k < 2; ++k) dst[m][k] = *(const PG8_LAS bf16x8*)(lds + PG8_SA(b, h) + aoff + m * 2048 + k * 1024); } while (0)
; #define PG8_MMA(ai, bj, At, Bt) do { __builtin_amdgcn_s_setprio(1); _Pragma("unroll") for (int m = 0; m < 4; ++m) _Pragma("unroll") for (int n = 0; n < 2; ++n) _Pragma("unroll") for (int k = 0; k < 2; ++k) \
;         acc[ai][bj][m][n] = __builtin_amdgcn_mfma_f32_16x16x32_bf16(Bt[n][k], At[m][k], acc[ai][bj][m][n], 0, 0, 0); __builtin_amdgcn_s_setprio(0); } while (0)
; #define PG8_WAIT_V(n) asm volatile("s_waitcnt vmcnt(" #n ")" ::: "memory")
; #define PG8_WAIT_L(n) asm volatile("s_waitcnt lgkmcnt(" #n ")" ::: "memory")
; #define PG8_BAR __builtin_amdgcn_s_barrier()
; #define PG8_SCHED __builtin_amdgcn_sched_barrier(0)
; template <class Epi, class Sched, bool ALIGN_EPI = false, bool SP2 = false, bool PAIR_ACC = false>
; __device__ __forceinline__ void gemm_phase(PG8_LAS unsigned char* lds, const Gemm g, const Sched& S, const Epi& E) {
;     ...
;             PG8_WAIT_V(8); PG8_WAIT_L(0); PG8_BAR; PG8_MMA(0, 0, At, B0); PG8_MMA(0, 1, At, B1); PG8_BAR; PG8_SCHED;
;             PG8_LDA(At, 1, 1); PG8_STAGE(PG8_SB(1, 0), b3, voffB); PG8_STAGE(PG8_SB(1, 1), b3 + hstep, voffB); PG8_STAGE(PG8_SA(1, 0), a3, voffA);
;             PG8_WAIT_V(8); PG8_WAIT_L(0); PG8_BAR; PG8_MMA(1, 0, At, B0); PG8_MMA(1, 1, At, B1); PG8_BAR; PG8_SCHED;
;     ...
;         if constexpr (ALIGN_EPI) { if (wr == 0) PG8_BAR; }
	v_mfma_f32_16x16x32_bf16 v[126:129], v[130:133], v[200:203], v[126:129]
	v_mfma_f32_16x16x32_bf16 v[122:125], v[138:141], v[200:203], v[122:125]
	v_mfma_f32_16x16x32_bf16 v[110:113], v[130:133], v[208:211], v[110:113]
	v_mfma_f32_16x16x32_bf16 v[106:109], v[138:141], v[208:211], v[106:109]
	v_mfma_f32_16x16x32_bf16 v[94:97], v[130:133], v[216:219], v[94:97]
	v_mfma_f32_16x16x32_bf16 v[90:93], v[138:141], v[216:219], v[90:93]
	v_mfma_f32_16x16x32_bf16 v[78:81], v[130:133], v[224:227], v[78:81]
	v_mfma_f32_16x16x32_bf16 v[74:77], v[138:141], v[224:227], v[74:77]
	v_mfma_f32_16x16x32_bf16 v[126:129], v[134:137], v[204:207], v[126:129]
	v_mfma_f32_16x16x32_bf16 v[122:125], v[142:145], v[204:207], v[122:125]
	v_mfma_f32_16x16x32_bf16 v[110:113], v[134:137], v[212:215], v[110:113]
	v_mfma_f32_16x16x32_bf16 v[106:109], v[142:145], v[212:215], v[106:109]
	v_mfma_f32_16x16x32_bf16 v[94:97], v[134:137], v[220:223], v[94:97]
	v_mfma_f32_16x16x32_bf16 v[90:93], v[142:145], v[220:223], v[90:93]
	v_mfma_f32_16x16x32_bf16 v[78:81], v[134:137], v[228:231], v[78:81]
	v_mfma_f32_16x16x32_bf16 v[74:77], v[142:145], v[228:231], v[74:77]
	s_setprio 0
	s_setprio 1
	v_mfma_f32_16x16x32_bf16 v[118:121], v[176:179], v[200:203], v[118:121]
	v_mfma_f32_16x16x32_bf16 v[114:117], v[184:187], v[200:203], v[114:117]
	v_mfma_f32_16x16x32_bf16 v[102:105], v[176:179], v[208:211], v[102:105]
	v_mfma_f32_16x16x32_bf16 v[98:101], v[184:187], v[208:211], v[98:101]
	v_mfma_f32_16x16x32_bf16 v[86:89], v[176:179], v[216:219], v[86:89]
	v_mfma_f32_16x16x32_bf16 v[82:85], v[184:187], v[216:219], v[82:85]
	v_mfma_f32_16x16x32_bf16 v[70:73], v[176:179], v[224:227], v[70:73]
	v_mfma_f32_16x16x32_bf16 v[66:69], v[184:187], v[224:227], v[66:69]
	v_mfma_f32_16x16x32_bf16 v[118:121], v[180:183], v[204:207], v[118:121]
	v_mfma_f32_16x16x32_bf16 v[114:117], v[188:191], v[204:207], v[114:117]
	v_mfma_f32_16x16x32_bf16 v[102:105], v[180:183], v[212:215], v[102:105]
	v_mfma_f32_16x16x32_bf16 v[98:101], v[188:191], v[212:215], v[98:101]
	v_mfma_f32_16x16x32_bf16 v[86:89], v[180:183], v[220:223], v[86:89]
	v_mfma_f32_16x16x32_bf16 v[82:85], v[188:191], v[220:223], v[82:85]
	v_mfma_f32_16x16x32_bf16 v[70:73], v[180:183], v[228:231], v[70:73]
	v_mfma_f32_16x16x32_bf16 v[66:69], v[188:191], v[228:231], v[66:69]
	s_barrier
	s_setprio 0
	s_add_i32 s20, s77, s71
	v_lshl_add_u64 v[192:193], v[192:193], 0, s[48:49]
	s_mov_b32 m0, s20
	ds_read_b128 v[200:203], v197 offset:49152
	ds_read_b128 v[204:207], v197 offset:50176
	ds_read_b128 v[208:211], v197 offset:51200
	ds_read_b128 v[212:215], v197 offset:52224
	ds_read_b128 v[216:219], v197 offset:53248
	ds_read_b128 v[220:223], v197 offset:54272
	ds_read_b128 v[224:227], v197 offset:55296
	ds_read_b128 v[228:231], v197 offset:56320
	global_load_lds_dwordx4 v[192:193], off
	s_add_i32 m0, s20, 0x2000
	s_add_u32 s16, s16, 0x40080
	v_lshl_add_u64 v[192:193], v[232:233], 0, s[48:49]
	s_addc_u32 s17, s17, 0
	s_add_i32 s20, s79, s71
	global_load_lds_dwordx4 v[192:193], off
	v_lshl_add_u64 v[192:193], s[16:17], 0, v[148:149]
	s_mov_b32 m0, s20
	s_nop 0
	global_load_lds_dwordx4 v[192:193], off
	v_lshl_add_u64 v[192:193], s[16:17], 0, v[152:153]
	s_add_i32 m0, s20, 0x2000
	s_nop 0
	global_load_lds_dwordx4 v[192:193], off
	v_lshl_add_u64 v[192:193], v[234:235], 0, s[48:49]
	s_mov_b32 m0, s36
	s_nop 0
	global_load_lds_dwordx4 v[192:193], off
	v_lshl_add_u64 v[192:193], v[236:237], 0, s[48:49]
	s_mov_b32 m0, s37
	s_nop 0
	global_load_lds_dwordx4 v[192:193], off
	s_waitcnt vmcnt(8)
	s_waitcnt lgkmcnt(0)
	s_setprio 1
	s_barrier
	v_mfma_f32_16x16x32_bf16 v[62:65], v[130:133], v[200:203], v[62:65]
	v_mfma_f32_16x16x32_bf16 v[58:61], v[138:141], v[200:203], v[58:61]
	v_mfma_f32_16x16x32_bf16 v[46:49], v[130:133], v[208:211], v[46:49]
	v_mfma_f32_16x16x32_bf16 v[42:45], v[138:141], v[208:211], v[42:45]
	v_mfma_f32_16x16x32_bf16 v[30:33], v[130:133], v[216:219], v[30:33]
	v_mfma_f32_16x16x32_bf16 v[26:29], v[138:141], v[216:219], v[26:29]
	v_mfma_f32_16x16x32_bf16 v[14:17], v[130:133], v[224:227], v[14:17]
	v_mfma_f32_16x16x32_bf16 v[10:13], v[138:141], v[224:227], v[10:13]
	v_mfma_f32_16x16x32_bf16 v[62:65], v[134:137], v[204:207], v[62:65]
	v_mfma_f32_16x16x32_bf16 v[58:61], v[142:145], v[204:207], v[58:61]
	v_mfma_f32_16x16x32_bf16 v[46:49], v[134:137], v[212:215], v[46:49]
	v_mfma_f32_16x16x32_bf16 v[42:45], v[142:145], v[212:215], v[42:45]
	v_mfma_f32_16x16x32_bf16 v[30:33], v[134:137], v[220:223], v[30:33]
	v_mfma_f32_16x16x32_bf16 v[26:29], v[142:145], v[220:223], v[26:29]
	v_mfma_f32_16x16x32_bf16 v[14:17], v[134:137], v[228:231], v[14:17]
	v_mfma_f32_16x16x32_bf16 v[10:13], v[142:145], v[228:231], v[10:13]
	s_setprio 0
	s_setprio 1
	v_mfma_f32_16x16x32_bf16 v[54:57], v[176:179], v[200:203], v[54:57]
	v_mfma_f32_16x16x32_bf16 v[50:53], v[184:187], v[200:203], v[50:53]
	v_mfma_f32_16x16x32_bf16 v[38:41], v[176:179], v[208:211], v[38:41]
	v_mfma_f32_16x16x32_bf16 v[34:37], v[184:187], v[208:211], v[34:37]
	v_mfma_f32_16x16x32_bf16 v[22:25], v[176:179], v[216:219], v[22:25]
	v_mfma_f32_16x16x32_bf16 v[18:21], v[184:187], v[216:219], v[18:21]
	v_mfma_f32_16x16x32_bf16 v[6:9], v[176:179], v[224:227], v[6:9]
	v_mfma_f32_16x16x32_bf16 v[2:5], v[184:187], v[224:227], v[2:5]
	v_mfma_f32_16x16x32_bf16 v[54:57], v[180:183], v[204:207], v[54:57]
	v_mfma_f32_16x16x32_bf16 v[50:53], v[188:191], v[204:207], v[50:53]
	v_mfma_f32_16x16x32_bf16 v[38:41], v[180:183], v[212:215], v[38:41]
	v_mfma_f32_16x16x32_bf16 v[34:37], v[188:191], v[212:215], v[34:37]
	v_mfma_f32_16x16x32_bf16 v[22:25], v[180:183], v[220:223], v[22:25]
	v_mfma_f32_16x16x32_bf16 v[18:21], v[188:191], v[220:223], v[18:21]
	v_mfma_f32_16x16x32_bf16 v[6:9], v[180:183], v[228:231], v[6:9]
	v_mfma_f32_16x16x32_bf16 v[2:5], v[188:191], v[228:231], v[2:5]
	s_barrier
	s_setprio 0
	s_add_i32 s43, s43, 2
	s_add_u32 s12, s12, 0x100
	s_addc_u32 s13, s13, 0
	s_add_u32 s30, s30, 0x100
	s_addc_u32 s42, s42, 0
	s_cmp_gt_u32 s43, 13
	s_cbranch_scc0 .LBB0_1093
	s_and_b64 vcc, exec, s[50:51]
	s_cbranch_vccz .LBB0_1096
	s_barrier

; #define PG8_STAGE(bufoff, gbase, voff) do { _Pragma("unroll") for (int _i = 0; _i < 2; ++_i) \
;         __builtin_amdgcn_global_load_lds((const unsigned*)((const char*)(gbase) + (voff)[_i]), (PG8_LAS unsigned*)(lds + (bufoff) + ldsw + _i * 8192), 16, 0, 0); } while (0)
; #define PG8_LDA(dst, b, h) do { _Pragma("unroll") for (int m = 0; m < 4; ++m) _Pragma("unroll") for (int k = 0; k < 2; ++k) dst[m][k] = *(const PG8_LAS bf16x8*)(lds + PG8_SA(b, h) + aoff + m * 2048 + k * 1024); } while (0)
; #define PG8_LDB(dst, b, h) do { _Pragma("unroll") for (int n = 0; n < 2; ++n) _Pragma("unroll") for (int k = 0; k < 2; ++k) dst[n][k] = *(const PG8_LAS bf16x8*)(lds + PG8_SB(b, h) + boff + n * 2048 + k * 1024); } while (0)
; #define PG8_MMA(ai, bj, At, Bt) do { __builtin_amdgcn_s_setprio(1); _Pragma("unroll") for (int m = 0; m < 4; ++m) _Pragma("unroll") for (int n = 0; n < 2; ++n) _Pragma("unroll") for (int k = 0; k < 2; ++k) \
;         acc[ai][bj][m][n] = __builtin_amdgcn_mfma_f32_16x16x32_bf16(Bt[n][k], At[m][k], acc[ai][bj][m][n], 0, 0, 0); __builtin_amdgcn_s_setprio(0); } while (0)
; #define PG8_WAIT_V(n) asm volatile("s_waitcnt vmcnt(" #n ")" ::: "memory")
; #define PG8_WAIT_L(n) asm volatile("s_waitcnt lgkmcnt(" #n ")" ::: "memory")
; template <class Epi, class Sched, bool ALIGN_EPI = false, bool SP2 = false, bool PAIR_ACC = false>
; __device__ __forceinline__ void gemm_phase(PG8_LAS unsigned char* lds, const Gemm g, const Sched& S, const Epi& E) {
;     ...
;             const bool last = (t == nt - 2);
;             const char* a1 = cA + (size_t)(t + 1) * kstep;
;             const char* a2 = last ? nA : cA + (size_t)(t + 2) * kstep; const char* b2 = last ? nB : cB + (size_t)(t + 2) * kstep;
;             const char* a3 = a2 + kstep; const char* b3 = b2 + kstep;
;             if (last && has_next) S.a_ready(nxt);
;             if constexpr (SP2) {
;             PG8_LDB(B0, 0, 0); PG8_LDB(B1, 0, 1); PG8_SCHED; PG8_LDA(At, 0, 0); PG8_STAGE(PG8_SA(1, 1), a1 + hstep, voffA);
;             PG8_WAIT_V(8); PG8_WAIT_L(0); PG8_BAR; PG8_MMA(0, 0, At, B0); PG8_MMA(0, 1, At, B1); PG8_BAR; PG8_SCHED;
;             PG8_LDA(At, 0, 1); PG8_STAGE(PG8_SB(0, 0), b2, voffB); PG8_STAGE(PG8_SB(0, 1), b2 + hstep, voffB); PG8_STAGE(PG8_SA(0, 0), a2, voffA);
;             PG8_WAIT_V(8); PG8_WAIT_L(0); PG8_BAR; PG8_MMA(1, 0, At, B0); PG8_MMA(1, 1, At, B1); PG8_BAR; PG8_SCHED;
.LBB0_1488:
	v_add_u32_e32 v142, s51, v199
	v_add_u32_e32 v166, s52, v199
	ds_read_b128 v[130:133], v142
	ds_read_b128 v[134:137], v142 offset:1024
	ds_read_b128 v[138:141], v142 offset:2048
	ds_read_b128 v[142:145], v142 offset:3072
	ds_read_b128 v[146:149], v166
	ds_read_b128 v[150:153], v166 offset:1024
	ds_read_b128 v[154:157], v166 offset:2048
	ds_read_b128 v[176:179], v166 offset:3072
	s_add_u32 s46, s8, 0xfffc0080
	s_addc_u32 s47, s9, -1
	s_cmp_eq_u32 s54, 12
	s_cselect_b32 s49, s31, s47
	s_cselect_b32 s48, s30, s46
	s_cselect_b32 s47, s23, s53
	s_cselect_b32 s46, s29, s41
	v_lshl_add_u64 v[196:197], s[8:9], 0, v[168:169]
	s_add_i32 m0, s35, 0xc000
	ds_read_b128 v[180:183], v201
	ds_read_b128 v[184:187], v201 offset:1024
	ds_read_b128 v[188:191], v201 offset:2048
	ds_read_b128 v[192:195], v201 offset:3072
	ds_read_b128 v[202:205], v201 offset:4096
	ds_read_b128 v[206:209], v201 offset:5120
	ds_read_b128 v[210:213], v201 offset:6144
	ds_read_b128 v[214:217], v201 offset:7168
	global_load_lds_dwordx4 v[196:197], off
	v_lshl_add_u64 v[196:197], s[8:9], 0, v[170:171]
	s_add_i32 m0, s35, 0xe000
	s_nop 0
	global_load_lds_dwordx4 v[196:197], off
	s_waitcnt vmcnt(8)
	s_waitcnt lgkmcnt(0)
	s_setprio 1
	s_barrier
	v_mfma_f32_16x16x32_bf16 v[126:129], v[130:133], v[180:183], v[126:129]
	v_mfma_f32_16x16x32_bf16 v[122:125], v[138:141], v[180:183], v[122:125]
	v_mfma_f32_16x16x32_bf16 v[118:121], v[130:133], v[188:191], v[118:121]
	v_mfma_f32_16x16x32_bf16 v[114:117], v[138:141], v[188:191], v[114:117]
	v_mfma_f32_16x16x32_bf16 v[110:113], v[130:133], v[202:205], v[110:113]
	v_mfma_f32_16x16x32_bf16 v[106:109], v[138:141], v[202:205], v[106:109]
	v_mfma_f32_16x16x32_bf16 v[102:105], v[130:133], v[210:213], v[102:105]
	v_mfma_f32_16x16x32_bf16 v[98:101], v[138:141], v[210:213], v[98:101]
	v_mfma_f32_16x16x32_bf16 v[126:129], v[134:137], v[184:187], v[126:129]
	v_mfma_f32_16x16x32_bf16 v[122:125], v[142:145], v[184:187], v[122:125]
	v_mfma_f32_16x16x32_bf16 v[118:121], v[134:137], v[192:195], v[118:121]
	v_mfma_f32_16x16x32_bf16 v[114:117], v[142:145], v[192:195], v[114:117]
	v_mfma_f32_16x16x32_bf16 v[110:113], v[134:137], v[206:209], v[110:113]
	v_mfma_f32_16x16x32_bf16 v[106:109], v[142:145], v[206:209], v[106:109]
	v_mfma_f32_16x16x32_bf16 v[102:105], v[134:137], v[214:217], v[102:105]
	v_mfma_f32_16x16x32_bf16 v[98:101], v[142:145], v[214:217], v[98:101]
	s_setprio 0
	s_setprio 1
	v_mfma_f32_16x16x32_bf16 v[94:97], v[146:149], v[180:183], v[94:97]
	v_mfma_f32_16x16x32_bf16 v[90:93], v[154:157], v[180:183], v[90:93]
	v_mfma_f32_16x16x32_bf16 v[86:89], v[146:149], v[188:191], v[86:89]
	v_mfma_f32_16x16x32_bf16 v[82:85], v[154:157], v[188:191], v[82:85]
	v_mfma_f32_16x16x32_bf16 v[78:81], v[146:149], v[202:205], v[78:81]
	v_mfma_f32_16x16x32_bf16 v[74:77], v[154:157], v[202:205], v[74:77]
	v_mfma_f32_16x16x32_bf16 v[70:73], v[146:149], v[210:213], v[70:73]
	v_mfma_f32_16x16x32_bf16 v[66:69], v[154:157], v[210:213], v[66:69]
	v_mfma_f32_16x16x32_bf16 v[94:97], v[150:153], v[184:187], v[94:97]
	v_mfma_f32_16x16x32_bf16 v[90:93], v[176:179], v[184:187], v[90:93]
	v_mfma_f32_16x16x32_bf16 v[86:89], v[150:153], v[192:195], v[86:89]
	v_mfma_f32_16x16x32_bf16 v[82:85], v[176:179], v[192:195], v[82:85]
	v_mfma_f32_16x16x32_bf16 v[78:81], v[150:153], v[206:209], v[78:81]
	v_mfma_f32_16x16x32_bf16 v[74:77], v[176:179], v[206:209], v[74:77]
	v_mfma_f32_16x16x32_bf16 v[70:73], v[150:153], v[214:217], v[70:73]
	v_mfma_f32_16x16x32_bf16 v[66:69], v[176:179], v[214:217], v[66:69]
	s_barrier
	s_setprio 0
	s_add_i32 s55, s51, s34
	v_lshl_add_u64 v[196:197], s[46:47], 0, v[160:161]
	s_mov_b32 m0, s55
	ds_read_b128 v[180:183], v201 offset:16384
	ds_read_b128 v[184:187], v201 offset:17408
	ds_read_b128 v[188:191], v201 offset:18432
	ds_read_b128 v[192:195], v201 offset:19456
	ds_read_b128 v[202:205], v201 offset:20480
	ds_read_b128 v[206:209], v201 offset:21504
	ds_read_b128 v[210:213], v201 offset:22528
	ds_read_b128 v[214:217], v201 offset:23552
	global_load_lds_dwordx4 v[196:197], off
	s_add_i32 m0, s55, 0x2000
	s_add_u32 s56, s46, 0x40000
	v_lshl_add_u64 v[218:219], s[46:47], 0, v[164:165]
	s_addc_u32 s57, s47, 0
	s_add_i32 s55, s52, s34
	global_load_lds_dwordx4 v[218:219], off
	v_lshl_add_u64 v[220:221], s[56:57], 0, v[160:161]
	s_mov_b32 m0, s55
	v_lshl_add_u64 v[222:223], s[48:49], 0, v[162:163]
	global_load_lds_dwordx4 v[220:221], off
	v_lshl_add_u64 v[220:221], s[56:57], 0, v[164:165]
	s_add_i32 m0, s55, 0x2000
	s_nop 0
	global_load_lds_dwordx4 v[220:221], off
	v_lshl_add_u64 v[220:221], s[48:49], 0, v[158:159]
	s_mov_b32 m0, s35
	s_nop 0
	global_load_lds_dwordx4 v[220:221], off
	s_mov_b32 m0, s36
	s_nop 0
	global_load_lds_dwordx4 v[222:223], off
	s_waitcnt vmcnt(8)
	s_waitcnt lgkmcnt(0)
	s_setprio 1
	s_barrier
; #define PG8_STAGE(bufoff, gbase, voff) do { _Pragma("unroll") for (int _i = 0; _i < 2; ++_i) \
;         __builtin_amdgcn_global_load_lds((const unsigned*)((const char*)(gbase) + (voff)[_i]), (PG8_LAS unsigned*)(lds + (bufoff) + ldsw + _i * 8192), 16, 0, 0); } while (0)
; #define PG8_LDA(dst, b, h) do { _Pragma("unroll") for (int m = 0; m < 4; ++m) _Pragma("unroll") for (int k = 0; k < 2; ++k) dst[m][k] = *(const PG8_LAS bf16x8*)(lds + PG8_SA(b, h) + aoff + m * 2048 + k * 1024); } while (0)
; #define PG8_LDB(dst, b, h) do { _Pragma("unroll") for (int n = 0; n < 2; ++n) _Pragma("unroll") for (int k = 0; k < 2; ++k) dst[n][k] = *(const PG8_LAS bf16x8*)(lds + PG8_SB(b, h) + boff + n * 2048 + k * 1024); } while (0)
; #define PG8_MMA(ai, bj, At, Bt) do { __builtin_amdgcn_s_setprio(1); _Pragma("unroll") for (int m = 0; m < 4; ++m) _Pragma("unroll") for (int n = 0; n < 2; ++n) _Pragma("unroll") for (int k = 0; k < 2; ++k) \
;         acc[ai][bj][m][n] = __builtin_amdgcn_mfma_f32_16x16x32_bf16(Bt[n][k], At[m][k], acc[ai][bj][m][n], 0, 0, 0); __builtin_amdgcn_s_setprio(0); } while (0)
; #define PG8_WAIT_V(n) asm volatile("s_waitcnt vmcnt(" #n ")" ::: "memory")
; #define PG8_WAIT_L(n) asm volatile("s_waitcnt lgkmcnt(" #n ")" ::: "memory")
; #define PG8_BAR __builtin_amdgcn_s_barrier()
; #define PG8_SCHED __builtin_amdgcn_sched_barrier(0)
; template <class Epi, class Sched, bool ALIGN_EPI = false, bool SP2 = false, bool PAIR_ACC = false>
; __device__ __forceinline__ void gemm_phase(PG8_LAS unsigned char* lds, const Gemm g, const Sched& S, const Epi& E) {
;     ...
;             PG8_WAIT_V(8); PG8_WAIT_L(0); PG8_BAR; PG8_MMA(1, 0, At, B0); PG8_MMA(1, 1, At, B1); PG8_BAR; PG8_SCHED;
;             PG8_LDB(B0, 1, 0); PG8_LDB(B1, 1, 1); PG8_SCHED; PG8_LDA(At, 1, 0); PG8_STAGE(PG8_SA(0, 1), a2 + hstep, voffA);
;             PG8_WAIT_V(8); PG8_WAIT_L(0); PG8_BAR; PG8_MMA(0, 0, At, B0); PG8_MMA(0, 1, At, B1); PG8_BAR; PG8_SCHED;
	v_mfma_f32_16x16x32_bf16 v[62:65], v[130:133], v[180:183], v[62:65]
	v_mfma_f32_16x16x32_bf16 v[58:61], v[138:141], v[180:183], v[58:61]
	v_mfma_f32_16x16x32_bf16 v[54:57], v[130:133], v[188:191], v[54:57]
	v_mfma_f32_16x16x32_bf16 v[50:53], v[138:141], v[188:191], v[50:53]
	v_mfma_f32_16x16x32_bf16 v[46:49], v[130:133], v[202:205], v[46:49]
	v_mfma_f32_16x16x32_bf16 v[42:45], v[138:141], v[202:205], v[42:45]
	v_mfma_f32_16x16x32_bf16 v[38:41], v[130:133], v[210:213], v[38:41]
	v_mfma_f32_16x16x32_bf16 v[34:37], v[138:141], v[210:213], v[34:37]
	v_mfma_f32_16x16x32_bf16 v[62:65], v[134:137], v[184:187], v[62:65]
	v_mfma_f32_16x16x32_bf16 v[58:61], v[142:145], v[184:187], v[58:61]
	v_mfma_f32_16x16x32_bf16 v[54:57], v[134:137], v[192:195], v[54:57]
	v_mfma_f32_16x16x32_bf16 v[50:53], v[142:145], v[192:195], v[50:53]
	v_mfma_f32_16x16x32_bf16 v[46:49], v[134:137], v[206:209], v[46:49]
	v_mfma_f32_16x16x32_bf16 v[42:45], v[142:145], v[206:209], v[42:45]
	v_mfma_f32_16x16x32_bf16 v[38:41], v[134:137], v[214:217], v[38:41]
	v_mfma_f32_16x16x32_bf16 v[34:37], v[142:145], v[214:217], v[34:37]
	s_setprio 0
	s_setprio 1
	v_mfma_f32_16x16x32_bf16 v[30:33], v[146:149], v[180:183], v[30:33]
	v_mfma_f32_16x16x32_bf16 v[26:29], v[154:157], v[180:183], v[26:29]
	v_mfma_f32_16x16x32_bf16 v[22:25], v[146:149], v[188:191], v[22:25]
	v_mfma_f32_16x16x32_bf16 v[18:21], v[154:157], v[188:191], v[18:21]
	v_mfma_f32_16x16x32_bf16 v[14:17], v[146:149], v[202:205], v[14:17]
	v_mfma_f32_16x16x32_bf16 v[10:13], v[154:157], v[202:205], v[10:13]
	v_mfma_f32_16x16x32_bf16 v[6:9], v[146:149], v[210:213], v[6:9]
	v_mfma_f32_16x16x32_bf16 v[2:5], v[154:157], v[210:213], v[2:5]
	v_mfma_f32_16x16x32_bf16 v[30:33], v[150:153], v[184:187], v[30:33]
	v_mfma_f32_16x16x32_bf16 v[26:29], v[176:179], v[184:187], v[26:29]
	v_mfma_f32_16x16x32_bf16 v[22:25], v[150:153], v[192:195], v[22:25]
	v_mfma_f32_16x16x32_bf16 v[18:21], v[176:179], v[192:195], v[18:21]
	v_mfma_f32_16x16x32_bf16 v[14:17], v[150:153], v[206:209], v[14:17]
	v_mfma_f32_16x16x32_bf16 v[10:13], v[176:179], v[206:209], v[10:13]
	v_mfma_f32_16x16x32_bf16 v[6:9], v[150:153], v[214:217], v[6:9]
	v_mfma_f32_16x16x32_bf16 v[2:5], v[176:179], v[214:217], v[2:5]
	s_barrier
	s_setprio 0
	s_add_i32 s55, 0, 0x18000
	s_add_i32 s56, 0, 0x1c000
	v_add_u32_e32 v142, s55, v199
	v_add_u32_e32 v166, s56, v199
	ds_read_b128 v[130:133], v142
	ds_read_b128 v[134:137], v142 offset:1024
	ds_read_b128 v[138:141], v142 offset:2048
	ds_read_b128 v[142:145], v142 offset:3072
	ds_read_b128 v[146:149], v166
	ds_read_b128 v[150:153], v166 offset:1024
	ds_read_b128 v[154:157], v166 offset:2048
	ds_read_b128 v[176:179], v166 offset:3072
	s_add_u32 s48, s48, 0x40000
	s_addc_u32 s49, s49, 0
	s_mov_b32 m0, s37
	v_lshl_add_u64 v[224:225], s[48:49], 0, v[158:159]
	ds_read_b128 v[180:183], v201 offset:32768
	ds_read_b128 v[184:187], v201 offset:33792
	ds_read_b128 v[188:191], v201 offset:34816
	ds_read_b128 v[192:195], v201 offset:35840
	ds_read_b128 v[202:205], v201 offset:36864
	ds_read_b128 v[206:209], v201 offset:37888
	ds_read_b128 v[210:213], v201 offset:38912
	ds_read_b128 v[214:217], v201 offset:39936
	global_load_lds_dwordx4 v[224:225], off
	v_lshl_add_u64 v[224:225], s[48:49], 0, v[162:163]
	s_mov_b32 m0, s42
	s_nop 0
	global_load_lds_dwordx4 v[224:225], off
	s_waitcnt vmcnt(8)
	s_waitcnt lgkmcnt(0)
	s_setprio 1
	s_barrier
	v_mfma_f32_16x16x32_bf16 v[126:129], v[130:133], v[180:183], v[126:129]
	v_mfma_f32_16x16x32_bf16 v[122:125], v[138:141], v[180:183], v[122:125]
	v_mfma_f32_16x16x32_bf16 v[118:121], v[130:133], v[188:191], v[118:121]
	v_mfma_f32_16x16x32_bf16 v[114:117], v[138:141], v[188:191], v[114:117]
	v_mfma_f32_16x16x32_bf16 v[110:113], v[130:133], v[202:205], v[110:113]
	v_mfma_f32_16x16x32_bf16 v[106:109], v[138:141], v[202:205], v[106:109]
	v_mfma_f32_16x16x32_bf16 v[102:105], v[130:133], v[210:213], v[102:105]
	v_mfma_f32_16x16x32_bf16 v[98:101], v[138:141], v[210:213], v[98:101]
	v_mfma_f32_16x16x32_bf16 v[126:129], v[134:137], v[184:187], v[126:129]
	v_mfma_f32_16x16x32_bf16 v[122:125], v[142:145], v[184:187], v[122:125]
	v_mfma_f32_16x16x32_bf16 v[118:121], v[134:137], v[192:195], v[118:121]
	v_mfma_f32_16x16x32_bf16 v[114:117], v[142:145], v[192:195], v[114:117]
	v_mfma_f32_16x16x32_bf16 v[110:113], v[134:137], v[206:209], v[110:113]
	v_mfma_f32_16x16x32_bf16 v[106:109], v[142:145], v[206:209], v[106:109]
	v_mfma_f32_16x16x32_bf16 v[102:105], v[134:137], v[214:217], v[102:105]
	v_mfma_f32_16x16x32_bf16 v[98:101], v[142:145], v[214:217], v[98:101]
	s_setprio 0
	s_setprio 1
	v_mfma_f32_16x16x32_bf16 v[94:97], v[146:149], v[180:183], v[94:97]
	v_mfma_f32_16x16x32_bf16 v[90:93], v[154:157], v[180:183], v[90:93]
	v_mfma_f32_16x16x32_bf16 v[86:89], v[146:149], v[188:191], v[86:89]
	v_mfma_f32_16x16x32_bf16 v[82:85], v[154:157], v[188:191], v[82:85]
	v_mfma_f32_16x16x32_bf16 v[78:81], v[146:149], v[202:205], v[78:81]
	v_mfma_f32_16x16x32_bf16 v[74:77], v[154:157], v[202:205], v[74:77]
	v_mfma_f32_16x16x32_bf16 v[70:73], v[146:149], v[210:213], v[70:73]
	v_mfma_f32_16x16x32_bf16 v[66:69], v[154:157], v[210:213], v[66:69]
	v_mfma_f32_16x16x32_bf16 v[94:97], v[150:153], v[184:187], v[94:97]
	v_mfma_f32_16x16x32_bf16 v[90:93], v[176:179], v[184:187], v[90:93]
	v_mfma_f32_16x16x32_bf16 v[86:89], v[150:153], v[192:195], v[86:89]
	v_mfma_f32_16x16x32_bf16 v[82:85], v[176:179], v[192:195], v[82:85]
	v_mfma_f32_16x16x32_bf16 v[78:81], v[150:153], v[206:209], v[78:81]
	v_mfma_f32_16x16x32_bf16 v[74:77], v[176:179], v[206:209], v[74:77]
	v_mfma_f32_16x16x32_bf16 v[70:73], v[150:153], v[214:217], v[70:73]
	v_mfma_f32_16x16x32_bf16 v[66:69], v[176:179], v[214:217], v[66:69]
	s_barrier
; #define PG8_STAGE(bufoff, gbase, voff) do { _Pragma("unroll") for (int _i = 0; _i < 2; ++_i) \
;         __builtin_amdgcn_global_load_lds((const unsigned*)((const char*)(gbase) + (voff)[_i]), (PG8_LAS unsigned*)(lds + (bufoff) + ldsw + _i * 8192), 16, 0, 0); } while (0)
; #define PG8_LDA(dst, b, h) do { _Pragma("unroll") for (int m = 0; m < 4; ++m) _Pragma("unroll") for (int k = 0; k < 2; ++k) dst[m][k] = *(const PG8_LAS bf16x8*)(lds + PG8_SA(b, h) + aoff + m * 2048 + k * 1024); } while (0)
; #define PG8_MMA(ai, bj, At, Bt) do { __builtin_amdgcn_s_setprio(1); _Pragma("unroll") for (int m = 0; m < 4; ++m) _Pragma("unroll") for (int n = 0; n < 2; ++n) _Pragma("unroll") for (int k = 0; k < 2; ++k) \
;         acc[ai][bj][m][n] = __builtin_amdgcn_mfma_f32_16x16x32_bf16(Bt[n][k], At[m][k], acc[ai][bj][m][n], 0, 0, 0); __builtin_amdgcn_s_setprio(0); } while (0)
; #define PG8_WAIT_V(n) asm volatile("s_waitcnt vmcnt(" #n ")" ::: "memory")
; #define PG8_WAIT_L(n) asm volatile("s_waitcnt lgkmcnt(" #n ")" ::: "memory")
; #define PG8_BAR __builtin_amdgcn_s_barrier()
; #define PG8_SCHED __builtin_amdgcn_sched_barrier(0)
; template <class Epi, class Sched, bool ALIGN_EPI = false, bool SP2 = false, bool PAIR_ACC = false>
; __device__ __forceinline__ void gemm_phase(PG8_LAS unsigned char* lds, const Gemm g, const Sched& S, const Epi& E) {
;     ...
;             PG8_LDA(At, 1, 1); PG8_STAGE(PG8_SB(1, 0), b3, voffB); PG8_STAGE(PG8_SB(1, 1), b3 + hstep, voffB); PG8_STAGE(PG8_SA(1, 0), a3, voffA);
;             PG8_WAIT_V(8); PG8_WAIT_L(0); PG8_BAR; PG8_MMA(1, 0, At, B0); PG8_MMA(1, 1, At, B1); PG8_BAR; PG8_SCHED;
;     ...
;         if constexpr (ALIGN_EPI) { if (wr == 0) PG8_BAR; }
	s_setprio 0
	s_add_i32 s48, s55, s34
	v_lshl_add_u64 v[196:197], v[196:197], 0, s[18:19]
	s_mov_b32 m0, s48
	ds_read_b128 v[180:183], v201 offset:49152
	ds_read_b128 v[184:187], v201 offset:50176
	ds_read_b128 v[188:191], v201 offset:51200
	ds_read_b128 v[192:195], v201 offset:52224
	ds_read_b128 v[202:205], v201 offset:53248
	ds_read_b128 v[206:209], v201 offset:54272
	ds_read_b128 v[210:213], v201 offset:55296
	ds_read_b128 v[214:217], v201 offset:56320
	global_load_lds_dwordx4 v[196:197], off
	s_add_i32 m0, s48, 0x2000
	s_add_u32 s46, s46, 0x40080
	v_lshl_add_u64 v[196:197], v[218:219], 0, s[18:19]
	s_addc_u32 s47, s47, 0
	s_add_i32 s48, s56, s34
	global_load_lds_dwordx4 v[196:197], off
	v_lshl_add_u64 v[196:197], s[46:47], 0, v[160:161]
	s_mov_b32 m0, s48
	s_nop 0
	global_load_lds_dwordx4 v[196:197], off
	v_lshl_add_u64 v[196:197], s[46:47], 0, v[164:165]
	s_add_i32 m0, s48, 0x2000
	s_nop 0
	global_load_lds_dwordx4 v[196:197], off
	v_lshl_add_u64 v[196:197], v[220:221], 0, s[18:19]
	s_mov_b32 m0, s45
	s_nop 0
	global_load_lds_dwordx4 v[196:197], off
	v_lshl_add_u64 v[196:197], v[222:223], 0, s[18:19]
	s_mov_b32 m0, s50
	s_nop 0
	global_load_lds_dwordx4 v[196:197], off
	s_waitcnt vmcnt(8)
	s_waitcnt lgkmcnt(0)
	s_setprio 1
	s_barrier
	v_mfma_f32_16x16x32_bf16 v[62:65], v[130:133], v[180:183], v[62:65]
	v_mfma_f32_16x16x32_bf16 v[58:61], v[138:141], v[180:183], v[58:61]
	v_mfma_f32_16x16x32_bf16 v[54:57], v[130:133], v[188:191], v[54:57]
	v_mfma_f32_16x16x32_bf16 v[50:53], v[138:141], v[188:191], v[50:53]
	v_mfma_f32_16x16x32_bf16 v[46:49], v[130:133], v[202:205], v[46:49]
	v_mfma_f32_16x16x32_bf16 v[42:45], v[138:141], v[202:205], v[42:45]
	v_mfma_f32_16x16x32_bf16 v[38:41], v[130:133], v[210:213], v[38:41]
	v_mfma_f32_16x16x32_bf16 v[34:37], v[138:141], v[210:213], v[34:37]
	v_mfma_f32_16x16x32_bf16 v[62:65], v[134:137], v[184:187], v[62:65]
	v_mfma_f32_16x16x32_bf16 v[58:61], v[142:145], v[184:187], v[58:61]
	v_mfma_f32_16x16x32_bf16 v[54:57], v[134:137], v[192:195], v[54:57]
	v_mfma_f32_16x16x32_bf16 v[50:53], v[142:145], v[192:195], v[50:53]
	v_mfma_f32_16x16x32_bf16 v[46:49], v[134:137], v[206:209], v[46:49]
	v_mfma_f32_16x16x32_bf16 v[42:45], v[142:145], v[206:209], v[42:45]
	v_mfma_f32_16x16x32_bf16 v[38:41], v[134:137], v[214:217], v[38:41]
	v_mfma_f32_16x16x32_bf16 v[34:37], v[142:145], v[214:217], v[34:37]
	s_setprio 0
	s_setprio 1
	v_mfma_f32_16x16x32_bf16 v[30:33], v[146:149], v[180:183], v[30:33]
	v_mfma_f32_16x16x32_bf16 v[26:29], v[154:157], v[180:183], v[26:29]
	v_mfma_f32_16x16x32_bf16 v[22:25], v[146:149], v[188:191], v[22:25]
	v_mfma_f32_16x16x32_bf16 v[18:21], v[154:157], v[188:191], v[18:21]
	v_mfma_f32_16x16x32_bf16 v[14:17], v[146:149], v[202:205], v[14:17]
	v_mfma_f32_16x16x32_bf16 v[10:13], v[154:157], v[202:205], v[10:13]
	v_mfma_f32_16x16x32_bf16 v[6:9], v[146:149], v[210:213], v[6:9]
	v_mfma_f32_16x16x32_bf16 v[2:5], v[154:157], v[210:213], v[2:5]
	v_mfma_f32_16x16x32_bf16 v[30:33], v[150:153], v[184:187], v[30:33]
	v_mfma_f32_16x16x32_bf16 v[26:29], v[176:179], v[184:187], v[26:29]
	v_mfma_f32_16x16x32_bf16 v[22:25], v[150:153], v[192:195], v[22:25]
	v_mfma_f32_16x16x32_bf16 v[18:21], v[176:179], v[192:195], v[18:21]
	v_mfma_f32_16x16x32_bf16 v[14:17], v[150:153], v[206:209], v[14:17]
	v_mfma_f32_16x16x32_bf16 v[10:13], v[176:179], v[206:209], v[10:13]
	v_mfma_f32_16x16x32_bf16 v[6:9], v[150:153], v[214:217], v[6:9]
	v_mfma_f32_16x16x32_bf16 v[2:5], v[176:179], v[214:217], v[2:5]
	s_barrier
	s_setprio 0
	s_add_i32 s54, s54, 2
	s_add_u32 s8, s8, 0x100
	s_addc_u32 s9, s9, 0
	s_add_u32 s41, s41, 0x100
	s_addc_u32 s53, s53, 0
	s_cmp_gt_u32 s54, 13
	s_cbranch_scc0 .LBB0_1488
	s_and_b64 vcc, exec, s[20:21]
	s_cbranch_vccz .LBB0_1491
	s_barrier

; #define PG8_STAGE(bufoff, gbase, voff) do { _Pragma("unroll") for (int _i = 0; _i < 2; ++_i) \
;         __builtin_amdgcn_global_load_lds((const unsigned*)((const char*)(gbase) + (voff)[_i]), (PG8_LAS unsigned*)(lds + (bufoff) + ldsw + _i * 8192), 16, 0, 0); } while (0)
; #define PG8_LDA(dst, b, h) do { _Pragma("unroll") for (int m = 0; m < 4; ++m) _Pragma("unroll") for (int k = 0; k < 2; ++k) dst[m][k] = *(const PG8_LAS bf16x8*)(lds + PG8_SA(b, h) + aoff + m * 2048 + k * 1024); } while (0)
; #define PG8_LDB(dst, b, h) do { _Pragma("unroll") for (int n = 0; n < 2; ++n) _Pragma("unroll") for (int k = 0; k < 2; ++k) dst[n][k] = *(const PG8_LAS bf16x8*)(lds + PG8_SB(b, h) + boff + n * 2048 + k * 1024); } while (0)
; #define PG8_MMA(ai, bj, At, Bt) do { __builtin_amdgcn_s_setprio(1); _Pragma("unroll") for (int m = 0; m < 4; ++m) _Pragma("unroll") for (int n = 0; n < 2; ++n) _Pragma("unroll") for (int k = 0; k < 2; ++k) \
;         acc[ai][bj][m][n] = __builtin_amdgcn_mfma_f32_16x16x32_bf16(Bt[n][k], At[m][k], acc[ai][bj][m][n], 0, 0, 0); __builtin_amdgcn_s_setprio(0); } while (0)
; #define PG8_WAIT_V(n) asm volatile("s_waitcnt vmcnt(" #n ")" ::: "memory")
; #define PG8_WAIT_L(n) asm volatile("s_waitcnt lgkmcnt(" #n ")" ::: "memory")
; template <class Epi, class Sched, bool ALIGN_EPI = false, bool SP2 = false, bool PAIR_ACC = false>
; __device__ __forceinline__ void gemm_phase(PG8_LAS unsigned char* lds, const Gemm g, const Sched& S, const Epi& E) {
;     ...
;             const bool last = (t == nt - 2);
;             const char* a1 = cA + (size_t)(t + 1) * kstep;
;             const char* a2 = last ? nA : cA + (size_t)(t + 2) * kstep; const char* b2 = last ? nB : cB + (size_t)(t + 2) * kstep;
;             const char* a3 = a2 + kstep; const char* b3 = b2 + kstep;
;             if (last && has_next) S.a_ready(nxt);
;             if constexpr (SP2) {
;             PG8_LDB(B0, 0, 0); PG8_LDB(B1, 0, 1); PG8_SCHED; PG8_LDA(At, 0, 0); PG8_STAGE(PG8_SA(1, 1), a1 + hstep, voffA);
;             PG8_WAIT_V(8); PG8_WAIT_L(0); PG8_BAR; PG8_MMA(0, 0, At, B0); PG8_MMA(0, 1, At, B1); PG8_BAR; PG8_SCHED;
;             PG8_LDA(At, 0, 1); PG8_STAGE(PG8_SB(0, 0), b2, voffB); PG8_STAGE(PG8_SB(0, 1), b2 + hstep, voffB); PG8_STAGE(PG8_SA(0, 0), a2, voffA);
;             PG8_WAIT_V(8); PG8_WAIT_L(0); PG8_BAR; PG8_MMA(1, 0, At, B0); PG8_MMA(1, 1, At, B1); PG8_BAR; PG8_SCHED;
.LBB0_1630:
	v_add_u32_e32 v164, s57, v150
	ds_read_b128 v[152:155], v164
	ds_read_b128 v[156:159], v164 offset:1024
	ds_read_b128 v[160:163], v164 offset:2048
	ds_read_b128 v[170:173], v164 offset:3072
	v_add_u32_e32 v164, s58, v150
	s_add_u32 s46, s20, s44
	ds_read_b128 v[174:177], v164
	ds_read_b128 v[178:181], v164 offset:1024
	ds_read_b128 v[182:185], v164 offset:2048
	ds_read_b128 v[186:189], v164 offset:3072
	s_addc_u32 s47, s21, s45
	s_add_u32 s46, s46, 0x100
	s_addc_u32 s47, s47, 0
	s_add_u32 s63, s42, s44
	s_addc_u32 s64, s43, s45
	s_cmpk_eq_i32 s44, 0x700
	s_cselect_b32 s49, s31, s47
	s_cselect_b32 s48, s60, s46
	s_cselect_b32 s47, s29, s64
	s_cselect_b32 s46, s61, s63
	v_lshl_add_u64 v[164:165], v[146:147], 0, s[44:45]
	s_add_i32 m0, s50, 0xc000
	ds_read_b128 v[190:193], v151
	ds_read_b128 v[194:197], v151 offset:1024
	ds_read_b128 v[198:201], v151 offset:2048
	ds_read_b128 v[202:205], v151 offset:3072
	ds_read_b128 v[206:209], v151 offset:4096
	ds_read_b128 v[210:213], v151 offset:5120
	ds_read_b128 v[214:217], v151 offset:6144
	ds_read_b128 v[218:221], v151 offset:7168
	global_load_lds_dwordx4 v[164:165], off
	v_lshl_add_u64 v[164:165], v[148:149], 0, s[44:45]
	s_add_i32 m0, s50, 0xe000
	s_nop 0
	global_load_lds_dwordx4 v[164:165], off
	s_waitcnt vmcnt(8)
	s_waitcnt lgkmcnt(0)
	s_setprio 1
	s_barrier
	v_mfma_f32_16x16x32_bf16 v[58:61], v[152:155], v[190:193], v[58:61]
	v_mfma_f32_16x16x32_bf16 v[62:65], v[160:163], v[190:193], v[62:65]
	v_mfma_f32_16x16x32_bf16 v[78:81], v[152:155], v[198:201], v[78:81]
	v_mfma_f32_16x16x32_bf16 v[70:73], v[160:163], v[198:201], v[70:73]
	v_mfma_f32_16x16x32_bf16 v[98:101], v[152:155], v[206:209], v[98:101]
	v_mfma_f32_16x16x32_bf16 v[90:93], v[160:163], v[206:209], v[90:93]
	v_mfma_f32_16x16x32_bf16 v[114:117], v[152:155], v[214:217], v[114:117]
	v_mfma_f32_16x16x32_bf16 v[106:109], v[160:163], v[214:217], v[106:109]
	v_mfma_f32_16x16x32_bf16 v[58:61], v[156:159], v[194:197], v[58:61]
	v_mfma_f32_16x16x32_bf16 v[62:65], v[170:173], v[194:197], v[62:65]
	v_mfma_f32_16x16x32_bf16 v[78:81], v[156:159], v[202:205], v[78:81]
	v_mfma_f32_16x16x32_bf16 v[70:73], v[170:173], v[202:205], v[70:73]
	v_mfma_f32_16x16x32_bf16 v[98:101], v[156:159], v[210:213], v[98:101]
	v_mfma_f32_16x16x32_bf16 v[90:93], v[170:173], v[210:213], v[90:93]
	v_mfma_f32_16x16x32_bf16 v[114:117], v[156:159], v[218:221], v[114:117]
	v_mfma_f32_16x16x32_bf16 v[106:109], v[170:173], v[218:221], v[106:109]
	s_setprio 0
	s_setprio 1
	v_mfma_f32_16x16x32_bf16 v[54:57], v[174:177], v[190:193], v[54:57]
	v_mfma_f32_16x16x32_bf16 v[46:49], v[182:185], v[190:193], v[46:49]
	v_mfma_f32_16x16x32_bf16 v[50:53], v[174:177], v[198:201], v[50:53]
	v_mfma_f32_16x16x32_bf16 v[42:45], v[182:185], v[198:201], v[42:45]
	v_mfma_f32_16x16x32_bf16 v[74:77], v[174:177], v[206:209], v[74:77]
	v_mfma_f32_16x16x32_bf16 v[66:69], v[182:185], v[206:209], v[66:69]
	v_mfma_f32_16x16x32_bf16 v[102:105], v[174:177], v[214:217], v[102:105]
	v_mfma_f32_16x16x32_bf16 v[94:97], v[182:185], v[214:217], v[94:97]
	v_mfma_f32_16x16x32_bf16 v[54:57], v[178:181], v[194:197], v[54:57]
	v_mfma_f32_16x16x32_bf16 v[46:49], v[186:189], v[194:197], v[46:49]
	v_mfma_f32_16x16x32_bf16 v[50:53], v[178:181], v[202:205], v[50:53]
	v_mfma_f32_16x16x32_bf16 v[42:45], v[186:189], v[202:205], v[42:45]
	v_mfma_f32_16x16x32_bf16 v[74:77], v[178:181], v[210:213], v[74:77]
	v_mfma_f32_16x16x32_bf16 v[66:69], v[186:189], v[210:213], v[66:69]
	v_mfma_f32_16x16x32_bf16 v[102:105], v[178:181], v[218:221], v[102:105]
	v_mfma_f32_16x16x32_bf16 v[94:97], v[186:189], v[218:221], v[94:97]
	s_barrier
	s_setprio 0
	s_add_i32 s63, s57, s37
	v_lshl_add_u64 v[164:165], s[46:47], 0, v[132:133]
	s_mov_b32 m0, s63
	ds_read_b128 v[190:193], v151 offset:16384
	ds_read_b128 v[194:197], v151 offset:17408
	ds_read_b128 v[198:201], v151 offset:18432
	ds_read_b128 v[202:205], v151 offset:19456
	ds_read_b128 v[206:209], v151 offset:20480
	ds_read_b128 v[210:213], v151 offset:21504
	ds_read_b128 v[214:217], v151 offset:22528
	ds_read_b128 v[218:221], v151 offset:23552
	global_load_lds_dwordx4 v[164:165], off
	s_add_i32 m0, s63, 0x2000
	s_add_u32 s68, s46, 0x40000
	v_lshl_add_u64 v[222:223], s[46:47], 0, v[136:137]
	s_addc_u32 s69, s47, 0
	s_add_i32 s63, s58, s37
	global_load_lds_dwordx4 v[222:223], off
	v_lshl_add_u64 v[224:225], s[68:69], 0, v[132:133]
	s_mov_b32 m0, s63
	v_lshl_add_u64 v[226:227], s[48:49], 0, v[134:135]
	global_load_lds_dwordx4 v[224:225], off
	v_lshl_add_u64 v[224:225], s[68:69], 0, v[136:137]
	s_add_i32 m0, s63, 0x2000
	s_nop 0
	global_load_lds_dwordx4 v[224:225], off
	v_lshl_add_u64 v[224:225], s[48:49], 0, v[130:131]
	s_mov_b32 m0, s50
	s_nop 0
	global_load_lds_dwordx4 v[224:225], off
	s_mov_b32 m0, s51
	s_nop 0
	global_load_lds_dwordx4 v[226:227], off
	s_waitcnt vmcnt(8)
	s_waitcnt lgkmcnt(0)
	s_setprio 1
	s_barrier
; #define PG8_STAGE(bufoff, gbase, voff) do { _Pragma("unroll") for (int _i = 0; _i < 2; ++_i) \
;         __builtin_amdgcn_global_load_lds((const unsigned*)((const char*)(gbase) + (voff)[_i]), (PG8_LAS unsigned*)(lds + (bufoff) + ldsw + _i * 8192), 16, 0, 0); } while (0)
; #define PG8_LDA(dst, b, h) do { _Pragma("unroll") for (int m = 0; m < 4; ++m) _Pragma("unroll") for (int k = 0; k < 2; ++k) dst[m][k] = *(const PG8_LAS bf16x8*)(lds + PG8_SA(b, h) + aoff + m * 2048 + k * 1024); } while (0)
; #define PG8_LDB(dst, b, h) do { _Pragma("unroll") for (int n = 0; n < 2; ++n) _Pragma("unroll") for (int k = 0; k < 2; ++k) dst[n][k] = *(const PG8_LAS bf16x8*)(lds + PG8_SB(b, h) + boff + n * 2048 + k * 1024); } while (0)
; #define PG8_MMA(ai, bj, At, Bt) do { __builtin_amdgcn_s_setprio(1); _Pragma("unroll") for (int m = 0; m < 4; ++m) _Pragma("unroll") for (int n = 0; n < 2; ++n) _Pragma("unroll") for (int k = 0; k < 2; ++k) \
;         acc[ai][bj][m][n] = __builtin_amdgcn_mfma_f32_16x16x32_bf16(Bt[n][k], At[m][k], acc[ai][bj][m][n], 0, 0, 0); __builtin_amdgcn_s_setprio(0); } while (0)
; #define PG8_WAIT_V(n) asm volatile("s_waitcnt vmcnt(" #n ")" ::: "memory")
; #define PG8_WAIT_L(n) asm volatile("s_waitcnt lgkmcnt(" #n ")" ::: "memory")
; #define PG8_BAR __builtin_amdgcn_s_barrier()
; #define PG8_SCHED __builtin_amdgcn_sched_barrier(0)
; template <class Epi, class Sched, bool ALIGN_EPI = false, bool SP2 = false, bool PAIR_ACC = false>
; __device__ __forceinline__ void gemm_phase(PG8_LAS unsigned char* lds, const Gemm g, const Sched& S, const Epi& E) {
;     ...
;             PG8_WAIT_V(8); PG8_WAIT_L(0); PG8_BAR; PG8_MMA(1, 0, At, B0); PG8_MMA(1, 1, At, B1); PG8_BAR; PG8_SCHED;
;             PG8_LDB(B0, 1, 0); PG8_LDB(B1, 1, 1); PG8_SCHED; PG8_LDA(At, 1, 0); PG8_STAGE(PG8_SA(0, 1), a2 + hstep, voffA);
;             PG8_WAIT_V(8); PG8_WAIT_L(0); PG8_BAR; PG8_MMA(0, 0, At, B0); PG8_MMA(0, 1, At, B1); PG8_BAR; PG8_SCHED;
	v_mfma_f32_16x16x32_bf16 v[126:129], v[152:155], v[190:193], v[126:129]
	v_mfma_f32_16x16x32_bf16 v[122:125], v[160:163], v[190:193], v[122:125]
	v_mfma_f32_16x16x32_bf16 v[86:89], v[152:155], v[198:201], v[86:89]
	v_mfma_f32_16x16x32_bf16 v[82:85], v[160:163], v[198:201], v[82:85]
	v_mfma_f32_16x16x32_bf16 v[30:33], v[152:155], v[206:209], v[30:33]
	v_mfma_f32_16x16x32_bf16 v[26:29], v[160:163], v[206:209], v[26:29]
	v_mfma_f32_16x16x32_bf16 v[14:17], v[152:155], v[214:217], v[14:17]
	v_mfma_f32_16x16x32_bf16 v[10:13], v[160:163], v[214:217], v[10:13]
	v_mfma_f32_16x16x32_bf16 v[126:129], v[156:159], v[194:197], v[126:129]
	v_mfma_f32_16x16x32_bf16 v[122:125], v[170:173], v[194:197], v[122:125]
	v_mfma_f32_16x16x32_bf16 v[86:89], v[156:159], v[202:205], v[86:89]
	v_mfma_f32_16x16x32_bf16 v[82:85], v[170:173], v[202:205], v[82:85]
	v_mfma_f32_16x16x32_bf16 v[30:33], v[156:159], v[210:213], v[30:33]
	v_mfma_f32_16x16x32_bf16 v[26:29], v[170:173], v[210:213], v[26:29]
	v_mfma_f32_16x16x32_bf16 v[14:17], v[156:159], v[218:221], v[14:17]
	v_mfma_f32_16x16x32_bf16 v[10:13], v[170:173], v[218:221], v[10:13]
	s_setprio 0
	s_setprio 1
	v_mfma_f32_16x16x32_bf16 v[118:121], v[174:177], v[190:193], v[118:121]
	v_mfma_f32_16x16x32_bf16 v[110:113], v[182:185], v[190:193], v[110:113]
	v_mfma_f32_16x16x32_bf16 v[38:41], v[174:177], v[198:201], v[38:41]
	v_mfma_f32_16x16x32_bf16 v[34:37], v[182:185], v[198:201], v[34:37]
	v_mfma_f32_16x16x32_bf16 v[22:25], v[174:177], v[206:209], v[22:25]
	v_mfma_f32_16x16x32_bf16 v[18:21], v[182:185], v[206:209], v[18:21]
	v_mfma_f32_16x16x32_bf16 v[6:9], v[174:177], v[214:217], v[6:9]
	v_mfma_f32_16x16x32_bf16 v[2:5], v[182:185], v[214:217], v[2:5]
	v_mfma_f32_16x16x32_bf16 v[118:121], v[178:181], v[194:197], v[118:121]
	v_mfma_f32_16x16x32_bf16 v[110:113], v[186:189], v[194:197], v[110:113]
	v_mfma_f32_16x16x32_bf16 v[38:41], v[178:181], v[202:205], v[38:41]
	v_mfma_f32_16x16x32_bf16 v[34:37], v[186:189], v[202:205], v[34:37]
	v_mfma_f32_16x16x32_bf16 v[22:25], v[178:181], v[210:213], v[22:25]
	v_mfma_f32_16x16x32_bf16 v[18:21], v[186:189], v[210:213], v[18:21]
	v_mfma_f32_16x16x32_bf16 v[6:9], v[178:181], v[218:221], v[6:9]
	v_mfma_f32_16x16x32_bf16 v[2:5], v[186:189], v[218:221], v[2:5]
	s_barrier
	s_setprio 0
	s_add_i32 s63, 0, 0x18000
	v_add_u32_e32 v169, s63, v150
	s_add_i32 s64, 0, 0x1c000
	ds_read_b128 v[152:155], v169
	ds_read_b128 v[156:159], v169 offset:1024
	ds_read_b128 v[160:163], v169 offset:2048
	ds_read_b128 v[170:173], v169 offset:3072
	v_add_u32_e32 v169, s64, v150
	ds_read_b128 v[174:177], v169
	ds_read_b128 v[178:181], v169 offset:1024
	ds_read_b128 v[182:185], v169 offset:2048
	ds_read_b128 v[186:189], v169 offset:3072
	s_add_u32 s48, s48, 0x40000
	s_addc_u32 s49, s49, 0
	s_mov_b32 m0, s52
	v_lshl_add_u64 v[228:229], s[48:49], 0, v[130:131]
	ds_read_b128 v[190:193], v151 offset:32768
	ds_read_b128 v[194:197], v151 offset:33792
	ds_read_b128 v[198:201], v151 offset:34816
	ds_read_b128 v[202:205], v151 offset:35840
	ds_read_b128 v[206:209], v151 offset:36864
	ds_read_b128 v[210:213], v151 offset:37888
	ds_read_b128 v[214:217], v151 offset:38912
	ds_read_b128 v[218:221], v151 offset:39936
	global_load_lds_dwordx4 v[228:229], off
	v_lshl_add_u64 v[228:229], s[48:49], 0, v[134:135]
	s_mov_b32 m0, s53
	s_nop 0
	global_load_lds_dwordx4 v[228:229], off
	s_waitcnt vmcnt(8)
	s_waitcnt lgkmcnt(0)
	s_setprio 1
	s_barrier
	v_mfma_f32_16x16x32_bf16 v[58:61], v[152:155], v[190:193], v[58:61]
	v_mfma_f32_16x16x32_bf16 v[62:65], v[160:163], v[190:193], v[62:65]
	v_mfma_f32_16x16x32_bf16 v[78:81], v[152:155], v[198:201], v[78:81]
	v_mfma_f32_16x16x32_bf16 v[70:73], v[160:163], v[198:201], v[70:73]
	v_mfma_f32_16x16x32_bf16 v[98:101], v[152:155], v[206:209], v[98:101]
	v_mfma_f32_16x16x32_bf16 v[90:93], v[160:163], v[206:209], v[90:93]
	v_mfma_f32_16x16x32_bf16 v[114:117], v[152:155], v[214:217], v[114:117]
	v_mfma_f32_16x16x32_bf16 v[106:109], v[160:163], v[214:217], v[106:109]
	v_mfma_f32_16x16x32_bf16 v[58:61], v[156:159], v[194:197], v[58:61]
	v_mfma_f32_16x16x32_bf16 v[62:65], v[170:173], v[194:197], v[62:65]
	v_mfma_f32_16x16x32_bf16 v[78:81], v[156:159], v[202:205], v[78:81]
	v_mfma_f32_16x16x32_bf16 v[70:73], v[170:173], v[202:205], v[70:73]
	v_mfma_f32_16x16x32_bf16 v[98:101], v[156:159], v[210:213], v[98:101]
	v_mfma_f32_16x16x32_bf16 v[90:93], v[170:173], v[210:213], v[90:93]
	v_mfma_f32_16x16x32_bf16 v[114:117], v[156:159], v[218:221], v[114:117]
	v_mfma_f32_16x16x32_bf16 v[106:109], v[170:173], v[218:221], v[106:109]
	s_setprio 0
	s_setprio 1
	v_mfma_f32_16x16x32_bf16 v[54:57], v[174:177], v[190:193], v[54:57]
	v_mfma_f32_16x16x32_bf16 v[46:49], v[182:185], v[190:193], v[46:49]
	v_mfma_f32_16x16x32_bf16 v[50:53], v[174:177], v[198:201], v[50:53]
	v_mfma_f32_16x16x32_bf16 v[42:45], v[182:185], v[198:201], v[42:45]
	v_mfma_f32_16x16x32_bf16 v[74:77], v[174:177], v[206:209], v[74:77]
	v_mfma_f32_16x16x32_bf16 v[66:69], v[182:185], v[206:209], v[66:69]
	v_mfma_f32_16x16x32_bf16 v[102:105], v[174:177], v[214:217], v[102:105]
	v_mfma_f32_16x16x32_bf16 v[94:97], v[182:185], v[214:217], v[94:97]
	v_mfma_f32_16x16x32_bf16 v[54:57], v[178:181], v[194:197], v[54:57]
	v_mfma_f32_16x16x32_bf16 v[46:49], v[186:189], v[194:197], v[46:49]
	v_mfma_f32_16x16x32_bf16 v[50:53], v[178:181], v[202:205], v[50:53]
	v_mfma_f32_16x16x32_bf16 v[42:45], v[186:189], v[202:205], v[42:45]
	v_mfma_f32_16x16x32_bf16 v[74:77], v[178:181], v[210:213], v[74:77]
	v_mfma_f32_16x16x32_bf16 v[66:69], v[186:189], v[210:213], v[66:69]
	v_mfma_f32_16x16x32_bf16 v[102:105], v[178:181], v[218:221], v[102:105]
	v_mfma_f32_16x16x32_bf16 v[94:97], v[186:189], v[218:221], v[94:97]
	s_barrier
; #define PG8_STAGE(bufoff, gbase, voff) do { _Pragma("unroll") for (int _i = 0; _i < 2; ++_i) \
;         __builtin_amdgcn_global_load_lds((const unsigned*)((const char*)(gbase) + (voff)[_i]), (PG8_LAS unsigned*)(lds + (bufoff) + ldsw + _i * 8192), 16, 0, 0); } while (0)
; #define PG8_LDA(dst, b, h) do { _Pragma("unroll") for (int m = 0; m < 4; ++m) _Pragma("unroll") for (int k = 0; k < 2; ++k) dst[m][k] = *(const PG8_LAS bf16x8*)(lds + PG8_SA(b, h) + aoff + m * 2048 + k * 1024); } while (0)
; #define PG8_MMA(ai, bj, At, Bt) do { __builtin_amdgcn_s_setprio(1); _Pragma("unroll") for (int m = 0; m < 4; ++m) _Pragma("unroll") for (int n = 0; n < 2; ++n) _Pragma("unroll") for (int k = 0; k < 2; ++k) \
;         acc[ai][bj][m][n] = __builtin_amdgcn_mfma_f32_16x16x32_bf16(Bt[n][k], At[m][k], acc[ai][bj][m][n], 0, 0, 0); __builtin_amdgcn_s_setprio(0); } while (0)
; #define PG8_WAIT_V(n) asm volatile("s_waitcnt vmcnt(" #n ")" ::: "memory")
; #define PG8_WAIT_L(n) asm volatile("s_waitcnt lgkmcnt(" #n ")" ::: "memory")
; #define PG8_BAR __builtin_amdgcn_s_barrier()
; #define PG8_SCHED __builtin_amdgcn_sched_barrier(0)
; template <class Epi, class Sched, bool ALIGN_EPI = false, bool SP2 = false, bool PAIR_ACC = false>
; __device__ __forceinline__ void gemm_phase(PG8_LAS unsigned char* lds, const Gemm g, const Sched& S, const Epi& E) {
;     ...
;             PG8_LDA(At, 1, 1); PG8_STAGE(PG8_SB(1, 0), b3, voffB); PG8_STAGE(PG8_SB(1, 1), b3 + hstep, voffB); PG8_STAGE(PG8_SA(1, 0), a3, voffA);
;             PG8_WAIT_V(8); PG8_WAIT_L(0); PG8_BAR; PG8_MMA(1, 0, At, B0); PG8_MMA(1, 1, At, B1); PG8_BAR; PG8_SCHED;
;     ...
;         if (!has_next) break;
;         if (!(PAIR_ACC && cur.pn < 4)) {
; #pragma unroll
;         for (int a = 0; a < 2; ++a)
; #pragma unroll
;             for (int b = 0; b < 2; ++b)
; #pragma unroll
;                 for (int m = 0; m < 4; ++m)
; #pragma unroll
;                     for (int n = 0; n < 2; ++n) acc[a][b][m][n] = (f32x4){0.f, 0.f, 0.f, 0.f};
;         }
;         cur = nxt; cA = nA; cB = nB; ++ui;
	s_setprio 0
	s_add_i32 s48, s63, s37
	v_lshl_add_u64 v[164:165], v[164:165], 0, s[22:23]
	s_mov_b32 m0, s48
	ds_read_b128 v[190:193], v151 offset:49152
	ds_read_b128 v[194:197], v151 offset:50176
	ds_read_b128 v[198:201], v151 offset:51200
	ds_read_b128 v[202:205], v151 offset:52224
	ds_read_b128 v[206:209], v151 offset:53248
	ds_read_b128 v[210:213], v151 offset:54272
	ds_read_b128 v[214:217], v151 offset:55296
	ds_read_b128 v[218:221], v151 offset:56320
	global_load_lds_dwordx4 v[164:165], off
	s_add_i32 m0, s48, 0x2000
	s_add_u32 s46, s46, 0x40080
	v_lshl_add_u64 v[164:165], v[222:223], 0, s[22:23]
	s_addc_u32 s47, s47, 0
	s_add_i32 s48, s64, s37
	global_load_lds_dwordx4 v[164:165], off
	v_lshl_add_u64 v[164:165], s[46:47], 0, v[132:133]
	s_mov_b32 m0, s48
	s_nop 0
	global_load_lds_dwordx4 v[164:165], off
	v_lshl_add_u64 v[164:165], s[46:47], 0, v[136:137]
	s_add_i32 m0, s48, 0x2000
	s_nop 0
	global_load_lds_dwordx4 v[164:165], off
	v_lshl_add_u64 v[164:165], v[224:225], 0, s[22:23]
	s_mov_b32 m0, s55
	s_nop 0
	global_load_lds_dwordx4 v[164:165], off
	v_lshl_add_u64 v[164:165], v[226:227], 0, s[22:23]
	s_mov_b32 m0, s56
	s_nop 0
	global_load_lds_dwordx4 v[164:165], off
	s_waitcnt vmcnt(8)
	s_waitcnt lgkmcnt(0)
	s_setprio 1
	s_barrier
	v_mfma_f32_16x16x32_bf16 v[126:129], v[152:155], v[190:193], v[126:129]
	v_mfma_f32_16x16x32_bf16 v[122:125], v[160:163], v[190:193], v[122:125]
	v_mfma_f32_16x16x32_bf16 v[86:89], v[152:155], v[198:201], v[86:89]
	v_mfma_f32_16x16x32_bf16 v[82:85], v[160:163], v[198:201], v[82:85]
	v_mfma_f32_16x16x32_bf16 v[30:33], v[152:155], v[206:209], v[30:33]
	v_mfma_f32_16x16x32_bf16 v[26:29], v[160:163], v[206:209], v[26:29]
	v_mfma_f32_16x16x32_bf16 v[14:17], v[152:155], v[214:217], v[14:17]
	v_mfma_f32_16x16x32_bf16 v[10:13], v[160:163], v[214:217], v[10:13]
	v_mfma_f32_16x16x32_bf16 v[126:129], v[156:159], v[194:197], v[126:129]
	v_mfma_f32_16x16x32_bf16 v[122:125], v[170:173], v[194:197], v[122:125]
	v_mfma_f32_16x16x32_bf16 v[86:89], v[156:159], v[202:205], v[86:89]
	v_mfma_f32_16x16x32_bf16 v[82:85], v[170:173], v[202:205], v[82:85]
	v_mfma_f32_16x16x32_bf16 v[30:33], v[156:159], v[210:213], v[30:33]
	v_mfma_f32_16x16x32_bf16 v[26:29], v[170:173], v[210:213], v[26:29]
	v_mfma_f32_16x16x32_bf16 v[14:17], v[156:159], v[218:221], v[14:17]
	v_mfma_f32_16x16x32_bf16 v[10:13], v[170:173], v[218:221], v[10:13]
	s_setprio 0
	s_setprio 1
	v_mfma_f32_16x16x32_bf16 v[118:121], v[174:177], v[190:193], v[118:121]
	v_mfma_f32_16x16x32_bf16 v[110:113], v[182:185], v[190:193], v[110:113]
	v_mfma_f32_16x16x32_bf16 v[38:41], v[174:177], v[198:201], v[38:41]
	v_mfma_f32_16x16x32_bf16 v[34:37], v[182:185], v[198:201], v[34:37]
	v_mfma_f32_16x16x32_bf16 v[22:25], v[174:177], v[206:209], v[22:25]
	v_mfma_f32_16x16x32_bf16 v[18:21], v[182:185], v[206:209], v[18:21]
	v_mfma_f32_16x16x32_bf16 v[6:9], v[174:177], v[214:217], v[6:9]
	v_mfma_f32_16x16x32_bf16 v[2:5], v[182:185], v[214:217], v[2:5]
	v_mfma_f32_16x16x32_bf16 v[118:121], v[178:181], v[194:197], v[118:121]
	v_mfma_f32_16x16x32_bf16 v[110:113], v[186:189], v[194:197], v[110:113]
	v_mfma_f32_16x16x32_bf16 v[38:41], v[178:181], v[202:205], v[38:41]
	v_mfma_f32_16x16x32_bf16 v[34:37], v[186:189], v[202:205], v[34:37]
	v_mfma_f32_16x16x32_bf16 v[22:25], v[178:181], v[210:213], v[22:25]
	v_mfma_f32_16x16x32_bf16 v[18:21], v[186:189], v[210:213], v[18:21]
	v_mfma_f32_16x16x32_bf16 v[6:9], v[178:181], v[218:221], v[6:9]
	v_mfma_f32_16x16x32_bf16 v[2:5], v[186:189], v[218:221], v[2:5]
	s_barrier
	s_setprio 0
	s_add_i32 s62, s62, 2
	s_add_u32 s44, s44, 0x100
	s_addc_u32 s45, s45, 0
	s_cmp_gt_u32 s62, 13
	s_cbranch_scc0 .LBB0_1630
	s_add_u32 s42, s42, 0xffffff00
	s_addc_u32 s43, s43, -1
	s_andn2_b64 vcc, exec, s[8:9]
	s_cbranch_vccnz .LBB0_1621
	v_mov_b32_e32 v2, 0
	s_mov_b32 s10, s28
	s_mov_b32 s18, s30
	s_mov_b64 s[20:21], s[40:41]
	s_mov_b32 s54, s59
	v_mov_b32_e32 v3, v2
	v_mov_b32_e32 v4, v2
	v_mov_b32_e32 v5, v2
	v_mov_b32_e32 v6, v2
	v_mov_b32_e32 v7, v2
	v_mov_b32_e32 v8, v2
	v_mov_b32_e32 v9, v2
	v_mov_b32_e32 v18, v2
	v_mov_b32_e32 v19, v2
	v_mov_b32_e32 v20, v2
	v_mov_b32_e32 v21, v2
	v_mov_b32_e32 v22, v2
	v_mov_b32_e32 v23, v2
	v_mov_b32_e32 v24, v2
	v_mov_b32_e32 v25, v2
	v_mov_b32_e32 v34, v2
	v_mov_b32_e32 v35, v2
	v_mov_b32_e32 v36, v2
	v_mov_b32_e32 v37, v2
	v_mov_b32_e32 v38, v2
	v_mov_b32_e32 v39, v2
	v_mov_b32_e32 v40, v2
	v_mov_b32_e32 v41, v2
	v_mov_b32_e32 v110, v2
	v_mov_b32_e32 v111, v2
	v_mov_b32_e32 v112, v2
	v_mov_b32_e32 v113, v2
	v_mov_b32_e32 v118, v2
	v_mov_b32_e32 v119, v2
	v_mov_b32_e32 v120, v2
	v_mov_b32_e32 v121, v2
	v_mov_b32_e32 v10, v2
	v_mov_b32_e32 v11, v2
	v_mov_b32_e32 v12, v2
	v_mov_b32_e32 v13, v2
	v_mov_b32_e32 v14, v2
	v_mov_b32_e32 v15, v2
	v_mov_b32_e32 v16, v2
	v_mov_b32_e32 v17, v2
	v_mov_b32_e32 v26, v2
	v_mov_b32_e32 v27, v2
	v_mov_b32_e32 v28, v2
	v_mov_b32_e32 v29, v2
	v_mov_b32_e32 v30, v2
	v_mov_b32_e32 v31, v2
	v_mov_b32_e32 v32, v2
	v_mov_b32_e32 v33, v2
	v_mov_b32_e32 v82, v2
	v_mov_b32_e32 v83, v2
	v_mov_b32_e32 v84, v2
	v_mov_b32_e32 v85, v2
	v_mov_b32_e32 v86, v2
	v_mov_b32_e32 v87, v2
	v_mov_b32_e32 v88, v2
	v_mov_b32_e32 v89, v2
	v_mov_b32_e32 v122, v2
	v_mov_b32_e32 v123, v2
	v_mov_b32_e32 v124, v2
	v_mov_b32_e32 v125, v2
	v_mov_b32_e32 v126, v2
	v_mov_b32_e32 v127, v2
	v_mov_b32_e32 v128, v2
	v_mov_b32_e32 v129, v2
	v_mov_b32_e32 v94, v2
	v_mov_b32_e32 v95, v2
	v_mov_b32_e32 v96, v2
	v_mov_b32_e32 v97, v2
	v_mov_b32_e32 v102, v2
	v_mov_b32_e32 v103, v2
	v_mov_b32_e32 v104, v2
	v_mov_b32_e32 v105, v2
	v_mov_b32_e32 v66, v2
	v_mov_b32_e32 v67, v2
	v_mov_b32_e32 v68, v2
	v_mov_b32_e32 v69, v2
	v_mov_b32_e32 v74, v2
	v_mov_b32_e32 v75, v2
	v_mov_b32_e32 v76, v2
	v_mov_b32_e32 v77, v2
	v_mov_b32_e32 v42, v2
	v_mov_b32_e32 v43, v2
	v_mov_b32_e32 v44, v2
	v_mov_b32_e32 v45, v2
	v_mov_b32_e32 v50, v2
	v_mov_b32_e32 v51, v2
	v_mov_b32_e32 v52, v2
	v_mov_b32_e32 v53, v2
	v_mov_b32_e32 v46, v2
	v_mov_b32_e32 v47, v2
	v_mov_b32_e32 v48, v2
	v_mov_b32_e32 v49, v2
	v_mov_b32_e32 v54, v2
	v_mov_b32_e32 v55, v2
	v_mov_b32_e32 v56, v2
	v_mov_b32_e32 v57, v2
	v_mov_b32_e32 v106, v2
	v_mov_b32_e32 v107, v2
	v_mov_b32_e32 v108, v2
	v_mov_b32_e32 v109, v2
	v_mov_b32_e32 v114, v2
	v_mov_b32_e32 v115, v2
	v_mov_b32_e32 v116, v2
	v_mov_b32_e32 v117, v2
	v_mov_b32_e32 v90, v2
	v_mov_b32_e32 v91, v2
	v_mov_b32_e32 v92, v2
	v_mov_b32_e32 v93, v2
	v_mov_b32_e32 v98, v2
	v_mov_b32_e32 v99, v2
	v_mov_b32_e32 v100, v2
	v_mov_b32_e32 v101, v2
	v_mov_b32_e32 v70, v2
	v_mov_b32_e32 v71, v2
	v_mov_b32_e32 v72, v2
	v_mov_b32_e32 v73, v2
	v_mov_b32_e32 v78, v2
	v_mov_b32_e32 v79, v2
	v_mov_b32_e32 v80, v2
	v_mov_b32_e32 v81, v2
	v_mov_b32_e32 v62, v2
	v_mov_b32_e32 v63, v2
	v_mov_b32_e32 v64, v2
	v_mov_b32_e32 v65, v2
	v_mov_b32_e32 v58, v2
	v_mov_b32_e32 v59, v2
	v_mov_b32_e32 v60, v2
	v_mov_b32_e32 v61, v2
	s_andn2_b64 vcc, exec, s[6:7]
	s_cbranch_vccnz .LBB0_1622

; #define PG8_STAGE(bufoff, gbase, voff) do { _Pragma("unroll") for (int _i = 0; _i < 2; ++_i) \
;         __builtin_amdgcn_global_load_lds((const unsigned*)((const char*)(gbase) + (voff)[_i]), (PG8_LAS unsigned*)(lds + (bufoff) + ldsw + _i * 8192), 16, 0, 0); } while (0)
; #define PG8_WAIT_V(n) asm volatile("s_waitcnt vmcnt(" #n ")" ::: "memory")
; #define PG8_WAIT_L(n) asm volatile("s_waitcnt lgkmcnt(" #n ")" ::: "memory")
; template <class Epi, class Sched, bool ALIGN_EPI = false, bool SP2 = false, bool PAIR_ACC = false>
; __device__ __forceinline__ void gemm_phase(PG8_LAS unsigned char* lds, const Gemm g, const Sched& S, const Epi& E) {
;     ...
;         const bool has_next = S.next(ui + 1, nxt);
;         const char* nA = has_next ? (const char*)g.A + (size_t)nxt.pm * tstep + (size_t)(nxt.pn / g.a_div) * g.a_sel : cA; const char* nB = has_next ? (const char*)g.Bt + (size_t)nxt.pn * tstep : cB;
;         for (int t = 0; t < nt; t += 2) {
;             const bool last = (t == nt - 2);
;             const char* a1 = cA + (size_t)(t + 1) * kstep;
;             const char* a2 = last ? nA : cA + (size_t)(t + 2) * kstep; const char* b2 = last ? nB : cB + (size_t)(t + 2) * kstep;
;             const char* a3 = a2 + kstep; const char* b3 = b2 + kstep;
;             if (last && has_next) S.a_ready(nxt);
;             if constexpr (SP2) {
;             PG8_LDB(B0, 0, 0); PG8_LDB(B1, 0, 1); PG8_SCHED; PG8_LDA(At, 0, 0); PG8_STAGE(PG8_SA(1, 1), a1 + hstep, voffA);
;             PG8_WAIT_V(8); PG8_WAIT_L(0); PG8_BAR; PG8_MMA(0, 0, At, B0); PG8_MMA(0, 1, At, B1); PG8_BAR; PG8_SCHED;
;             PG8_LDA(At, 0, 1); PG8_STAGE(PG8_SB(0, 0), b2, voffB); PG8_STAGE(PG8_SB(0, 1), b2 + hstep, voffB); PG8_STAGE(PG8_SA(0, 0), a2, voffA);
;             PG8_WAIT_V(8); PG8_WAIT_L(0); PG8_BAR; PG8_MMA(1, 0, At, B0); PG8_MMA(1, 1, At, B1); PG8_BAR; PG8_SCHED;
;             PG8_LDB(B0, 1, 0); PG8_LDB(B1, 1, 1); PG8_SCHED; PG8_LDA(At, 1, 0); PG8_STAGE(PG8_SA(0, 1), a2 + hstep, voffA);
;             PG8_WAIT_V(8); PG8_WAIT_L(0); PG8_BAR; PG8_MMA(0, 0, At, B0); PG8_MMA(0, 1, At, B1); PG8_BAR; PG8_SCHED;
;             PG8_LDA(At, 1, 1); PG8_STAGE(PG8_SB(1, 0), b3, voffB); PG8_STAGE(PG8_SB(1, 1), b3 + hstep, voffB); PG8_STAGE(PG8_SA(1, 0), a3, voffA);
;             PG8_WAIT_V(8); PG8_WAIT_L(0); PG8_BAR; PG8_MMA(1, 0, At, B0); PG8_MMA(1, 1, At, B1); PG8_BAR; PG8_SCHED;
.LBB0_1736:
	s_ashr_i32 s53, s52, 31
	s_lshl_b64 s[10:11], s[52:53], 19
	s_add_u32 s54, s4, s10
	s_addc_u32 s55, s5, s11
	s_and_b64 s[10:11], s[8:9], exec
	s_cselect_b32 s53, s55, s63
	s_cselect_b32 s75, s54, s62
	s_ashr_i32 s51, s50, 31
	s_lshl_b64 s[10:11], s[50:51], 19
	s_add_u32 s56, s24, s10
	s_addc_u32 s57, s25, s11
	s_and_b64 s[10:11], s[8:9], exec
	s_cselect_b32 s51, s57, s61
	s_cselect_b32 s76, s56, s60
	s_add_u32 s10, s62, 0x40080
	s_addc_u32 s11, s63, 0
	s_add_u32 s77, s60, 0x100
	s_addc_u32 s78, s61, 0
	s_mov_b32 s79, -2
	ds_read_b128 v[74:77], v196
	ds_read_b128 v[78:81], v196 offset:1024
	ds_read_b128 v[82:85], v196 offset:2048
	ds_read_b128 v[86:89], v196 offset:3072
	ds_read_b128 v[90:93], v197
	ds_read_b128 v[94:97], v197 offset:1024
	ds_read_b128 v[98:101], v197 offset:2048
	ds_read_b128 v[106:109], v197 offset:3072
	s_add_u32 s60, s10, 0xfffc0080
	s_addc_u32 s61, s11, -1
	s_cmp_eq_u32 s79, 12
	s_cselect_b32 s63, s53, s61
	s_cselect_b32 s62, s75, s60
	s_cselect_b32 s61, s51, s78
	s_cselect_b32 s60, s76, s77
	v_lshl_add_u64 v[170:171], s[10:11], 0, v[184:185]
	s_add_i32 m0, s36, 0xc000
	ds_read_b128 v[162:165], v198
	ds_read_b128 v[166:169], v198 offset:1024
	ds_read_b128 v[204:207], v198 offset:2048
	ds_read_b128 v[208:211], v198 offset:3072
	ds_read_b128 v[212:215], v198 offset:4096
	ds_read_b128 v[216:219], v198 offset:5120
	ds_read_b128 v[220:223], v198 offset:6144
	ds_read_b128 v[224:227], v198 offset:7168
	global_load_lds_dwordx4 v[170:171], off
	v_lshl_add_u64 v[170:171], s[10:11], 0, v[186:187]
	s_add_i32 m0, s36, 0xe000
	s_nop 0
	global_load_lds_dwordx4 v[170:171], off
	s_waitcnt vmcnt(8)
	s_waitcnt lgkmcnt(0)
	s_setprio 1
	s_barrier
	v_mfma_f32_16x16x32_bf16 v[150:153], v[74:77], v[162:165], 0
	v_mfma_f32_16x16x32_bf16 v[146:149], v[82:85], v[162:165], 0
	v_mfma_f32_16x16x32_bf16 v[134:137], v[74:77], v[204:207], 0
	v_mfma_f32_16x16x32_bf16 v[130:133], v[82:85], v[204:207], 0
	v_mfma_f32_16x16x32_bf16 v[118:121], v[74:77], v[212:215], 0
	v_mfma_f32_16x16x32_bf16 v[110:113], v[82:85], v[212:215], 0
	v_mfma_f32_16x16x32_bf16 v[114:117], v[74:77], v[220:223], 0
	v_mfma_f32_16x16x32_bf16 v[102:105], v[82:85], v[220:223], 0
	v_mfma_f32_16x16x32_bf16 v[150:153], v[78:81], v[166:169], v[150:153]
	v_mfma_f32_16x16x32_bf16 v[146:149], v[86:89], v[166:169], v[146:149]
	v_mfma_f32_16x16x32_bf16 v[134:137], v[78:81], v[208:211], v[134:137]
	v_mfma_f32_16x16x32_bf16 v[130:133], v[86:89], v[208:211], v[130:133]
	v_mfma_f32_16x16x32_bf16 v[118:121], v[78:81], v[216:219], v[118:121]
	v_mfma_f32_16x16x32_bf16 v[110:113], v[86:89], v[216:219], v[110:113]
	v_mfma_f32_16x16x32_bf16 v[114:117], v[78:81], v[224:227], v[114:117]
	v_mfma_f32_16x16x32_bf16 v[102:105], v[86:89], v[224:227], v[102:105]
	s_setprio 0
	s_setprio 1
	v_mfma_f32_16x16x32_bf16 v[158:161], v[90:93], v[162:165], 0
	v_mfma_f32_16x16x32_bf16 v[154:157], v[98:101], v[162:165], 0
	v_mfma_f32_16x16x32_bf16 v[142:145], v[90:93], v[204:207], 0
	v_mfma_f32_16x16x32_bf16 v[138:141], v[98:101], v[204:207], 0
	v_mfma_f32_16x16x32_bf16 v[126:129], v[90:93], v[212:215], 0
	v_mfma_f32_16x16x32_bf16 v[122:125], v[98:101], v[212:215], 0
	v_mfma_f32_16x16x32_bf16 v[70:73], v[90:93], v[220:223], 0
	v_mfma_f32_16x16x32_bf16 v[66:69], v[98:101], v[220:223], 0
	v_mfma_f32_16x16x32_bf16 v[158:161], v[94:97], v[166:169], v[158:161]
	v_mfma_f32_16x16x32_bf16 v[154:157], v[106:109], v[166:169], v[154:157]
	v_mfma_f32_16x16x32_bf16 v[142:145], v[94:97], v[208:211], v[142:145]
	v_mfma_f32_16x16x32_bf16 v[138:141], v[106:109], v[208:211], v[138:141]
	v_mfma_f32_16x16x32_bf16 v[126:129], v[94:97], v[216:219], v[126:129]
	v_mfma_f32_16x16x32_bf16 v[122:125], v[106:109], v[216:219], v[122:125]
	v_mfma_f32_16x16x32_bf16 v[70:73], v[94:97], v[224:227], v[70:73]
	v_mfma_f32_16x16x32_bf16 v[66:69], v[106:109], v[224:227], v[66:69]
	s_barrier
	s_setprio 0
	s_add_i32 s80, s70, s34
	v_lshl_add_u64 v[170:171], s[60:61], 0, v[176:177]
	s_mov_b32 m0, s80
	ds_read_b128 v[162:165], v198 offset:16384
	ds_read_b128 v[166:169], v198 offset:17408
	ds_read_b128 v[204:207], v198 offset:18432
	ds_read_b128 v[208:211], v198 offset:19456
	ds_read_b128 v[212:215], v198 offset:20480
	ds_read_b128 v[216:219], v198 offset:21504
	ds_read_b128 v[220:223], v198 offset:22528
	ds_read_b128 v[224:227], v198 offset:23552
	global_load_lds_dwordx4 v[170:171], off
	s_add_i32 m0, s80, 0x2000
	s_add_u32 s80, s60, 0x40000
	v_lshl_add_u64 v[192:193], s[60:61], 0, v[172:173]
	s_addc_u32 s81, s61, 0
	s_add_i32 s82, s71, s34
	global_load_lds_dwordx4 v[192:193], off
	v_lshl_add_u64 v[228:229], s[80:81], 0, v[176:177]
	s_mov_b32 m0, s82
	v_lshl_add_u64 v[230:231], s[62:63], 0, v[174:175]
	global_load_lds_dwordx4 v[228:229], off
	v_lshl_add_u64 v[228:229], s[80:81], 0, v[172:173]
	s_add_i32 m0, s82, 0x2000
	s_nop 0
	global_load_lds_dwordx4 v[228:229], off
	v_lshl_add_u64 v[228:229], s[62:63], 0, v[178:179]
	s_mov_b32 m0, s36
	s_nop 0
	global_load_lds_dwordx4 v[228:229], off
	s_mov_b32 m0, s37
	s_nop 0
	global_load_lds_dwordx4 v[230:231], off
	s_waitcnt vmcnt(8)
	s_waitcnt lgkmcnt(0)
	s_setprio 1
	s_barrier
; #define PG8_STAGE(bufoff, gbase, voff) do { _Pragma("unroll") for (int _i = 0; _i < 2; ++_i) \
;         __builtin_amdgcn_global_load_lds((const unsigned*)((const char*)(gbase) + (voff)[_i]), (PG8_LAS unsigned*)(lds + (bufoff) + ldsw + _i * 8192), 16, 0, 0); } while (0)
; #define PG8_LDA(dst, b, h) do { _Pragma("unroll") for (int m = 0; m < 4; ++m) _Pragma("unroll") for (int k = 0; k < 2; ++k) dst[m][k] = *(const PG8_LAS bf16x8*)(lds + PG8_SA(b, h) + aoff + m * 2048 + k * 1024); } while (0)
; #define PG8_LDB(dst, b, h) do { _Pragma("unroll") for (int n = 0; n < 2; ++n) _Pragma("unroll") for (int k = 0; k < 2; ++k) dst[n][k] = *(const PG8_LAS bf16x8*)(lds + PG8_SB(b, h) + boff + n * 2048 + k * 1024); } while (0)
; #define PG8_MMA(ai, bj, At, Bt) do { __builtin_amdgcn_s_setprio(1); _Pragma("unroll") for (int m = 0; m < 4; ++m) _Pragma("unroll") for (int n = 0; n < 2; ++n) _Pragma("unroll") for (int k = 0; k < 2; ++k) \
;         acc[ai][bj][m][n] = __builtin_amdgcn_mfma_f32_16x16x32_bf16(Bt[n][k], At[m][k], acc[ai][bj][m][n], 0, 0, 0); __builtin_amdgcn_s_setprio(0); } while (0)
; #define PG8_BAR __builtin_amdgcn_s_barrier()
; template <class Epi, class Sched, bool ALIGN_EPI = false, bool SP2 = false, bool PAIR_ACC = false>
; __device__ __forceinline__ void gemm_phase(PG8_LAS unsigned char* lds, const Gemm g, const Sched& S, const Epi& E) {
;     ...
;             PG8_LDB(B0, 0, 0); PG8_LDB(B1, 0, 1); PG8_SCHED; PG8_LDA(At, 0, 0); PG8_STAGE(PG8_SA(1, 1), a1 + hstep, voffA);
;             PG8_WAIT_V(8); PG8_WAIT_L(0); PG8_BAR; PG8_MMA(0, 0, At, B0); PG8_MMA(0, 1, At, B1); PG8_BAR; PG8_SCHED;
;             PG8_LDA(At, 0, 1); PG8_STAGE(PG8_SB(0, 0), b2, voffB); PG8_STAGE(PG8_SB(0, 1), b2 + hstep, voffB); PG8_STAGE(PG8_SA(0, 0), a2, voffA);
;             PG8_WAIT_V(8); PG8_WAIT_L(0); PG8_BAR; PG8_MMA(1, 0, At, B0); PG8_MMA(1, 1, At, B1); PG8_BAR; PG8_SCHED;
;             PG8_LDB(B0, 1, 0); PG8_LDB(B1, 1, 1); PG8_SCHED; PG8_LDA(At, 1, 0); PG8_STAGE(PG8_SA(0, 1), a2 + hstep, voffA);
;             PG8_WAIT_V(8); PG8_WAIT_L(0); PG8_BAR; PG8_MMA(0, 0, At, B0); PG8_MMA(0, 1, At, B1); PG8_BAR; PG8_SCHED;
;             PG8_LDA(At, 1, 1); PG8_STAGE(PG8_SB(1, 0), b3, voffB); PG8_STAGE(PG8_SB(1, 1), b3 + hstep, voffB); PG8_STAGE(PG8_SA(1, 0), a3, voffA);
;             PG8_WAIT_V(8); PG8_WAIT_L(0); PG8_BAR; PG8_MMA(1, 0, At, B0); PG8_MMA(1, 1, At, B1); PG8_BAR; PG8_SCHED;
	v_mfma_f32_16x16x32_bf16 v[54:57], v[74:77], v[162:165], 0
	v_mfma_f32_16x16x32_bf16 v[50:53], v[82:85], v[162:165], 0
	v_mfma_f32_16x16x32_bf16 v[38:41], v[74:77], v[204:207], 0
	v_mfma_f32_16x16x32_bf16 v[34:37], v[82:85], v[204:207], 0
	v_mfma_f32_16x16x32_bf16 v[22:25], v[74:77], v[212:215], 0
	v_mfma_f32_16x16x32_bf16 v[14:17], v[82:85], v[212:215], 0
	v_mfma_f32_16x16x32_bf16 v[18:21], v[74:77], v[220:223], 0
	v_mfma_f32_16x16x32_bf16 v[10:13], v[82:85], v[220:223], 0
	v_mfma_f32_16x16x32_bf16 v[54:57], v[78:81], v[166:169], v[54:57]
	v_mfma_f32_16x16x32_bf16 v[50:53], v[86:89], v[166:169], v[50:53]
	v_mfma_f32_16x16x32_bf16 v[38:41], v[78:81], v[208:211], v[38:41]
	v_mfma_f32_16x16x32_bf16 v[34:37], v[86:89], v[208:211], v[34:37]
	v_mfma_f32_16x16x32_bf16 v[22:25], v[78:81], v[216:219], v[22:25]
	v_mfma_f32_16x16x32_bf16 v[14:17], v[86:89], v[216:219], v[14:17]
	v_mfma_f32_16x16x32_bf16 v[18:21], v[78:81], v[224:227], v[18:21]
	v_mfma_f32_16x16x32_bf16 v[10:13], v[86:89], v[224:227], v[10:13]
	s_setprio 0
	s_setprio 1
	v_mfma_f32_16x16x32_bf16 v[62:65], v[90:93], v[162:165], 0
	v_mfma_f32_16x16x32_bf16 v[58:61], v[98:101], v[162:165], 0
	v_mfma_f32_16x16x32_bf16 v[46:49], v[90:93], v[204:207], 0
	v_mfma_f32_16x16x32_bf16 v[42:45], v[98:101], v[204:207], 0
	v_mfma_f32_16x16x32_bf16 v[30:33], v[90:93], v[212:215], 0
	v_mfma_f32_16x16x32_bf16 v[26:29], v[98:101], v[212:215], 0
	v_mfma_f32_16x16x32_bf16 v[6:9], v[90:93], v[220:223], 0
	v_mfma_f32_16x16x32_bf16 v[2:5], v[98:101], v[220:223], 0
	v_mfma_f32_16x16x32_bf16 v[62:65], v[94:97], v[166:169], v[62:65]
	v_mfma_f32_16x16x32_bf16 v[58:61], v[106:109], v[166:169], v[58:61]
	v_mfma_f32_16x16x32_bf16 v[46:49], v[94:97], v[208:211], v[46:49]
	v_mfma_f32_16x16x32_bf16 v[42:45], v[106:109], v[208:211], v[42:45]
	v_mfma_f32_16x16x32_bf16 v[30:33], v[94:97], v[216:219], v[30:33]
	v_mfma_f32_16x16x32_bf16 v[26:29], v[106:109], v[216:219], v[26:29]
	v_mfma_f32_16x16x32_bf16 v[6:9], v[94:97], v[224:227], v[6:9]
	v_mfma_f32_16x16x32_bf16 v[2:5], v[106:109], v[224:227], v[2:5]
	s_barrier
	s_setprio 0
	s_branch .Lpeel_mid_1737
.LBB0_1737:
	ds_read_b128 v[74:77], v196
	ds_read_b128 v[78:81], v196 offset:1024
	ds_read_b128 v[82:85], v196 offset:2048
	ds_read_b128 v[86:89], v196 offset:3072
	ds_read_b128 v[90:93], v197
	ds_read_b128 v[94:97], v197 offset:1024
	ds_read_b128 v[98:101], v197 offset:2048
	ds_read_b128 v[106:109], v197 offset:3072
	s_add_u32 s60, s10, 0xfffc0080
	s_addc_u32 s61, s11, -1
	s_cmp_eq_u32 s79, 12
	s_cselect_b32 s63, s53, s61
	s_cselect_b32 s62, s75, s60
	s_cselect_b32 s61, s51, s78
	s_cselect_b32 s60, s76, s77
	v_lshl_add_u64 v[170:171], s[10:11], 0, v[184:185]
	s_add_i32 m0, s36, 0xc000
	ds_read_b128 v[162:165], v198
	ds_read_b128 v[166:169], v198 offset:1024
	ds_read_b128 v[204:207], v198 offset:2048
	ds_read_b128 v[208:211], v198 offset:3072
	ds_read_b128 v[212:215], v198 offset:4096
	ds_read_b128 v[216:219], v198 offset:5120
	ds_read_b128 v[220:223], v198 offset:6144
	ds_read_b128 v[224:227], v198 offset:7168
	global_load_lds_dwordx4 v[170:171], off
	v_lshl_add_u64 v[170:171], s[10:11], 0, v[186:187]
	s_add_i32 m0, s36, 0xe000
	s_nop 0
	global_load_lds_dwordx4 v[170:171], off
	s_waitcnt vmcnt(8)
	s_waitcnt lgkmcnt(0)
	s_setprio 1
	s_barrier
	v_mfma_f32_16x16x32_bf16 v[150:153], v[74:77], v[162:165], v[150:153]
	v_mfma_f32_16x16x32_bf16 v[146:149], v[82:85], v[162:165], v[146:149]
	v_mfma_f32_16x16x32_bf16 v[134:137], v[74:77], v[204:207], v[134:137]
	v_mfma_f32_16x16x32_bf16 v[130:133], v[82:85], v[204:207], v[130:133]
	v_mfma_f32_16x16x32_bf16 v[118:121], v[74:77], v[212:215], v[118:121]
	v_mfma_f32_16x16x32_bf16 v[110:113], v[82:85], v[212:215], v[110:113]
	v_mfma_f32_16x16x32_bf16 v[114:117], v[74:77], v[220:223], v[114:117]
	v_mfma_f32_16x16x32_bf16 v[102:105], v[82:85], v[220:223], v[102:105]
	v_mfma_f32_16x16x32_bf16 v[150:153], v[78:81], v[166:169], v[150:153]
	v_mfma_f32_16x16x32_bf16 v[146:149], v[86:89], v[166:169], v[146:149]
	v_mfma_f32_16x16x32_bf16 v[134:137], v[78:81], v[208:211], v[134:137]
	v_mfma_f32_16x16x32_bf16 v[130:133], v[86:89], v[208:211], v[130:133]
	v_mfma_f32_16x16x32_bf16 v[118:121], v[78:81], v[216:219], v[118:121]
	v_mfma_f32_16x16x32_bf16 v[110:113], v[86:89], v[216:219], v[110:113]
	v_mfma_f32_16x16x32_bf16 v[114:117], v[78:81], v[224:227], v[114:117]
	v_mfma_f32_16x16x32_bf16 v[102:105], v[86:89], v[224:227], v[102:105]
	s_setprio 0
	s_setprio 1
	v_mfma_f32_16x16x32_bf16 v[158:161], v[90:93], v[162:165], v[158:161]
	v_mfma_f32_16x16x32_bf16 v[154:157], v[98:101], v[162:165], v[154:157]
	v_mfma_f32_16x16x32_bf16 v[142:145], v[90:93], v[204:207], v[142:145]
	v_mfma_f32_16x16x32_bf16 v[138:141], v[98:101], v[204:207], v[138:141]
	v_mfma_f32_16x16x32_bf16 v[126:129], v[90:93], v[212:215], v[126:129]
	v_mfma_f32_16x16x32_bf16 v[122:125], v[98:101], v[212:215], v[122:125]
	v_mfma_f32_16x16x32_bf16 v[70:73], v[90:93], v[220:223], v[70:73]
	v_mfma_f32_16x16x32_bf16 v[66:69], v[98:101], v[220:223], v[66:69]
	v_mfma_f32_16x16x32_bf16 v[158:161], v[94:97], v[166:169], v[158:161]
	v_mfma_f32_16x16x32_bf16 v[154:157], v[106:109], v[166:169], v[154:157]
	v_mfma_f32_16x16x32_bf16 v[142:145], v[94:97], v[208:211], v[142:145]
	v_mfma_f32_16x16x32_bf16 v[138:141], v[106:109], v[208:211], v[138:141]
	v_mfma_f32_16x16x32_bf16 v[126:129], v[94:97], v[216:219], v[126:129]
	v_mfma_f32_16x16x32_bf16 v[122:125], v[106:109], v[216:219], v[122:125]
	v_mfma_f32_16x16x32_bf16 v[70:73], v[94:97], v[224:227], v[70:73]
	v_mfma_f32_16x16x32_bf16 v[66:69], v[106:109], v[224:227], v[66:69]
	s_barrier
; #define PG8_STAGE(bufoff, gbase, voff) do { _Pragma("unroll") for (int _i = 0; _i < 2; ++_i) \
;         __builtin_amdgcn_global_load_lds((const unsigned*)((const char*)(gbase) + (voff)[_i]), (PG8_LAS unsigned*)(lds + (bufoff) + ldsw + _i * 8192), 16, 0, 0); } while (0)
; #define PG8_LDA(dst, b, h) do { _Pragma("unroll") for (int m = 0; m < 4; ++m) _Pragma("unroll") for (int k = 0; k < 2; ++k) dst[m][k] = *(const PG8_LAS bf16x8*)(lds + PG8_SA(b, h) + aoff + m * 2048 + k * 1024); } while (0)
; #define PG8_LDB(dst, b, h) do { _Pragma("unroll") for (int n = 0; n < 2; ++n) _Pragma("unroll") for (int k = 0; k < 2; ++k) dst[n][k] = *(const PG8_LAS bf16x8*)(lds + PG8_SB(b, h) + boff + n * 2048 + k * 1024); } while (0)
; #define PG8_MMA(ai, bj, At, Bt) do { __builtin_amdgcn_s_setprio(1); _Pragma("unroll") for (int m = 0; m < 4; ++m) _Pragma("unroll") for (int n = 0; n < 2; ++n) _Pragma("unroll") for (int k = 0; k < 2; ++k) \
;         acc[ai][bj][m][n] = __builtin_amdgcn_mfma_f32_16x16x32_bf16(Bt[n][k], At[m][k], acc[ai][bj][m][n], 0, 0, 0); __builtin_amdgcn_s_setprio(0); } while (0)
; #define PG8_BAR __builtin_amdgcn_s_barrier()
; template <class Epi, class Sched, bool ALIGN_EPI = false, bool SP2 = false, bool PAIR_ACC = false>
; __device__ __forceinline__ void gemm_phase(PG8_LAS unsigned char* lds, const Gemm g, const Sched& S, const Epi& E) {
;     ...
;             PG8_LDB(B0, 0, 0); PG8_LDB(B1, 0, 1); PG8_SCHED; PG8_LDA(At, 0, 0); PG8_STAGE(PG8_SA(1, 1), a1 + hstep, voffA);
;             PG8_WAIT_V(8); PG8_WAIT_L(0); PG8_BAR; PG8_MMA(0, 0, At, B0); PG8_MMA(0, 1, At, B1); PG8_BAR; PG8_SCHED;
;             PG8_LDA(At, 0, 1); PG8_STAGE(PG8_SB(0, 0), b2, voffB); PG8_STAGE(PG8_SB(0, 1), b2 + hstep, voffB); PG8_STAGE(PG8_SA(0, 0), a2, voffA);
;             PG8_WAIT_V(8); PG8_WAIT_L(0); PG8_BAR; PG8_MMA(1, 0, At, B0); PG8_MMA(1, 1, At, B1); PG8_BAR; PG8_SCHED;
;             PG8_LDB(B0, 1, 0); PG8_LDB(B1, 1, 1); PG8_SCHED; PG8_LDA(At, 1, 0); PG8_STAGE(PG8_SA(0, 1), a2 + hstep, voffA);
;             PG8_WAIT_V(8); PG8_WAIT_L(0); PG8_BAR; PG8_MMA(0, 0, At, B0); PG8_MMA(0, 1, At, B1); PG8_BAR; PG8_SCHED;
;             PG8_LDA(At, 1, 1); PG8_STAGE(PG8_SB(1, 0), b3, voffB); PG8_STAGE(PG8_SB(1, 1), b3 + hstep, voffB); PG8_STAGE(PG8_SA(1, 0), a3, voffA);
;             PG8_WAIT_V(8); PG8_WAIT_L(0); PG8_BAR; PG8_MMA(1, 0, At, B0); PG8_MMA(1, 1, At, B1); PG8_BAR; PG8_SCHED;
	s_setprio 0
	s_add_i32 s80, s70, s34
	v_lshl_add_u64 v[170:171], s[60:61], 0, v[176:177]
	s_mov_b32 m0, s80
	ds_read_b128 v[162:165], v198 offset:16384
	ds_read_b128 v[166:169], v198 offset:17408
	ds_read_b128 v[204:207], v198 offset:18432
	ds_read_b128 v[208:211], v198 offset:19456
	ds_read_b128 v[212:215], v198 offset:20480
	ds_read_b128 v[216:219], v198 offset:21504
	ds_read_b128 v[220:223], v198 offset:22528
	ds_read_b128 v[224:227], v198 offset:23552
	global_load_lds_dwordx4 v[170:171], off
	s_add_i32 m0, s80, 0x2000
	s_add_u32 s80, s60, 0x40000
	v_lshl_add_u64 v[192:193], s[60:61], 0, v[172:173]
	s_addc_u32 s81, s61, 0
	s_add_i32 s82, s71, s34
	global_load_lds_dwordx4 v[192:193], off
	v_lshl_add_u64 v[228:229], s[80:81], 0, v[176:177]
	s_mov_b32 m0, s82
	v_lshl_add_u64 v[230:231], s[62:63], 0, v[174:175]
	global_load_lds_dwordx4 v[228:229], off
	v_lshl_add_u64 v[228:229], s[80:81], 0, v[172:173]
	s_add_i32 m0, s82, 0x2000
	s_nop 0
	global_load_lds_dwordx4 v[228:229], off
	v_lshl_add_u64 v[228:229], s[62:63], 0, v[178:179]
	s_mov_b32 m0, s36
	s_nop 0
	global_load_lds_dwordx4 v[228:229], off
	s_mov_b32 m0, s37
	s_nop 0
	global_load_lds_dwordx4 v[230:231], off
	s_waitcnt vmcnt(8)
	s_waitcnt lgkmcnt(0)
	s_setprio 1
	s_barrier
	v_mfma_f32_16x16x32_bf16 v[54:57], v[74:77], v[162:165], v[54:57]
	v_mfma_f32_16x16x32_bf16 v[50:53], v[82:85], v[162:165], v[50:53]
	v_mfma_f32_16x16x32_bf16 v[38:41], v[74:77], v[204:207], v[38:41]
	v_mfma_f32_16x16x32_bf16 v[34:37], v[82:85], v[204:207], v[34:37]
	v_mfma_f32_16x16x32_bf16 v[22:25], v[74:77], v[212:215], v[22:25]
	v_mfma_f32_16x16x32_bf16 v[14:17], v[82:85], v[212:215], v[14:17]
	v_mfma_f32_16x16x32_bf16 v[18:21], v[74:77], v[220:223], v[18:21]
	v_mfma_f32_16x16x32_bf16 v[10:13], v[82:85], v[220:223], v[10:13]
	v_mfma_f32_16x16x32_bf16 v[54:57], v[78:81], v[166:169], v[54:57]
	v_mfma_f32_16x16x32_bf16 v[50:53], v[86:89], v[166:169], v[50:53]
	v_mfma_f32_16x16x32_bf16 v[38:41], v[78:81], v[208:211], v[38:41]
	v_mfma_f32_16x16x32_bf16 v[34:37], v[86:89], v[208:211], v[34:37]
	v_mfma_f32_16x16x32_bf16 v[22:25], v[78:81], v[216:219], v[22:25]
	v_mfma_f32_16x16x32_bf16 v[14:17], v[86:89], v[216:219], v[14:17]
	v_mfma_f32_16x16x32_bf16 v[18:21], v[78:81], v[224:227], v[18:21]
	v_mfma_f32_16x16x32_bf16 v[10:13], v[86:89], v[224:227], v[10:13]
	s_setprio 0
	s_setprio 1
	v_mfma_f32_16x16x32_bf16 v[62:65], v[90:93], v[162:165], v[62:65]
	v_mfma_f32_16x16x32_bf16 v[58:61], v[98:101], v[162:165], v[58:61]
	v_mfma_f32_16x16x32_bf16 v[46:49], v[90:93], v[204:207], v[46:49]
	v_mfma_f32_16x16x32_bf16 v[42:45], v[98:101], v[204:207], v[42:45]
	v_mfma_f32_16x16x32_bf16 v[30:33], v[90:93], v[212:215], v[30:33]
	v_mfma_f32_16x16x32_bf16 v[26:29], v[98:101], v[212:215], v[26:29]
	v_mfma_f32_16x16x32_bf16 v[6:9], v[90:93], v[220:223], v[6:9]
	v_mfma_f32_16x16x32_bf16 v[2:5], v[98:101], v[220:223], v[2:5]
	v_mfma_f32_16x16x32_bf16 v[62:65], v[94:97], v[166:169], v[62:65]
	v_mfma_f32_16x16x32_bf16 v[58:61], v[106:109], v[166:169], v[58:61]
	v_mfma_f32_16x16x32_bf16 v[46:49], v[94:97], v[208:211], v[46:49]
	v_mfma_f32_16x16x32_bf16 v[42:45], v[106:109], v[208:211], v[42:45]
	v_mfma_f32_16x16x32_bf16 v[30:33], v[94:97], v[216:219], v[30:33]
	v_mfma_f32_16x16x32_bf16 v[26:29], v[106:109], v[216:219], v[26:29]
	v_mfma_f32_16x16x32_bf16 v[6:9], v[94:97], v[224:227], v[6:9]
	v_mfma_f32_16x16x32_bf16 v[2:5], v[106:109], v[224:227], v[2:5]
	s_barrier
	s_setprio 0
.Lpeel_mid_1737:
	s_add_i32 s80, 0, 0x18000
	s_add_i32 s81, 0, 0x1c000
	v_add_u32_e32 v86, s80, v194
	v_add_u32_e32 v106, s81, v194
	ds_read_b128 v[74:77], v86
	ds_read_b128 v[78:81], v86 offset:1024
	ds_read_b128 v[82:85], v86 offset:2048
	ds_read_b128 v[86:89], v86 offset:3072
	ds_read_b128 v[90:93], v106
	ds_read_b128 v[94:97], v106 offset:1024
	ds_read_b128 v[98:101], v106 offset:2048
	ds_read_b128 v[106:109], v106 offset:3072
	s_add_u32 s62, s62, 0x40000
	s_addc_u32 s63, s63, 0
	s_mov_b32 m0, s49
	v_lshl_add_u64 v[232:233], s[62:63], 0, v[178:179]
	ds_read_b128 v[162:165], v198 offset:32768
	ds_read_b128 v[166:169], v198 offset:33792
	ds_read_b128 v[204:207], v198 offset:34816
	ds_read_b128 v[208:211], v198 offset:35840
	ds_read_b128 v[212:215], v198 offset:36864
	ds_read_b128 v[216:219], v198 offset:37888
	ds_read_b128 v[220:223], v198 offset:38912
	ds_read_b128 v[224:227], v198 offset:39936
	global_load_lds_dwordx4 v[232:233], off
	v_lshl_add_u64 v[232:233], s[62:63], 0, v[174:175]
	s_mov_b32 m0, s64
	s_nop 0
	global_load_lds_dwordx4 v[232:233], off
	s_waitcnt vmcnt(8)
	s_waitcnt lgkmcnt(0)
	s_setprio 1
	s_barrier
; #define PG8_STAGE(bufoff, gbase, voff) do { _Pragma("unroll") for (int _i = 0; _i < 2; ++_i) \
;         __builtin_amdgcn_global_load_lds((const unsigned*)((const char*)(gbase) + (voff)[_i]), (PG8_LAS unsigned*)(lds + (bufoff) + ldsw + _i * 8192), 16, 0, 0); } while (0)
; #define PG8_LDA(dst, b, h) do { _Pragma("unroll") for (int m = 0; m < 4; ++m) _Pragma("unroll") for (int k = 0; k < 2; ++k) dst[m][k] = *(const PG8_LAS bf16x8*)(lds + PG8_SA(b, h) + aoff + m * 2048 + k * 1024); } while (0)
; #define PG8_LDB(dst, b, h) do { _Pragma("unroll") for (int n = 0; n < 2; ++n) _Pragma("unroll") for (int k = 0; k < 2; ++k) dst[n][k] = *(const PG8_LAS bf16x8*)(lds + PG8_SB(b, h) + boff + n * 2048 + k * 1024); } while (0)
; #define PG8_MMA(ai, bj, At, Bt) do { __builtin_amdgcn_s_setprio(1); _Pragma("unroll") for (int m = 0; m < 4; ++m) _Pragma("unroll") for (int n = 0; n < 2; ++n) _Pragma("unroll") for (int k = 0; k < 2; ++k) \
;         acc[ai][bj][m][n] = __builtin_amdgcn_mfma_f32_16x16x32_bf16(Bt[n][k], At[m][k], acc[ai][bj][m][n], 0, 0, 0); __builtin_amdgcn_s_setprio(0); } while (0)
; #define PG8_BAR __builtin_amdgcn_s_barrier()
; template <class Epi, class Sched, bool ALIGN_EPI = false, bool SP2 = false, bool PAIR_ACC = false>
; __device__ __forceinline__ void gemm_phase(PG8_LAS unsigned char* lds, const Gemm g, const Sched& S, const Epi& E) {
;     ...
;             PG8_LDB(B0, 0, 0); PG8_LDB(B1, 0, 1); PG8_SCHED; PG8_LDA(At, 0, 0); PG8_STAGE(PG8_SA(1, 1), a1 + hstep, voffA);
;             PG8_WAIT_V(8); PG8_WAIT_L(0); PG8_BAR; PG8_MMA(0, 0, At, B0); PG8_MMA(0, 1, At, B1); PG8_BAR; PG8_SCHED;
;             PG8_LDA(At, 0, 1); PG8_STAGE(PG8_SB(0, 0), b2, voffB); PG8_STAGE(PG8_SB(0, 1), b2 + hstep, voffB); PG8_STAGE(PG8_SA(0, 0), a2, voffA);
;             PG8_WAIT_V(8); PG8_WAIT_L(0); PG8_BAR; PG8_MMA(1, 0, At, B0); PG8_MMA(1, 1, At, B1); PG8_BAR; PG8_SCHED;
;             PG8_LDB(B0, 1, 0); PG8_LDB(B1, 1, 1); PG8_SCHED; PG8_LDA(At, 1, 0); PG8_STAGE(PG8_SA(0, 1), a2 + hstep, voffA);
;             PG8_WAIT_V(8); PG8_WAIT_L(0); PG8_BAR; PG8_MMA(0, 0, At, B0); PG8_MMA(0, 1, At, B1); PG8_BAR; PG8_SCHED;
;             PG8_LDA(At, 1, 1); PG8_STAGE(PG8_SB(1, 0), b3, voffB); PG8_STAGE(PG8_SB(1, 1), b3 + hstep, voffB); PG8_STAGE(PG8_SA(1, 0), a3, voffA);
;             PG8_WAIT_V(8); PG8_WAIT_L(0); PG8_BAR; PG8_MMA(1, 0, At, B0); PG8_MMA(1, 1, At, B1); PG8_BAR; PG8_SCHED;
	v_mfma_f32_16x16x32_bf16 v[150:153], v[74:77], v[162:165], v[150:153]
	v_mfma_f32_16x16x32_bf16 v[146:149], v[82:85], v[162:165], v[146:149]
	v_mfma_f32_16x16x32_bf16 v[134:137], v[74:77], v[204:207], v[134:137]
	v_mfma_f32_16x16x32_bf16 v[130:133], v[82:85], v[204:207], v[130:133]
	v_mfma_f32_16x16x32_bf16 v[118:121], v[74:77], v[212:215], v[118:121]
	v_mfma_f32_16x16x32_bf16 v[110:113], v[82:85], v[212:215], v[110:113]
	v_mfma_f32_16x16x32_bf16 v[114:117], v[74:77], v[220:223], v[114:117]
	v_mfma_f32_16x16x32_bf16 v[102:105], v[82:85], v[220:223], v[102:105]
	v_mfma_f32_16x16x32_bf16 v[150:153], v[78:81], v[166:169], v[150:153]
	v_mfma_f32_16x16x32_bf16 v[146:149], v[86:89], v[166:169], v[146:149]
	v_mfma_f32_16x16x32_bf16 v[134:137], v[78:81], v[208:211], v[134:137]
	v_mfma_f32_16x16x32_bf16 v[130:133], v[86:89], v[208:211], v[130:133]
	v_mfma_f32_16x16x32_bf16 v[118:121], v[78:81], v[216:219], v[118:121]
	v_mfma_f32_16x16x32_bf16 v[110:113], v[86:89], v[216:219], v[110:113]
	v_mfma_f32_16x16x32_bf16 v[114:117], v[78:81], v[224:227], v[114:117]
	v_mfma_f32_16x16x32_bf16 v[102:105], v[86:89], v[224:227], v[102:105]
	s_setprio 0
	s_setprio 1
	v_mfma_f32_16x16x32_bf16 v[158:161], v[90:93], v[162:165], v[158:161]
	v_mfma_f32_16x16x32_bf16 v[154:157], v[98:101], v[162:165], v[154:157]
	v_mfma_f32_16x16x32_bf16 v[142:145], v[90:93], v[204:207], v[142:145]
	v_mfma_f32_16x16x32_bf16 v[138:141], v[98:101], v[204:207], v[138:141]
	v_mfma_f32_16x16x32_bf16 v[126:129], v[90:93], v[212:215], v[126:129]
	v_mfma_f32_16x16x32_bf16 v[122:125], v[98:101], v[212:215], v[122:125]
	v_mfma_f32_16x16x32_bf16 v[70:73], v[90:93], v[220:223], v[70:73]
	v_mfma_f32_16x16x32_bf16 v[66:69], v[98:101], v[220:223], v[66:69]
	v_mfma_f32_16x16x32_bf16 v[158:161], v[94:97], v[166:169], v[158:161]
	v_mfma_f32_16x16x32_bf16 v[154:157], v[106:109], v[166:169], v[154:157]
	v_mfma_f32_16x16x32_bf16 v[142:145], v[94:97], v[208:211], v[142:145]
	v_mfma_f32_16x16x32_bf16 v[138:141], v[106:109], v[208:211], v[138:141]
	v_mfma_f32_16x16x32_bf16 v[126:129], v[94:97], v[216:219], v[126:129]
	v_mfma_f32_16x16x32_bf16 v[122:125], v[106:109], v[216:219], v[122:125]
	v_mfma_f32_16x16x32_bf16 v[70:73], v[94:97], v[224:227], v[70:73]
	v_mfma_f32_16x16x32_bf16 v[66:69], v[106:109], v[224:227], v[66:69]
	s_barrier
	s_setprio 0
	s_add_i32 s62, s80, s34
	v_lshl_add_u64 v[170:171], v[170:171], 0, s[30:31]
	s_mov_b32 m0, s62
	ds_read_b128 v[162:165], v198 offset:49152
	ds_read_b128 v[166:169], v198 offset:50176
	ds_read_b128 v[204:207], v198 offset:51200
	ds_read_b128 v[208:211], v198 offset:52224
	ds_read_b128 v[212:215], v198 offset:53248
	ds_read_b128 v[216:219], v198 offset:54272
	ds_read_b128 v[220:223], v198 offset:55296
	ds_read_b128 v[224:227], v198 offset:56320
	global_load_lds_dwordx4 v[170:171], off
	s_add_i32 m0, s62, 0x2000
	s_add_u32 s60, s60, 0x40080
	v_lshl_add_u64 v[170:171], v[192:193], 0, s[30:31]
	s_addc_u32 s61, s61, 0
	s_add_i32 s62, s81, s34
	global_load_lds_dwordx4 v[170:171], off
	v_lshl_add_u64 v[170:171], s[60:61], 0, v[176:177]
	s_mov_b32 m0, s62
	s_nop 0
	global_load_lds_dwordx4 v[170:171], off
	v_lshl_add_u64 v[170:171], s[60:61], 0, v[172:173]
	s_add_i32 m0, s62, 0x2000
	s_nop 0
	global_load_lds_dwordx4 v[170:171], off
	v_lshl_add_u64 v[170:171], v[228:229], 0, s[30:31]
	s_mov_b32 m0, s68
	s_nop 0
	global_load_lds_dwordx4 v[170:171], off
	v_lshl_add_u64 v[170:171], v[230:231], 0, s[30:31]
	s_mov_b32 m0, s69
	s_nop 0
	global_load_lds_dwordx4 v[170:171], off
	s_waitcnt vmcnt(8)
	s_waitcnt lgkmcnt(0)
	s_setprio 1
	s_barrier
	v_mfma_f32_16x16x32_bf16 v[54:57], v[74:77], v[162:165], v[54:57]
	v_mfma_f32_16x16x32_bf16 v[50:53], v[82:85], v[162:165], v[50:53]
	v_mfma_f32_16x16x32_bf16 v[38:41], v[74:77], v[204:207], v[38:41]
	v_mfma_f32_16x16x32_bf16 v[34:37], v[82:85], v[204:207], v[34:37]
	v_mfma_f32_16x16x32_bf16 v[22:25], v[74:77], v[212:215], v[22:25]
	v_mfma_f32_16x16x32_bf16 v[14:17], v[82:85], v[212:215], v[14:17]
	v_mfma_f32_16x16x32_bf16 v[18:21], v[74:77], v[220:223], v[18:21]
	v_mfma_f32_16x16x32_bf16 v[10:13], v[82:85], v[220:223], v[10:13]
	v_mfma_f32_16x16x32_bf16 v[54:57], v[78:81], v[166:169], v[54:57]
	v_mfma_f32_16x16x32_bf16 v[50:53], v[86:89], v[166:169], v[50:53]
	v_mfma_f32_16x16x32_bf16 v[38:41], v[78:81], v[208:211], v[38:41]
	v_mfma_f32_16x16x32_bf16 v[34:37], v[86:89], v[208:211], v[34:37]
	v_mfma_f32_16x16x32_bf16 v[22:25], v[78:81], v[216:219], v[22:25]
	v_mfma_f32_16x16x32_bf16 v[14:17], v[86:89], v[216:219], v[14:17]
	v_mfma_f32_16x16x32_bf16 v[18:21], v[78:81], v[224:227], v[18:21]
	v_mfma_f32_16x16x32_bf16 v[10:13], v[86:89], v[224:227], v[10:13]
	s_setprio 0
	s_setprio 1
	v_mfma_f32_16x16x32_bf16 v[62:65], v[90:93], v[162:165], v[62:65]
	v_mfma_f32_16x16x32_bf16 v[58:61], v[98:101], v[162:165], v[58:61]
	v_mfma_f32_16x16x32_bf16 v[46:49], v[90:93], v[204:207], v[46:49]
	v_mfma_f32_16x16x32_bf16 v[42:45], v[98:101], v[204:207], v[42:45]
	v_mfma_f32_16x16x32_bf16 v[30:33], v[90:93], v[212:215], v[30:33]
	v_mfma_f32_16x16x32_bf16 v[26:29], v[98:101], v[212:215], v[26:29]
	v_mfma_f32_16x16x32_bf16 v[6:9], v[90:93], v[220:223], v[6:9]
	v_mfma_f32_16x16x32_bf16 v[2:5], v[98:101], v[220:223], v[2:5]
	v_mfma_f32_16x16x32_bf16 v[62:65], v[94:97], v[166:169], v[62:65]
	v_mfma_f32_16x16x32_bf16 v[58:61], v[106:109], v[166:169], v[58:61]
	v_mfma_f32_16x16x32_bf16 v[46:49], v[94:97], v[208:211], v[46:49]
	v_mfma_f32_16x16x32_bf16 v[42:45], v[106:109], v[208:211], v[42:45]
	v_mfma_f32_16x16x32_bf16 v[30:33], v[94:97], v[216:219], v[30:33]
	v_mfma_f32_16x16x32_bf16 v[26:29], v[106:109], v[216:219], v[26:29]
	v_mfma_f32_16x16x32_bf16 v[6:9], v[94:97], v[224:227], v[6:9]
	v_mfma_f32_16x16x32_bf16 v[2:5], v[106:109], v[224:227], v[2:5]
	s_barrier
	s_setprio 0
	s_add_i32 s79, s79, 2
	s_add_u32 s10, s10, 0x100
	s_addc_u32 s11, s11, 0
	s_add_u32 s77, s77, 0x100
	s_addc_u32 s78, s78, 0
	s_cmp_gt_u32 s79, 13
	s_cbranch_scc0 .LBB0_1737
	s_and_b64 vcc, exec, s[38:39]
	s_cbranch_vccz .LBB0_1740
	s_barrier

; #define PG8_STAGE(bufoff, gbase, voff) do { _Pragma("unroll") for (int _i = 0; _i < 2; ++_i) \
;         __builtin_amdgcn_global_load_lds((const unsigned*)((const char*)(gbase) + (voff)[_i]), (PG8_LAS unsigned*)(lds + (bufoff) + ldsw + _i * 8192), 16, 0, 0); } while (0)
; #define PG8_WAIT_V(n) asm volatile("s_waitcnt vmcnt(" #n ")" ::: "memory")
; #define PG8_WAIT_L(n) asm volatile("s_waitcnt lgkmcnt(" #n ")" ::: "memory")
; template <class Epi, class Sched, bool ALIGN_EPI = false, bool SP2 = false, bool PAIR_ACC = false>
; __device__ __forceinline__ void gemm_phase(PG8_LAS unsigned char* lds, const Gemm g, const Sched& S, const Epi& E) {
;     ...
;         const bool has_next = S.next(ui + 1, nxt);
;         const char* nA = has_next ? (const char*)g.A + (size_t)nxt.pm * tstep + (size_t)(nxt.pn / g.a_div) * g.a_sel : cA; const char* nB = has_next ? (const char*)g.Bt + (size_t)nxt.pn * tstep : cB;
;         for (int t = 0; t < nt; t += 2) {
;             const bool last = (t == nt - 2);
;             const char* a1 = cA + (size_t)(t + 1) * kstep;
;             const char* a2 = last ? nA : cA + (size_t)(t + 2) * kstep; const char* b2 = last ? nB : cB + (size_t)(t + 2) * kstep;
;             const char* a3 = a2 + kstep; const char* b3 = b2 + kstep;
;             if (last && has_next) S.a_ready(nxt);
;             if constexpr (SP2) {
;             PG8_LDB(B0, 0, 0); PG8_LDB(B1, 0, 1); PG8_SCHED; PG8_LDA(At, 0, 0); PG8_STAGE(PG8_SA(1, 1), a1 + hstep, voffA);
;             PG8_WAIT_V(8); PG8_WAIT_L(0); PG8_BAR; PG8_MMA(0, 0, At, B0); PG8_MMA(0, 1, At, B1); PG8_BAR; PG8_SCHED;
;             PG8_LDA(At, 0, 1); PG8_STAGE(PG8_SB(0, 0), b2, voffB); PG8_STAGE(PG8_SB(0, 1), b2 + hstep, voffB); PG8_STAGE(PG8_SA(0, 0), a2, voffA);
;             PG8_WAIT_V(8); PG8_WAIT_L(0); PG8_BAR; PG8_MMA(1, 0, At, B0); PG8_MMA(1, 1, At, B1); PG8_BAR; PG8_SCHED;
;             PG8_LDB(B0, 1, 0); PG8_LDB(B1, 1, 1); PG8_SCHED; PG8_LDA(At, 1, 0); PG8_STAGE(PG8_SA(0, 1), a2 + hstep, voffA);
;             PG8_WAIT_V(8); PG8_WAIT_L(0); PG8_BAR; PG8_MMA(0, 0, At, B0); PG8_MMA(0, 1, At, B1); PG8_BAR; PG8_SCHED;
;             PG8_LDA(At, 1, 1); PG8_STAGE(PG8_SB(1, 0), b3, voffB); PG8_STAGE(PG8_SB(1, 1), b3 + hstep, voffB); PG8_STAGE(PG8_SA(1, 0), a3, voffA);
;             PG8_WAIT_V(8); PG8_WAIT_L(0); PG8_BAR; PG8_MMA(1, 0, At, B0); PG8_MMA(1, 1, At, B1); PG8_BAR; PG8_SCHED;
.LBB0_1840:
	v_add_u32_e32 v164, s45, v150
	ds_read_b128 v[152:155], v164
	ds_read_b128 v[156:159], v164 offset:1024
	ds_read_b128 v[160:163], v164 offset:2048
	ds_read_b128 v[168:171], v164 offset:3072
	v_add_u32_e32 v164, s46, v150
	s_add_u32 s26, s18, s24
	ds_read_b128 v[172:175], v164
	ds_read_b128 v[176:179], v164 offset:1024
	ds_read_b128 v[180:183], v164 offset:2048
	ds_read_b128 v[184:187], v164 offset:3072
	s_addc_u32 s27, s19, s25
	s_add_u32 s26, s26, 0x100
	s_addc_u32 s27, s27, 0
	s_add_u32 s53, s50, s24
	s_addc_u32 s54, s51, s25
	s_cmpk_eq_i32 s24, 0x1500
	s_cselect_b32 s29, s23, s27
	s_cselect_b32 s28, s22, s26
	s_cselect_b32 s27, s5, s54
	s_cselect_b32 s26, s4, s53
	v_lshl_add_u64 v[164:165], v[146:147], 0, s[24:25]
	s_add_i32 m0, s38, 0xc000
	ds_read_b128 v[188:191], v151
	ds_read_b128 v[192:195], v151 offset:1024
	ds_read_b128 v[196:199], v151 offset:2048
	ds_read_b128 v[200:203], v151 offset:3072
	ds_read_b128 v[204:207], v151 offset:4096
	ds_read_b128 v[208:211], v151 offset:5120
	ds_read_b128 v[212:215], v151 offset:6144
	ds_read_b128 v[216:219], v151 offset:7168
	global_load_lds_dwordx4 v[164:165], off
	v_lshl_add_u64 v[164:165], v[148:149], 0, s[24:25]
	s_add_i32 m0, s38, 0xe000
	s_nop 0
	global_load_lds_dwordx4 v[164:165], off
	s_waitcnt vmcnt(8)
	s_waitcnt lgkmcnt(0)
	s_setprio 1
	s_barrier
	v_mfma_f32_16x16x32_bf16 v[102:105], v[152:155], v[188:191], v[102:105]
	v_mfma_f32_16x16x32_bf16 v[106:109], v[160:163], v[188:191], v[106:109]
	v_mfma_f32_16x16x32_bf16 v[114:117], v[152:155], v[196:199], v[114:117]
	v_mfma_f32_16x16x32_bf16 v[118:121], v[160:163], v[196:199], v[118:121]
	v_mfma_f32_16x16x32_bf16 v[126:129], v[152:155], v[204:207], v[126:129]
	v_mfma_f32_16x16x32_bf16 v[122:125], v[160:163], v[204:207], v[122:125]
	v_mfma_f32_16x16x32_bf16 v[78:81], v[152:155], v[212:215], v[78:81]
	v_mfma_f32_16x16x32_bf16 v[74:77], v[160:163], v[212:215], v[74:77]
	v_mfma_f32_16x16x32_bf16 v[102:105], v[156:159], v[192:195], v[102:105]
	v_mfma_f32_16x16x32_bf16 v[106:109], v[168:171], v[192:195], v[106:109]
	v_mfma_f32_16x16x32_bf16 v[114:117], v[156:159], v[200:203], v[114:117]
	v_mfma_f32_16x16x32_bf16 v[118:121], v[168:171], v[200:203], v[118:121]
	v_mfma_f32_16x16x32_bf16 v[126:129], v[156:159], v[208:211], v[126:129]
	v_mfma_f32_16x16x32_bf16 v[122:125], v[168:171], v[208:211], v[122:125]
	v_mfma_f32_16x16x32_bf16 v[78:81], v[156:159], v[216:219], v[78:81]
	v_mfma_f32_16x16x32_bf16 v[74:77], v[168:171], v[216:219], v[74:77]
	s_setprio 0
	s_setprio 1
	v_mfma_f32_16x16x32_bf16 v[86:89], v[172:175], v[188:191], v[86:89]
	v_mfma_f32_16x16x32_bf16 v[82:85], v[180:183], v[188:191], v[82:85]
	v_mfma_f32_16x16x32_bf16 v[94:97], v[172:175], v[196:199], v[94:97]
	v_mfma_f32_16x16x32_bf16 v[90:93], v[180:183], v[196:199], v[90:93]
	v_mfma_f32_16x16x32_bf16 v[110:113], v[172:175], v[204:207], v[110:113]
	v_mfma_f32_16x16x32_bf16 v[98:101], v[180:183], v[204:207], v[98:101]
	v_mfma_f32_16x16x32_bf16 v[70:73], v[172:175], v[212:215], v[70:73]
	v_mfma_f32_16x16x32_bf16 v[66:69], v[180:183], v[212:215], v[66:69]
	v_mfma_f32_16x16x32_bf16 v[86:89], v[176:179], v[192:195], v[86:89]
	v_mfma_f32_16x16x32_bf16 v[82:85], v[184:187], v[192:195], v[82:85]
	v_mfma_f32_16x16x32_bf16 v[94:97], v[176:179], v[200:203], v[94:97]
	v_mfma_f32_16x16x32_bf16 v[90:93], v[184:187], v[200:203], v[90:93]
	v_mfma_f32_16x16x32_bf16 v[110:113], v[176:179], v[208:211], v[110:113]
	v_mfma_f32_16x16x32_bf16 v[98:101], v[184:187], v[208:211], v[98:101]
	v_mfma_f32_16x16x32_bf16 v[70:73], v[176:179], v[216:219], v[70:73]
	v_mfma_f32_16x16x32_bf16 v[66:69], v[184:187], v[216:219], v[66:69]
	s_barrier
	s_setprio 0
	s_add_i32 s53, s45, s37
	v_lshl_add_u64 v[164:165], s[26:27], 0, v[132:133]
	s_mov_b32 m0, s53
	ds_read_b128 v[188:191], v151 offset:16384
	ds_read_b128 v[192:195], v151 offset:17408
	ds_read_b128 v[196:199], v151 offset:18432
	ds_read_b128 v[200:203], v151 offset:19456
	ds_read_b128 v[204:207], v151 offset:20480
	ds_read_b128 v[208:211], v151 offset:21504
	ds_read_b128 v[212:215], v151 offset:22528
	ds_read_b128 v[216:219], v151 offset:23552
	global_load_lds_dwordx4 v[164:165], off
	s_add_i32 m0, s53, 0x2000
	s_add_u32 s54, s26, 0xb0000
	v_lshl_add_u64 v[220:221], s[26:27], 0, v[136:137]
	s_addc_u32 s55, s27, 0
	s_add_i32 s53, s46, s37
	global_load_lds_dwordx4 v[220:221], off
	v_lshl_add_u64 v[222:223], s[54:55], 0, v[132:133]
	s_mov_b32 m0, s53
	v_lshl_add_u64 v[224:225], s[28:29], 0, v[134:135]
	global_load_lds_dwordx4 v[222:223], off
	v_lshl_add_u64 v[222:223], s[54:55], 0, v[136:137]
	s_add_i32 m0, s53, 0x2000
	s_nop 0
	global_load_lds_dwordx4 v[222:223], off
	v_lshl_add_u64 v[222:223], s[28:29], 0, v[130:131]
	s_mov_b32 m0, s38
	s_nop 0
	global_load_lds_dwordx4 v[222:223], off
	s_mov_b32 m0, s39
	s_nop 0
	global_load_lds_dwordx4 v[224:225], off
	s_waitcnt vmcnt(8)
	s_waitcnt lgkmcnt(0)
	s_setprio 1
	s_barrier
; #define PG8_STAGE(bufoff, gbase, voff) do { _Pragma("unroll") for (int _i = 0; _i < 2; ++_i) \
;         __builtin_amdgcn_global_load_lds((const unsigned*)((const char*)(gbase) + (voff)[_i]), (PG8_LAS unsigned*)(lds + (bufoff) + ldsw + _i * 8192), 16, 0, 0); } while (0)
; #define PG8_LDA(dst, b, h) do { _Pragma("unroll") for (int m = 0; m < 4; ++m) _Pragma("unroll") for (int k = 0; k < 2; ++k) dst[m][k] = *(const PG8_LAS bf16x8*)(lds + PG8_SA(b, h) + aoff + m * 2048 + k * 1024); } while (0)
; #define PG8_LDB(dst, b, h) do { _Pragma("unroll") for (int n = 0; n < 2; ++n) _Pragma("unroll") for (int k = 0; k < 2; ++k) dst[n][k] = *(const PG8_LAS bf16x8*)(lds + PG8_SB(b, h) + boff + n * 2048 + k * 1024); } while (0)
; #define PG8_MMA(ai, bj, At, Bt) do { __builtin_amdgcn_s_setprio(1); _Pragma("unroll") for (int m = 0; m < 4; ++m) _Pragma("unroll") for (int n = 0; n < 2; ++n) _Pragma("unroll") for (int k = 0; k < 2; ++k) \
;         acc[ai][bj][m][n] = __builtin_amdgcn_mfma_f32_16x16x32_bf16(Bt[n][k], At[m][k], acc[ai][bj][m][n], 0, 0, 0); __builtin_amdgcn_s_setprio(0); } while (0)
; #define PG8_BAR __builtin_amdgcn_s_barrier()
; template <class Epi, class Sched, bool ALIGN_EPI = false, bool SP2 = false, bool PAIR_ACC = false>
; __device__ __forceinline__ void gemm_phase(PG8_LAS unsigned char* lds, const Gemm g, const Sched& S, const Epi& E) {
;     ...
;             PG8_LDB(B0, 0, 0); PG8_LDB(B1, 0, 1); PG8_SCHED; PG8_LDA(At, 0, 0); PG8_STAGE(PG8_SA(1, 1), a1 + hstep, voffA);
;             PG8_WAIT_V(8); PG8_WAIT_L(0); PG8_BAR; PG8_MMA(0, 0, At, B0); PG8_MMA(0, 1, At, B1); PG8_BAR; PG8_SCHED;
;             PG8_LDA(At, 0, 1); PG8_STAGE(PG8_SB(0, 0), b2, voffB); PG8_STAGE(PG8_SB(0, 1), b2 + hstep, voffB); PG8_STAGE(PG8_SA(0, 0), a2, voffA);
;             PG8_WAIT_V(8); PG8_WAIT_L(0); PG8_BAR; PG8_MMA(1, 0, At, B0); PG8_MMA(1, 1, At, B1); PG8_BAR; PG8_SCHED;
;             PG8_LDB(B0, 1, 0); PG8_LDB(B1, 1, 1); PG8_SCHED; PG8_LDA(At, 1, 0); PG8_STAGE(PG8_SA(0, 1), a2 + hstep, voffA);
;             PG8_WAIT_V(8); PG8_WAIT_L(0); PG8_BAR; PG8_MMA(0, 0, At, B0); PG8_MMA(0, 1, At, B1); PG8_BAR; PG8_SCHED;
;             PG8_LDA(At, 1, 1); PG8_STAGE(PG8_SB(1, 0), b3, voffB); PG8_STAGE(PG8_SB(1, 1), b3 + hstep, voffB); PG8_STAGE(PG8_SA(1, 0), a3, voffA);
;             PG8_WAIT_V(8); PG8_WAIT_L(0); PG8_BAR; PG8_MMA(1, 0, At, B0); PG8_MMA(1, 1, At, B1); PG8_BAR; PG8_SCHED;
	v_mfma_f32_16x16x32_bf16 v[62:65], v[152:155], v[188:191], v[62:65]
	v_mfma_f32_16x16x32_bf16 v[58:61], v[160:163], v[188:191], v[58:61]
	v_mfma_f32_16x16x32_bf16 v[46:49], v[152:155], v[196:199], v[46:49]
	v_mfma_f32_16x16x32_bf16 v[42:45], v[160:163], v[196:199], v[42:45]
	v_mfma_f32_16x16x32_bf16 v[30:33], v[152:155], v[204:207], v[30:33]
	v_mfma_f32_16x16x32_bf16 v[26:29], v[160:163], v[204:207], v[26:29]
	v_mfma_f32_16x16x32_bf16 v[14:17], v[152:155], v[212:215], v[14:17]
	v_mfma_f32_16x16x32_bf16 v[10:13], v[160:163], v[212:215], v[10:13]
	v_mfma_f32_16x16x32_bf16 v[62:65], v[156:159], v[192:195], v[62:65]
	v_mfma_f32_16x16x32_bf16 v[58:61], v[168:171], v[192:195], v[58:61]
	v_mfma_f32_16x16x32_bf16 v[46:49], v[156:159], v[200:203], v[46:49]
	v_mfma_f32_16x16x32_bf16 v[42:45], v[168:171], v[200:203], v[42:45]
	v_mfma_f32_16x16x32_bf16 v[30:33], v[156:159], v[208:211], v[30:33]
	v_mfma_f32_16x16x32_bf16 v[26:29], v[168:171], v[208:211], v[26:29]
	v_mfma_f32_16x16x32_bf16 v[14:17], v[156:159], v[216:219], v[14:17]
	v_mfma_f32_16x16x32_bf16 v[10:13], v[168:171], v[216:219], v[10:13]
	s_setprio 0
	s_setprio 1
	v_mfma_f32_16x16x32_bf16 v[54:57], v[172:175], v[188:191], v[54:57]
	v_mfma_f32_16x16x32_bf16 v[50:53], v[180:183], v[188:191], v[50:53]
	v_mfma_f32_16x16x32_bf16 v[38:41], v[172:175], v[196:199], v[38:41]
	v_mfma_f32_16x16x32_bf16 v[34:37], v[180:183], v[196:199], v[34:37]
	v_mfma_f32_16x16x32_bf16 v[22:25], v[172:175], v[204:207], v[22:25]
	v_mfma_f32_16x16x32_bf16 v[18:21], v[180:183], v[204:207], v[18:21]
	v_mfma_f32_16x16x32_bf16 v[6:9], v[172:175], v[212:215], v[6:9]
	v_mfma_f32_16x16x32_bf16 v[2:5], v[180:183], v[212:215], v[2:5]
	v_mfma_f32_16x16x32_bf16 v[54:57], v[176:179], v[192:195], v[54:57]
	v_mfma_f32_16x16x32_bf16 v[50:53], v[184:187], v[192:195], v[50:53]
	v_mfma_f32_16x16x32_bf16 v[38:41], v[176:179], v[200:203], v[38:41]
	v_mfma_f32_16x16x32_bf16 v[34:37], v[184:187], v[200:203], v[34:37]
	v_mfma_f32_16x16x32_bf16 v[22:25], v[176:179], v[208:211], v[22:25]
	v_mfma_f32_16x16x32_bf16 v[18:21], v[184:187], v[208:211], v[18:21]
	v_mfma_f32_16x16x32_bf16 v[6:9], v[176:179], v[216:219], v[6:9]
	v_mfma_f32_16x16x32_bf16 v[2:5], v[184:187], v[216:219], v[2:5]
	s_barrier
	s_setprio 0
	s_add_i32 s53, 0, 0x18000
	s_add_i32 s54, 0, 0x1c000
	v_add_u32_e32 v168, s53, v150
	v_add_u32_e32 v184, s54, v150
	ds_read_b128 v[152:155], v168
	ds_read_b128 v[156:159], v168 offset:1024
	ds_read_b128 v[160:163], v168 offset:2048
	ds_read_b128 v[168:171], v168 offset:3072
	ds_read_b128 v[172:175], v184
	ds_read_b128 v[176:179], v184 offset:1024
	ds_read_b128 v[180:183], v184 offset:2048
	ds_read_b128 v[184:187], v184 offset:3072
	s_add_u32 s28, s28, 0xb0000
	s_addc_u32 s29, s29, 0
	s_mov_b32 m0, s40
	v_lshl_add_u64 v[226:227], s[28:29], 0, v[130:131]
	ds_read_b128 v[188:191], v151 offset:32768
	ds_read_b128 v[192:195], v151 offset:33792
	ds_read_b128 v[196:199], v151 offset:34816
	ds_read_b128 v[200:203], v151 offset:35840
	ds_read_b128 v[204:207], v151 offset:36864
	ds_read_b128 v[208:211], v151 offset:37888
	ds_read_b128 v[212:215], v151 offset:38912
	ds_read_b128 v[216:219], v151 offset:39936
	global_load_lds_dwordx4 v[226:227], off
	v_lshl_add_u64 v[226:227], s[28:29], 0, v[134:135]
	s_mov_b32 m0, s41
	s_nop 0
	global_load_lds_dwordx4 v[226:227], off
	s_waitcnt vmcnt(8)
	s_waitcnt lgkmcnt(0)
	s_setprio 1
	s_barrier
	v_mfma_f32_16x16x32_bf16 v[102:105], v[152:155], v[188:191], v[102:105]
	v_mfma_f32_16x16x32_bf16 v[106:109], v[160:163], v[188:191], v[106:109]
	v_mfma_f32_16x16x32_bf16 v[114:117], v[152:155], v[196:199], v[114:117]
	v_mfma_f32_16x16x32_bf16 v[118:121], v[160:163], v[196:199], v[118:121]
	v_mfma_f32_16x16x32_bf16 v[126:129], v[152:155], v[204:207], v[126:129]
	v_mfma_f32_16x16x32_bf16 v[122:125], v[160:163], v[204:207], v[122:125]
	v_mfma_f32_16x16x32_bf16 v[78:81], v[152:155], v[212:215], v[78:81]
	v_mfma_f32_16x16x32_bf16 v[74:77], v[160:163], v[212:215], v[74:77]
	v_mfma_f32_16x16x32_bf16 v[102:105], v[156:159], v[192:195], v[102:105]
	v_mfma_f32_16x16x32_bf16 v[106:109], v[168:171], v[192:195], v[106:109]
	v_mfma_f32_16x16x32_bf16 v[114:117], v[156:159], v[200:203], v[114:117]
	v_mfma_f32_16x16x32_bf16 v[118:121], v[168:171], v[200:203], v[118:121]
	v_mfma_f32_16x16x32_bf16 v[126:129], v[156:159], v[208:211], v[126:129]
	v_mfma_f32_16x16x32_bf16 v[122:125], v[168:171], v[208:211], v[122:125]
	v_mfma_f32_16x16x32_bf16 v[78:81], v[156:159], v[216:219], v[78:81]
	v_mfma_f32_16x16x32_bf16 v[74:77], v[168:171], v[216:219], v[74:77]
	s_setprio 0
	s_setprio 1
	v_mfma_f32_16x16x32_bf16 v[86:89], v[172:175], v[188:191], v[86:89]
	v_mfma_f32_16x16x32_bf16 v[82:85], v[180:183], v[188:191], v[82:85]
	v_mfma_f32_16x16x32_bf16 v[94:97], v[172:175], v[196:199], v[94:97]
	v_mfma_f32_16x16x32_bf16 v[90:93], v[180:183], v[196:199], v[90:93]
	v_mfma_f32_16x16x32_bf16 v[110:113], v[172:175], v[204:207], v[110:113]
	v_mfma_f32_16x16x32_bf16 v[98:101], v[180:183], v[204:207], v[98:101]
	v_mfma_f32_16x16x32_bf16 v[70:73], v[172:175], v[212:215], v[70:73]
	v_mfma_f32_16x16x32_bf16 v[66:69], v[180:183], v[212:215], v[66:69]
	v_mfma_f32_16x16x32_bf16 v[86:89], v[176:179], v[192:195], v[86:89]
	v_mfma_f32_16x16x32_bf16 v[82:85], v[184:187], v[192:195], v[82:85]
	v_mfma_f32_16x16x32_bf16 v[94:97], v[176:179], v[200:203], v[94:97]
	v_mfma_f32_16x16x32_bf16 v[90:93], v[184:187], v[200:203], v[90:93]
	v_mfma_f32_16x16x32_bf16 v[110:113], v[176:179], v[208:211], v[110:113]
	v_mfma_f32_16x16x32_bf16 v[98:101], v[184:187], v[208:211], v[98:101]
	v_mfma_f32_16x16x32_bf16 v[70:73], v[176:179], v[216:219], v[70:73]
	v_mfma_f32_16x16x32_bf16 v[66:69], v[184:187], v[216:219], v[66:69]
	s_barrier
; #define PG8_STAGE(bufoff, gbase, voff) do { _Pragma("unroll") for (int _i = 0; _i < 2; ++_i) \
;         __builtin_amdgcn_global_load_lds((const unsigned*)((const char*)(gbase) + (voff)[_i]), (PG8_LAS unsigned*)(lds + (bufoff) + ldsw + _i * 8192), 16, 0, 0); } while (0)
; #define PG8_LDA(dst, b, h) do { _Pragma("unroll") for (int m = 0; m < 4; ++m) _Pragma("unroll") for (int k = 0; k < 2; ++k) dst[m][k] = *(const PG8_LAS bf16x8*)(lds + PG8_SA(b, h) + aoff + m * 2048 + k * 1024); } while (0)
; #define PG8_LDB(dst, b, h) do { _Pragma("unroll") for (int n = 0; n < 2; ++n) _Pragma("unroll") for (int k = 0; k < 2; ++k) dst[n][k] = *(const PG8_LAS bf16x8*)(lds + PG8_SB(b, h) + boff + n * 2048 + k * 1024); } while (0)
; #define PG8_BAR __builtin_amdgcn_s_barrier()
; template <class Epi, class Sched, bool ALIGN_EPI = false, bool SP2 = false, bool PAIR_ACC = false>
; __device__ __forceinline__ void gemm_phase(PG8_LAS unsigned char* lds, const Gemm g, const Sched& S, const Epi& E) {
;     ...
;             PG8_LDB(B0, 0, 0); PG8_LDB(B1, 0, 1); PG8_SCHED; PG8_LDA(At, 0, 0); PG8_STAGE(PG8_SA(1, 1), a1 + hstep, voffA);
;             PG8_WAIT_V(8); PG8_WAIT_L(0); PG8_BAR; PG8_MMA(0, 0, At, B0); PG8_MMA(0, 1, At, B1); PG8_BAR; PG8_SCHED;
;             PG8_LDA(At, 0, 1); PG8_STAGE(PG8_SB(0, 0), b2, voffB); PG8_STAGE(PG8_SB(0, 1), b2 + hstep, voffB); PG8_STAGE(PG8_SA(0, 0), a2, voffA);
;             PG8_WAIT_V(8); PG8_WAIT_L(0); PG8_BAR; PG8_MMA(1, 0, At, B0); PG8_MMA(1, 1, At, B1); PG8_BAR; PG8_SCHED;
;             PG8_LDB(B0, 1, 0); PG8_LDB(B1, 1, 1); PG8_SCHED; PG8_LDA(At, 1, 0); PG8_STAGE(PG8_SA(0, 1), a2 + hstep, voffA);
;             PG8_WAIT_V(8); PG8_WAIT_L(0); PG8_BAR; PG8_MMA(0, 0, At, B0); PG8_MMA(0, 1, At, B1); PG8_BAR; PG8_SCHED;
;             PG8_LDA(At, 1, 1); PG8_STAGE(PG8_SB(1, 0), b3, voffB); PG8_STAGE(PG8_SB(1, 1), b3 + hstep, voffB); PG8_STAGE(PG8_SA(1, 0), a3, voffA);
;             PG8_WAIT_V(8); PG8_WAIT_L(0); PG8_BAR; PG8_MMA(1, 0, At, B0); PG8_MMA(1, 1, At, B1); PG8_BAR; PG8_SCHED;
;     ...
;         if (!has_next) break;
;         if (!(PAIR_ACC && cur.pn < 4)) {
; #pragma unroll
;         for (int a = 0; a < 2; ++a)
; #pragma unroll
;             for (int b = 0; b < 2; ++b)
; #pragma unroll
;                 for (int m = 0; m < 4; ++m)
; #pragma unroll
;                     for (int n = 0; n < 2; ++n) acc[a][b][m][n] = (f32x4){0.f, 0.f, 0.f, 0.f};
;         }
	s_setprio 0
	s_add_i32 s28, s53, s37
	v_lshl_add_u64 v[164:165], v[164:165], 0, s[20:21]
	s_mov_b32 m0, s28
	ds_read_b128 v[188:191], v151 offset:49152
	ds_read_b128 v[192:195], v151 offset:50176
	ds_read_b128 v[196:199], v151 offset:51200
	ds_read_b128 v[200:203], v151 offset:52224
	ds_read_b128 v[204:207], v151 offset:53248
	ds_read_b128 v[208:211], v151 offset:54272
	ds_read_b128 v[212:215], v151 offset:55296
	ds_read_b128 v[216:219], v151 offset:56320
	global_load_lds_dwordx4 v[164:165], off
	s_add_i32 m0, s28, 0x2000
	s_add_u32 s26, s26, 0xb0080
	v_lshl_add_u64 v[164:165], v[220:221], 0, s[20:21]
	s_addc_u32 s27, s27, 0
	s_add_i32 s28, s54, s37
	global_load_lds_dwordx4 v[164:165], off
	v_lshl_add_u64 v[164:165], s[26:27], 0, v[132:133]
	s_mov_b32 m0, s28
	s_nop 0
	global_load_lds_dwordx4 v[164:165], off
	v_lshl_add_u64 v[164:165], s[26:27], 0, v[136:137]
	s_add_i32 m0, s28, 0x2000
	s_nop 0
	global_load_lds_dwordx4 v[164:165], off
	v_lshl_add_u64 v[164:165], v[222:223], 0, s[20:21]
	s_mov_b32 m0, s43
	s_nop 0
	global_load_lds_dwordx4 v[164:165], off
	v_lshl_add_u64 v[164:165], v[224:225], 0, s[20:21]
	s_mov_b32 m0, s44
	s_nop 0
	global_load_lds_dwordx4 v[164:165], off
	s_waitcnt vmcnt(8)
	s_waitcnt lgkmcnt(0)
	s_setprio 1
	s_barrier
	v_mfma_f32_16x16x32_bf16 v[62:65], v[152:155], v[188:191], v[62:65]
	v_mfma_f32_16x16x32_bf16 v[58:61], v[160:163], v[188:191], v[58:61]
	v_mfma_f32_16x16x32_bf16 v[46:49], v[152:155], v[196:199], v[46:49]
	v_mfma_f32_16x16x32_bf16 v[42:45], v[160:163], v[196:199], v[42:45]
	v_mfma_f32_16x16x32_bf16 v[30:33], v[152:155], v[204:207], v[30:33]
	v_mfma_f32_16x16x32_bf16 v[26:29], v[160:163], v[204:207], v[26:29]
	v_mfma_f32_16x16x32_bf16 v[14:17], v[152:155], v[212:215], v[14:17]
	v_mfma_f32_16x16x32_bf16 v[10:13], v[160:163], v[212:215], v[10:13]
	v_mfma_f32_16x16x32_bf16 v[62:65], v[156:159], v[192:195], v[62:65]
	v_mfma_f32_16x16x32_bf16 v[58:61], v[168:171], v[192:195], v[58:61]
	v_mfma_f32_16x16x32_bf16 v[46:49], v[156:159], v[200:203], v[46:49]
	v_mfma_f32_16x16x32_bf16 v[42:45], v[168:171], v[200:203], v[42:45]
	v_mfma_f32_16x16x32_bf16 v[30:33], v[156:159], v[208:211], v[30:33]
	v_mfma_f32_16x16x32_bf16 v[26:29], v[168:171], v[208:211], v[26:29]
	v_mfma_f32_16x16x32_bf16 v[14:17], v[156:159], v[216:219], v[14:17]
	v_mfma_f32_16x16x32_bf16 v[10:13], v[168:171], v[216:219], v[10:13]
	s_setprio 0
	s_setprio 1
	v_mfma_f32_16x16x32_bf16 v[54:57], v[172:175], v[188:191], v[54:57]
	v_mfma_f32_16x16x32_bf16 v[50:53], v[180:183], v[188:191], v[50:53]
	v_mfma_f32_16x16x32_bf16 v[38:41], v[172:175], v[196:199], v[38:41]
	v_mfma_f32_16x16x32_bf16 v[34:37], v[180:183], v[196:199], v[34:37]
	v_mfma_f32_16x16x32_bf16 v[22:25], v[172:175], v[204:207], v[22:25]
	v_mfma_f32_16x16x32_bf16 v[18:21], v[180:183], v[204:207], v[18:21]
	v_mfma_f32_16x16x32_bf16 v[6:9], v[172:175], v[212:215], v[6:9]
	v_mfma_f32_16x16x32_bf16 v[2:5], v[180:183], v[212:215], v[2:5]
	v_mfma_f32_16x16x32_bf16 v[54:57], v[176:179], v[192:195], v[54:57]
	v_mfma_f32_16x16x32_bf16 v[50:53], v[184:187], v[192:195], v[50:53]
	v_mfma_f32_16x16x32_bf16 v[38:41], v[176:179], v[200:203], v[38:41]
	v_mfma_f32_16x16x32_bf16 v[34:37], v[184:187], v[200:203], v[34:37]
	v_mfma_f32_16x16x32_bf16 v[22:25], v[176:179], v[208:211], v[22:25]
	v_mfma_f32_16x16x32_bf16 v[18:21], v[184:187], v[208:211], v[18:21]
	v_mfma_f32_16x16x32_bf16 v[6:9], v[176:179], v[216:219], v[6:9]
	v_mfma_f32_16x16x32_bf16 v[2:5], v[184:187], v[216:219], v[2:5]
	s_barrier
	s_setprio 0
	s_add_i32 s52, s52, 2
	s_add_u32 s24, s24, 0x100
	s_addc_u32 s25, s25, 0
	s_cmp_gt_u32 s52, 41
	s_cbranch_scc0 .LBB0_1840
	s_add_u32 s24, s50, 0xffffff00
	s_addc_u32 s25, s51, -1
	s_and_b64 vcc, exec, s[6:7]
	s_cbranch_vccnz .LBB0_1827
	v_mov_b32_e32 v2, 0
	s_mov_b32 s14, s47
	s_mov_b32 s31, s48
	s_mov_b64 s[18:19], s[22:23]
	s_mov_b32 s42, s49
	v_mov_b32_e32 v3, v2
	v_mov_b32_e32 v4, v2
	v_mov_b32_e32 v5, v2
	v_mov_b32_e32 v6, v2
	v_mov_b32_e32 v7, v2
	v_mov_b32_e32 v8, v2
	v_mov_b32_e32 v9, v2
	v_mov_b32_e32 v18, v2
	v_mov_b32_e32 v19, v2
	v_mov_b32_e32 v20, v2
	v_mov_b32_e32 v21, v2
	v_mov_b32_e32 v22, v2
	v_mov_b32_e32 v23, v2
	v_mov_b32_e32 v24, v2
	v_mov_b32_e32 v25, v2
	v_mov_b32_e32 v34, v2
	v_mov_b32_e32 v35, v2
	v_mov_b32_e32 v36, v2
	v_mov_b32_e32 v37, v2
	v_mov_b32_e32 v38, v2
	v_mov_b32_e32 v39, v2
	v_mov_b32_e32 v40, v2
	v_mov_b32_e32 v41, v2
	v_mov_b32_e32 v50, v2
	v_mov_b32_e32 v51, v2
	v_mov_b32_e32 v52, v2
	v_mov_b32_e32 v53, v2
	v_mov_b32_e32 v54, v2
	v_mov_b32_e32 v55, v2
	v_mov_b32_e32 v56, v2
	v_mov_b32_e32 v57, v2
	v_mov_b32_e32 v10, v2
	v_mov_b32_e32 v11, v2
	v_mov_b32_e32 v12, v2
	v_mov_b32_e32 v13, v2
	v_mov_b32_e32 v14, v2
	v_mov_b32_e32 v15, v2
	v_mov_b32_e32 v16, v2
	v_mov_b32_e32 v17, v2
	v_mov_b32_e32 v26, v2
	v_mov_b32_e32 v27, v2
	v_mov_b32_e32 v28, v2
	v_mov_b32_e32 v29, v2
	v_mov_b32_e32 v30, v2
	v_mov_b32_e32 v31, v2
	v_mov_b32_e32 v32, v2
	v_mov_b32_e32 v33, v2
	v_mov_b32_e32 v42, v2
	v_mov_b32_e32 v43, v2
	v_mov_b32_e32 v44, v2
	v_mov_b32_e32 v45, v2
	v_mov_b32_e32 v46, v2
	v_mov_b32_e32 v47, v2
	v_mov_b32_e32 v48, v2
	v_mov_b32_e32 v49, v2
	v_mov_b32_e32 v58, v2
	v_mov_b32_e32 v59, v2
	v_mov_b32_e32 v60, v2
	v_mov_b32_e32 v61, v2
	v_mov_b32_e32 v62, v2
	v_mov_b32_e32 v63, v2
	v_mov_b32_e32 v64, v2
	v_mov_b32_e32 v65, v2
	v_mov_b32_e32 v66, v2
	v_mov_b32_e32 v67, v2
	v_mov_b32_e32 v68, v2
	v_mov_b32_e32 v69, v2
	v_mov_b32_e32 v70, v2
	v_mov_b32_e32 v71, v2
	v_mov_b32_e32 v72, v2
	v_mov_b32_e32 v73, v2
	v_mov_b32_e32 v98, v2
	v_mov_b32_e32 v99, v2
	v_mov_b32_e32 v100, v2
	v_mov_b32_e32 v101, v2
	v_mov_b32_e32 v110, v2
	v_mov_b32_e32 v111, v2
	v_mov_b32_e32 v112, v2
	v_mov_b32_e32 v113, v2
	v_mov_b32_e32 v90, v2
	v_mov_b32_e32 v91, v2
	v_mov_b32_e32 v92, v2
	v_mov_b32_e32 v93, v2
	v_mov_b32_e32 v94, v2
	v_mov_b32_e32 v95, v2
	v_mov_b32_e32 v96, v2
	v_mov_b32_e32 v97, v2
	v_mov_b32_e32 v82, v2
	v_mov_b32_e32 v83, v2
	v_mov_b32_e32 v84, v2
	v_mov_b32_e32 v85, v2
	v_mov_b32_e32 v86, v2
	v_mov_b32_e32 v87, v2
	v_mov_b32_e32 v88, v2
	v_mov_b32_e32 v89, v2
	v_mov_b32_e32 v74, v2
	v_mov_b32_e32 v75, v2
	v_mov_b32_e32 v76, v2
	v_mov_b32_e32 v77, v2
	v_mov_b32_e32 v78, v2
	v_mov_b32_e32 v79, v2
	v_mov_b32_e32 v80, v2
	v_mov_b32_e32 v81, v2
	v_mov_b32_e32 v122, v2
	v_mov_b32_e32 v123, v2
	v_mov_b32_e32 v124, v2
	v_mov_b32_e32 v125, v2
	v_mov_b32_e32 v126, v2
	v_mov_b32_e32 v127, v2
	v_mov_b32_e32 v128, v2
	v_mov_b32_e32 v129, v2
	v_mov_b32_e32 v118, v2
	v_mov_b32_e32 v119, v2
	v_mov_b32_e32 v120, v2
	v_mov_b32_e32 v121, v2
	v_mov_b32_e32 v114, v2
	v_mov_b32_e32 v115, v2
	v_mov_b32_e32 v116, v2
	v_mov_b32_e32 v117, v2
	v_mov_b32_e32 v106, v2
	v_mov_b32_e32 v107, v2
	v_mov_b32_e32 v108, v2
	v_mov_b32_e32 v109, v2
	v_mov_b32_e32 v102, v2
	v_mov_b32_e32 v103, v2
	v_mov_b32_e32 v104, v2
	v_mov_b32_e32 v105, v2
	s_andn2_b64 vcc, exec, s[0:1]
	s_cbranch_vccnz .LBB0_1828
